# v_ntwin + P1 epilogue de-serialisation: the 8 per-row rstd loads of each in-proj unit issued before its K-loop (v247-254), epilogue reads them from registers
# speedup vs baseline: 1.0092x; 1.0092x over previous
; template <class Epi, class Sched, bool ALIGN_EPI = false, bool SP2 = false>
; __device__ __forceinline__ void gemm_phase(PG8_LAS unsigned char* lds, const Gemm g, const Sched& S, const Epi& E) {
;     ...
;         for (int a = 0; a < 2; ++a)
; #pragma unroll
;             for (int b = 0; b < 2; ++b)
; #pragma unroll
;                 for (int m = 0; m < 4; ++m)
; #pragma unroll
;                     for (int n = 0; n < 2; ++n) acc[a][b][m][n] = (f32x4){0.f, 0.f, 0.f, 0.f};
;         cur = nxt; cA = nA; cB = nB; ++ui;
;     __device__ __forceinline__ void operator()(const f32x4 (&acc)[2][2][4][2], const pg8::Unit& u, int wr, int wc, int fr, int fq) const {
;     ...
;             for (int m = 0; m < 4; ++m) rs8[ai][m] = rstd[256 * pm + 128 * ai + 64 * wr + 16 * m + fr];
.LBB0_410:
	s_lshl_b32 s98, s8, 8
	s_add_i32 s98, s98, s66
	v_add_lshl_u32 v255, v1, s98, 2
	global_load_dword v247, v255, s[16:17]
	global_load_dword v248, v255, s[16:17] offset:64
	global_load_dword v249, v255, s[16:17] offset:128
	global_load_dword v250, v255, s[16:17] offset:192
	global_load_dword v251, v255, s[16:17] offset:512
	global_load_dword v252, v255, s[16:17] offset:576
	global_load_dword v253, v255, s[16:17] offset:640
	global_load_dword v254, v255, s[16:17] offset:704
	s_ashr_i32 s35, s34, 31
	s_lshl_b64 s[0:1], s[34:35], 19
	s_add_u32 s38, s29, s0
	s_addc_u32 s39, s31, s1
	s_and_b64 s[0:1], s[10:11], exec
	s_cselect_b32 s0, s39, s5
	s_cselect_b32 s1, s38, s4
	s_ashr_i32 s37, s36, 31
	s_lshl_b64 s[40:41], s[36:37], 19
	s_add_u32 s40, s48, s40
	s_addc_u32 s41, s49, s41
	s_and_b64 s[44:45], s[10:11], exec
	s_cselect_b32 s9, s41, s7
	s_cselect_b32 s12, s40, s6
	s_add_u32 s4, s4, 0x40080
	s_addc_u32 s5, s5, 0
	s_add_u32 s33, s6, 0x100
	v_mov_b32_e32 v2, 0
	s_addc_u32 s35, s7, 0
	s_mov_b32 s37, -2
	v_mov_b32_e32 v3, v2
	v_mov_b32_e32 v4, v2
	v_mov_b32_e32 v5, v2
	v_mov_b32_e32 v6, v2
	v_mov_b32_e32 v7, v2
	v_mov_b32_e32 v8, v2
	v_mov_b32_e32 v9, v2
	v_mov_b32_e32 v18, v2
	v_mov_b32_e32 v19, v2
	v_mov_b32_e32 v20, v2
	v_mov_b32_e32 v21, v2
	v_mov_b32_e32 v22, v2
	v_mov_b32_e32 v23, v2
	v_mov_b32_e32 v24, v2
	v_mov_b32_e32 v25, v2
	v_mov_b32_e32 v34, v2
	v_mov_b32_e32 v35, v2
	v_mov_b32_e32 v36, v2
	v_mov_b32_e32 v37, v2
	v_mov_b32_e32 v38, v2
	v_mov_b32_e32 v39, v2
	v_mov_b32_e32 v40, v2
	v_mov_b32_e32 v41, v2
	v_mov_b32_e32 v50, v2
	v_mov_b32_e32 v51, v2
	v_mov_b32_e32 v52, v2
	v_mov_b32_e32 v53, v2
	v_mov_b32_e32 v54, v2
	v_mov_b32_e32 v55, v2
	v_mov_b32_e32 v56, v2
	v_mov_b32_e32 v57, v2
	v_mov_b32_e32 v10, v2
	v_mov_b32_e32 v11, v2
	v_mov_b32_e32 v12, v2
	v_mov_b32_e32 v13, v2
	v_mov_b32_e32 v14, v2
	v_mov_b32_e32 v15, v2
	v_mov_b32_e32 v16, v2
	v_mov_b32_e32 v17, v2
	v_mov_b32_e32 v26, v2
	v_mov_b32_e32 v27, v2
	v_mov_b32_e32 v28, v2
	v_mov_b32_e32 v29, v2
	v_mov_b32_e32 v30, v2
	v_mov_b32_e32 v31, v2
	v_mov_b32_e32 v32, v2
	v_mov_b32_e32 v33, v2
	v_mov_b32_e32 v42, v2
	v_mov_b32_e32 v43, v2
	v_mov_b32_e32 v44, v2
	v_mov_b32_e32 v45, v2
	v_mov_b32_e32 v46, v2
	v_mov_b32_e32 v47, v2
	v_mov_b32_e32 v48, v2
	v_mov_b32_e32 v49, v2
	v_mov_b32_e32 v58, v2
	v_mov_b32_e32 v59, v2
	v_mov_b32_e32 v60, v2
	v_mov_b32_e32 v61, v2
	v_mov_b32_e32 v62, v2
	v_mov_b32_e32 v63, v2
	v_mov_b32_e32 v64, v2
	v_mov_b32_e32 v65, v2
	v_mov_b32_e32 v66, v2
	v_mov_b32_e32 v67, v2
	v_mov_b32_e32 v68, v2
	v_mov_b32_e32 v69, v2
	v_mov_b32_e32 v70, v2
	v_mov_b32_e32 v71, v2
	v_mov_b32_e32 v72, v2
	v_mov_b32_e32 v73, v2
	v_mov_b32_e32 v82, v2
	v_mov_b32_e32 v83, v2
	v_mov_b32_e32 v84, v2
	v_mov_b32_e32 v85, v2
	v_mov_b32_e32 v86, v2
	v_mov_b32_e32 v87, v2
	v_mov_b32_e32 v88, v2
	v_mov_b32_e32 v89, v2
	v_mov_b32_e32 v98, v2
	v_mov_b32_e32 v99, v2
	v_mov_b32_e32 v100, v2
	v_mov_b32_e32 v101, v2
	v_mov_b32_e32 v102, v2
	v_mov_b32_e32 v103, v2
	v_mov_b32_e32 v104, v2
	v_mov_b32_e32 v105, v2
	v_mov_b32_e32 v114, v2
	v_mov_b32_e32 v115, v2
	v_mov_b32_e32 v116, v2
	v_mov_b32_e32 v117, v2
	v_mov_b32_e32 v118, v2
	v_mov_b32_e32 v119, v2
	v_mov_b32_e32 v120, v2
	v_mov_b32_e32 v121, v2
	v_mov_b32_e32 v74, v2
	v_mov_b32_e32 v75, v2
	v_mov_b32_e32 v76, v2
	v_mov_b32_e32 v77, v2
	v_mov_b32_e32 v78, v2
	v_mov_b32_e32 v79, v2
	v_mov_b32_e32 v80, v2
	v_mov_b32_e32 v81, v2
	v_mov_b32_e32 v90, v2
	v_mov_b32_e32 v91, v2
	v_mov_b32_e32 v92, v2
	v_mov_b32_e32 v93, v2
	v_mov_b32_e32 v94, v2
	v_mov_b32_e32 v95, v2
	v_mov_b32_e32 v96, v2
	v_mov_b32_e32 v97, v2
	v_mov_b32_e32 v106, v2
	v_mov_b32_e32 v107, v2
	v_mov_b32_e32 v108, v2
	v_mov_b32_e32 v109, v2
	v_mov_b32_e32 v110, v2
	v_mov_b32_e32 v111, v2
	v_mov_b32_e32 v112, v2
	v_mov_b32_e32 v113, v2
	v_mov_b32_e32 v122, v2
	v_mov_b32_e32 v123, v2
	v_mov_b32_e32 v124, v2
	v_mov_b32_e32 v125, v2
	v_mov_b32_e32 v126, v2
	v_mov_b32_e32 v127, v2
	v_mov_b32_e32 v128, v2
	v_mov_b32_e32 v129, v2

; __device__ __forceinline__ float fast_exp(float x) { return __builtin_amdgcn_exp2f(x * LOG2E); }
;     __device__ __forceinline__ void operator()(const f32x4 (&acc)[2][2][4][2], const pg8::Unit& u, int wr, int wc, int fr, int fq) const {
;     ...
;         float rs8[2][4];
; #pragma unroll
;         for (int ai = 0; ai < 2; ++ai)
; #pragma unroll
;             for (int m = 0; m < 4; ++m) rs8[ai][m] = rstd[256 * pm + 128 * ai + 64 * wr + 16 * m + fr];
;     ...
;         } else {
;             f32x4 bg[2][2];
; #pragma unroll
;             for (int bj = 0; bj < 2; ++bj)
; #pragma unroll
;                 for (int n = 0; n < 2; ++n) bg[bj][n] = *(const f32x4*)(bgate + 64 * wc + 32 * bj + 8 * fq + 4 * n);
; #pragma unroll
;             for (int ai = 0; ai < 2; ++ai)
; #pragma unroll
;                 for (int m = 0; m < 4; ++m) {
;                     const int rowa = 256 * pm + 128 * ai + 64 * wr + 16 * m + tt.rr;
;                     const float rs = rs8[ai][m];
;                     v4u pk[2];
; #pragma unroll
;                     for (int bj = 0; bj < 2; ++bj) {
;                         f32x4 r2[2];
; #pragma unroll
;                         for (int n = 0; n < 2; ++n) {
;                             const f32x4 z = acc[ai][bj][m][n] * rs + bg[bj][n];
; #pragma unroll
;                             for (int j = 0; j < 4; ++j) { const float az = fabsf(z[j]); r2[n][j] = (fminf(z[j], 0.f) - __logf(1.0f + fast_exp(-az))) * (1.0f / 16.0f); }
.LBB0_414:
	v_mov_b32_e32 v158, v216
	v_mov_b32_e32 v146, v1
	s_lshl_b32 s9, s8, 8
	v_add_u32_e32 v159, s66, v146
	v_add_u32_e32 v130, s9, v159
	v_ashrrev_i32_e32 v131, 31, v130
	v_lshl_add_u64 v[132:133], v[130:131], 2, s[16:17]
	v_add_u32_e32 v134, 16, v130
	v_add_u32_e32 v136, 32, v130
	v_add_u32_e32 v138, 48, v130
	v_add_u32_e32 v140, 0x80, v130
	v_add_u32_e32 v142, 0x90, v130
	v_add_u32_e32 v144, 0xa0, v130
	v_add_u32_e32 v130, 0xb0, v130
	v_ashrrev_i32_e32 v135, 31, v134
	v_ashrrev_i32_e32 v137, 31, v136
	v_ashrrev_i32_e32 v139, 31, v138
	v_ashrrev_i32_e32 v141, 31, v140
	v_ashrrev_i32_e32 v143, 31, v142
	v_ashrrev_i32_e32 v145, 31, v144
	v_ashrrev_i32_e32 v131, 31, v130
	v_lshl_add_u64 v[134:135], v[134:135], 2, s[16:17]
	v_lshl_add_u64 v[136:137], v[136:137], 2, s[16:17]
	v_lshl_add_u64 v[138:139], v[138:139], 2, s[16:17]
	v_lshl_add_u64 v[140:141], v[140:141], 2, s[16:17]
	v_lshl_add_u64 v[142:143], v[142:143], 2, s[16:17]
	v_lshl_add_u64 v[144:145], v[144:145], 2, s[16:17]
	v_lshl_add_u64 v[130:131], v[130:131], 2, s[16:17]
	v_mov_b32_e32 v162, v247
	v_mov_b32_e32 v210, v248
	v_mov_b32_e32 v208, v249
	v_mov_b32_e32 v206, v250
	v_mov_b32_e32 v204, v251
	v_mov_b32_e32 v202, v252
	v_mov_b32_e32 v198, v253
	v_mov_b32_e32 v196, v254
	v_lshlrev_b32_e32 v200, 4, v158
	v_add_u32_e32 v130, v200, v146
	v_and_b32_e32 v213, 7, v146
	v_add_u32_e32 v132, 4, v158
	v_lshlrev_b32_e32 v133, 1, v158
	v_ashrrev_i32_e32 v227, 3, v130
	v_lshlrev_b32_e32 v130, 7, v146
	v_bitop3_b32 v131, v146, v158, 7 bitop3:0x6c
	v_bitop3_b32 v132, v132, v146, 7 bitop3:0x78
	v_bitop3_b32 v134, v133, v146, 7 bitop3:0x78
	v_bitop3_b32 v133, v133, v213, 1 bitop3:0x36
	v_lshl_add_u32 v225, v133, 4, v130
	v_bitop3_b32 v133, v227, v146, 7 bitop3:0x78
	s_cmpk_gt_i32 s8, 0xff
	v_lshl_add_u32 v229, v131, 4, v130
	v_lshl_add_u32 v228, v132, 4, v130
	v_lshl_add_u32 v226, v134, 4, v130
	v_lshlrev_b32_e32 v130, 7, v227
	s_cselect_b64 s[4:5], -1, 0
	v_lshl_add_u32 v230, v133, 4, v130
	s_cmp_gt_i32 s42, 3
	s_mov_b64 s[6:7], -1
	s_cbranch_scc0 .LBB0_475
	s_cmp_gt_u32 s42, 5
	s_cbranch_scc0 .LBB0_457
	s_cmp_gt_u32 s42, 7
	s_cbranch_scc0 .LBB0_454
	s_add_i32 s0, s9, s66
	v_add_u32_e32 v150, s0, v227
	s_cmp_gt_u32 s42, 13
	v_ashrrev_i32_e32 v151, 31, v150
	s_cbranch_scc0 .LBB0_419
	v_lshlrev_b32_e32 v130, 3, v158
	v_ashrrev_i32_e32 v131, 31, v130
	v_lshl_add_u64 v[130:131], v[130:131], 2, v[186:187]
	flat_load_dwordx4 v[142:145], v[130:131]
	flat_load_dwordx4 v[138:141], v[130:131] offset:16
	flat_load_dwordx4 v[134:137], v[130:131] offset:128
	s_nop 0
	flat_load_dwordx4 v[130:133], v[130:131] offset:144
	v_lshlrev_b32_e32 v184, 4, v213
	s_waitcnt vmcnt(0) lgkmcnt(0)
	v_fma_f32 v147, v126, v162, v142
	v_min_f32_e32 v146, 0, v147
	v_mul_f32_e64 v147, |v147|, s88
	v_exp_f32_e32 v147, v147
	v_fma_f32 v149, v127, v162, v143
	v_fma_f32 v153, v129, v162, v145
	v_fma_f32 v155, v123, v162, v139
	v_add_f32_e32 v147, 1.0, v147
	v_cmp_gt_f32_e32 vcc, s89, v147
	v_fma_f32 v157, v125, v162, v141
	v_fma_f32 v161, v115, v162, v131
	v_cndmask_b32_e64 v148, 0, 32, vcc
	v_ldexp_f32 v147, v147, v148
	v_log_f32_e32 v147, v147
	v_fma_f32 v167, v101, v210, v133
	v_mul_f32_e32 v148, 0x3f317217, v147
	v_fma_f32 v148, v147, s90, -v148
	v_fmac_f32_e32 v148, 0x3377d1cf, v147
	v_fmac_f32_e32 v148, 0x3f317217, v147
	v_cmp_lt_f32_e64 s[6:7], |v147|, s91
	s_nop 1
	v_cndmask_b32_e64 v147, v147, v148, s[6:7]
	v_cndmask_b32_e32 v148, 0, v222, vcc
	v_sub_f32_e32 v148, v147, v148
	v_min_f32_e32 v147, 0, v149
	v_mul_f32_e64 v149, |v149|, s88
	v_exp_f32_e32 v149, v149
	s_nop 0
	v_add_f32_e32 v149, 1.0, v149
	v_cmp_gt_f32_e32 vcc, s89, v149
	s_nop 1
	v_cndmask_b32_e64 v152, 0, 32, vcc
	v_ldexp_f32 v149, v149, v152
	v_log_f32_e32 v149, v149
	s_nop 0
	v_mul_f32_e32 v152, 0x3f317217, v149
	v_fma_f32 v152, v149, s90, -v152
	v_fmac_f32_e32 v152, 0x3377d1cf, v149
	v_fmac_f32_e32 v152, 0x3f317217, v149
	v_cmp_lt_f32_e64 s[6:7], |v149|, s91
	s_nop 1
	v_cndmask_b32_e64 v149, v149, v152, s[6:7]
	v_cndmask_b32_e32 v152, 0, v222, vcc
	v_sub_f32_e32 v149, v149, v152
	v_pk_add_f32 v[146:147], v[146:147], v[148:149] neg_lo:[0,1] neg_hi:[0,1]
	v_fma_f32 v149, v128, v162, v144
	v_min_f32_e32 v148, 0, v149
	v_mul_f32_e64 v149, |v149|, s88
	v_exp_f32_e32 v149, v149
	v_pk_mul_f32 v[146:147], v[146:147], s[28:29] op_sel_hi:[1,0]
	v_add_f32_e32 v149, 1.0, v149
	v_cmp_gt_f32_e32 vcc, s89, v149
	v_cvt_pk_bf16_f32 v146, v146, v147
	s_nop 0
	v_cndmask_b32_e64 v152, 0, 32, vcc
	v_ldexp_f32 v149, v149, v152
	v_log_f32_e32 v149, v149
	s_nop 0
	v_mul_f32_e32 v152, 0x3f317217, v149
	v_fma_f32 v152, v149, s90, -v152
	v_fmac_f32_e32 v152, 0x3377d1cf, v149
	v_fmac_f32_e32 v152, 0x3f317217, v149
	v_cmp_lt_f32_e64 s[6:7], |v149|, s91
	s_nop 1
	v_cndmask_b32_e64 v149, v149, v152, s[6:7]
	v_cndmask_b32_e32 v152, 0, v222, vcc
	v_sub_f32_e32 v152, v149, v152
	v_min_f32_e32 v149, 0, v153
	v_mul_f32_e64 v153, |v153|, s88
	v_exp_f32_e32 v153, v153
	s_nop 0
	v_add_f32_e32 v153, 1.0, v153
	v_cmp_gt_f32_e32 vcc, s89, v153
	s_nop 1
	v_cndmask_b32_e64 v154, 0, 32, vcc
	v_ldexp_f32 v153, v153, v154
	v_log_f32_e32 v153, v153
	s_nop 0
	v_mul_f32_e32 v154, 0x3f317217, v153
	v_fma_f32 v154, v153, s90, -v154
	v_fmac_f32_e32 v154, 0x3377d1cf, v153
	v_fmac_f32_e32 v154, 0x3f317217, v153
	v_cmp_lt_f32_e64 s[6:7], |v153|, s91
	s_nop 1
	v_cndmask_b32_e64 v153, v153, v154, s[6:7]
	v_cndmask_b32_e32 v154, 0, v222, vcc
	v_sub_f32_e32 v153, v153, v154
	v_pk_add_f32 v[148:149], v[148:149], v[152:153] neg_lo:[0,1] neg_hi:[0,1]
	v_fma_f32 v153, v122, v162, v138
	v_min_f32_e32 v152, 0, v153
	v_mul_f32_e64 v153, |v153|, s88
	v_exp_f32_e32 v153, v153
	v_pk_mul_f32 v[148:149], v[148:149], s[28:29] op_sel_hi:[1,0]
; __device__ __forceinline__ v4u pack8(const f32x4 a, const f32x4 b) { v4u w; w.x = pk2(a[0], a[1]); w.y = pk2(a[2], a[3]); w.z = pk2(b[0], b[1]); w.w = pk2(b[2], b[3]); return w; }
; __device__ __forceinline__ float fast_exp(float x) { return __builtin_amdgcn_exp2f(x * LOG2E); }
;     __device__ __forceinline__ void operator()(const f32x4 (&acc)[2][2][4][2], const pg8::Unit& u, int wr, int wc, int fr, int fq) const {
;     ...
;             for (int ai = 0; ai < 2; ++ai)
; #pragma unroll
;                 for (int m = 0; m < 4; ++m) {
;                     const int rowa = 256 * pm + 128 * ai + 64 * wr + 16 * m + tt.rr;
;                     const float rs = rs8[ai][m];
;                     v4u pk[2];
; #pragma unroll
;                     for (int bj = 0; bj < 2; ++bj) {
;                         f32x4 r2[2];
; #pragma unroll
;                         for (int n = 0; n < 2; ++n) {
;                             const f32x4 z = acc[ai][bj][m][n] * rs + bg[bj][n];
; #pragma unroll
;                             for (int j = 0; j < 4; ++j) { const float az = fabsf(z[j]); r2[n][j] = (fminf(z[j], 0.f) - __logf(1.0f + fast_exp(-az))) * (1.0f / 16.0f); }
;                         }
;                         pk[bj] = pack8(r2[0], r2[1]);
;                     }
;                     v4u a, b; tt.bf(pk[0], pk[1], a, b);
;                     bf16* d = (bf16*)(ws + WS_LOGA) + (size_t)rowa * 256 + 64 * wc + 8 * tt.p; *(v4u*)d = a; *(v4u*)(d + 8 * 256) = b;
	v_add_f32_e32 v153, 1.0, v153
	v_cmp_gt_f32_e32 vcc, s89, v153
	v_cvt_pk_bf16_f32 v147, v148, v149
	s_nop 0
	v_cndmask_b32_e64 v154, 0, 32, vcc
	v_ldexp_f32 v153, v153, v154
	v_log_f32_e32 v153, v153
	s_nop 0
	v_mul_f32_e32 v154, 0x3f317217, v153
	v_fma_f32 v154, v153, s90, -v154
	v_fmac_f32_e32 v154, 0x3377d1cf, v153
	v_fmac_f32_e32 v154, 0x3f317217, v153
	v_cmp_lt_f32_e64 s[6:7], |v153|, s91
	s_nop 1
	v_cndmask_b32_e64 v153, v153, v154, s[6:7]
	v_cndmask_b32_e32 v154, 0, v222, vcc
	v_sub_f32_e32 v154, v153, v154
	v_min_f32_e32 v153, 0, v155
	v_mul_f32_e64 v155, |v155|, s88
	v_exp_f32_e32 v155, v155
	s_nop 0
	v_add_f32_e32 v155, 1.0, v155
	v_cmp_gt_f32_e32 vcc, s89, v155
	s_nop 1
	v_cndmask_b32_e64 v156, 0, 32, vcc
	v_ldexp_f32 v155, v155, v156
	v_log_f32_e32 v155, v155
	s_nop 0
	v_mul_f32_e32 v156, 0x3f317217, v155
	v_fma_f32 v156, v155, s90, -v156
	v_fmac_f32_e32 v156, 0x3377d1cf, v155
	v_fmac_f32_e32 v156, 0x3f317217, v155
	v_cmp_lt_f32_e64 s[6:7], |v155|, s91
	s_nop 1
	v_cndmask_b32_e64 v155, v155, v156, s[6:7]
	v_cndmask_b32_e32 v156, 0, v222, vcc
	v_sub_f32_e32 v155, v155, v156
	v_pk_add_f32 v[152:153], v[152:153], v[154:155] neg_lo:[0,1] neg_hi:[0,1]
	v_fma_f32 v155, v124, v162, v140
	v_min_f32_e32 v154, 0, v155
	v_mul_f32_e64 v155, |v155|, s88
	v_exp_f32_e32 v155, v155
	v_pk_mul_f32 v[152:153], v[152:153], s[28:29] op_sel_hi:[1,0]
	v_add_f32_e32 v155, 1.0, v155
	v_cmp_gt_f32_e32 vcc, s89, v155
	v_cvt_pk_bf16_f32 v148, v152, v153
	v_fma_f32 v153, v118, v162, v134
	v_cndmask_b32_e64 v156, 0, 32, vcc
	v_ldexp_f32 v155, v155, v156
	v_log_f32_e32 v155, v155
	v_min_f32_e32 v152, 0, v153
	v_mul_f32_e64 v153, |v153|, s88
	v_exp_f32_e32 v153, v153
	v_mul_f32_e32 v156, 0x3f317217, v155
	v_fma_f32 v156, v155, s90, -v156
	v_fmac_f32_e32 v156, 0x3377d1cf, v155
	v_fmac_f32_e32 v156, 0x3f317217, v155
	v_cmp_lt_f32_e64 s[6:7], |v155|, s91
	v_add_f32_e32 v153, 1.0, v153
	s_nop 0
	v_cndmask_b32_e64 v155, v155, v156, s[6:7]
	v_cndmask_b32_e32 v156, 0, v222, vcc
	v_sub_f32_e32 v156, v155, v156
	v_min_f32_e32 v155, 0, v157
	v_mul_f32_e64 v157, |v157|, s88
	v_exp_f32_e32 v157, v157
	s_nop 0
	v_add_f32_e32 v157, 1.0, v157
	v_cmp_gt_f32_e32 vcc, s89, v157
	s_nop 1
	v_cndmask_b32_e64 v160, 0, 32, vcc
	v_ldexp_f32 v157, v157, v160
	v_log_f32_e32 v157, v157
	s_nop 0
	v_mul_f32_e32 v160, 0x3f317217, v157
	v_fma_f32 v160, v157, s90, -v160
	v_fmac_f32_e32 v160, 0x3377d1cf, v157
	v_fmac_f32_e32 v160, 0x3f317217, v157
	v_cmp_lt_f32_e64 s[6:7], |v157|, s91
	s_nop 1
	v_cndmask_b32_e64 v157, v157, v160, s[6:7]
	v_cndmask_b32_e32 v160, 0, v222, vcc
	v_sub_f32_e32 v157, v157, v160
	v_pk_add_f32 v[154:155], v[154:155], v[156:157] neg_lo:[0,1] neg_hi:[0,1]
	v_cmp_gt_f32_e32 vcc, s89, v153
	v_pk_mul_f32 v[154:155], v[154:155], s[28:29] op_sel_hi:[1,0]
	v_fma_f32 v157, v121, v162, v137
	v_cvt_pk_bf16_f32 v149, v154, v155
	v_cndmask_b32_e64 v154, 0, 32, vcc
	v_ldexp_f32 v153, v153, v154
	v_log_f32_e32 v153, v153
	v_fma_f32 v155, v119, v162, v135
	v_mul_f32_e32 v154, 0x3f317217, v153
	v_fma_f32 v154, v153, s90, -v154
	v_fmac_f32_e32 v154, 0x3377d1cf, v153
	v_fmac_f32_e32 v154, 0x3f317217, v153
	v_cmp_lt_f32_e64 s[6:7], |v153|, s91
	s_nop 1
	v_cndmask_b32_e64 v153, v153, v154, s[6:7]
	v_cndmask_b32_e32 v154, 0, v222, vcc
	v_sub_f32_e32 v154, v153, v154
	v_min_f32_e32 v153, 0, v155
	v_mul_f32_e64 v155, |v155|, s88
	v_exp_f32_e32 v155, v155
	s_nop 0
	v_add_f32_e32 v155, 1.0, v155
	v_cmp_gt_f32_e32 vcc, s89, v155
	s_nop 1
	v_cndmask_b32_e64 v156, 0, 32, vcc
	v_ldexp_f32 v155, v155, v156
	v_log_f32_e32 v155, v155
	s_nop 0
	v_mul_f32_e32 v156, 0x3f317217, v155
	v_fma_f32 v156, v155, s90, -v156
	v_fmac_f32_e32 v156, 0x3377d1cf, v155
	v_fmac_f32_e32 v156, 0x3f317217, v155
	v_cmp_lt_f32_e64 s[6:7], |v155|, s91
	s_nop 1
	v_cndmask_b32_e64 v155, v155, v156, s[6:7]
	v_cndmask_b32_e32 v156, 0, v222, vcc
	v_sub_f32_e32 v155, v155, v156
	v_pk_add_f32 v[152:153], v[152:153], v[154:155] neg_lo:[0,1] neg_hi:[0,1]
	v_fma_f32 v155, v120, v162, v136
	v_min_f32_e32 v154, 0, v155
	v_mul_f32_e64 v155, |v155|, s88
	v_exp_f32_e32 v155, v155
	v_pk_mul_f32 v[152:153], v[152:153], s[28:29] op_sel_hi:[1,0]
	v_add_f32_e32 v155, 1.0, v155
	v_cmp_gt_f32_e32 vcc, s89, v155
	v_cvt_pk_bf16_f32 v152, v152, v153
	s_nop 0
	v_cndmask_b32_e64 v156, 0, 32, vcc
	v_ldexp_f32 v155, v155, v156
	v_log_f32_e32 v155, v155
	s_nop 0
	v_mul_f32_e32 v156, 0x3f317217, v155
	v_fma_f32 v156, v155, s90, -v156
	v_fmac_f32_e32 v156, 0x3377d1cf, v155
	v_fmac_f32_e32 v156, 0x3f317217, v155
	v_cmp_lt_f32_e64 s[6:7], |v155|, s91
	s_nop 1
	v_cndmask_b32_e64 v155, v155, v156, s[6:7]
	v_cndmask_b32_e32 v156, 0, v222, vcc
	v_sub_f32_e32 v156, v155, v156
	v_min_f32_e32 v155, 0, v157
	v_mul_f32_e64 v157, |v157|, s88
	v_exp_f32_e32 v157, v157
	s_nop 0
	v_add_f32_e32 v157, 1.0, v157
	v_cmp_gt_f32_e32 vcc, s89, v157
	s_nop 1
	v_cndmask_b32_e64 v160, 0, 32, vcc
	v_ldexp_f32 v157, v157, v160
	v_log_f32_e32 v157, v157
	s_nop 0
	v_mul_f32_e32 v160, 0x3f317217, v157
	v_fma_f32 v160, v157, s90, -v160
	v_fmac_f32_e32 v160, 0x3377d1cf, v157
	v_fmac_f32_e32 v160, 0x3f317217, v157
	v_cmp_lt_f32_e64 s[6:7], |v157|, s91
	s_nop 1
	v_cndmask_b32_e64 v157, v157, v160, s[6:7]
	v_cndmask_b32_e32 v160, 0, v222, vcc
	v_sub_f32_e32 v157, v157, v160
	v_pk_add_f32 v[154:155], v[154:155], v[156:157] neg_lo:[0,1] neg_hi:[0,1]
	v_fma_f32 v157, v114, v162, v130
	v_min_f32_e32 v156, 0, v157
	v_mul_f32_e64 v157, |v157|, s88
	v_exp_f32_e32 v157, v157
	v_pk_mul_f32 v[154:155], v[154:155], s[28:29] op_sel_hi:[1,0]
	v_add_f32_e32 v157, 1.0, v157
	v_cmp_gt_f32_e32 vcc, s89, v157
	v_cvt_pk_bf16_f32 v153, v154, v155
	s_nop 0
	v_cndmask_b32_e64 v160, 0, 32, vcc
; __device__ __forceinline__ v4u pack8(const f32x4 a, const f32x4 b) { v4u w; w.x = pk2(a[0], a[1]); w.y = pk2(a[2], a[3]); w.z = pk2(b[0], b[1]); w.w = pk2(b[2], b[3]); return w; }
; __device__ __forceinline__ float fast_exp(float x) { return __builtin_amdgcn_exp2f(x * LOG2E); }
;     __device__ __forceinline__ void operator()(const f32x4 (&acc)[2][2][4][2], const pg8::Unit& u, int wr, int wc, int fr, int fq) const {
;     ...
;             for (int ai = 0; ai < 2; ++ai)
; #pragma unroll
;                 for (int m = 0; m < 4; ++m) {
;                     const int rowa = 256 * pm + 128 * ai + 64 * wr + 16 * m + tt.rr;
;                     const float rs = rs8[ai][m];
;                     v4u pk[2];
; #pragma unroll
;                     for (int bj = 0; bj < 2; ++bj) {
;                         f32x4 r2[2];
; #pragma unroll
;                         for (int n = 0; n < 2; ++n) {
;                             const f32x4 z = acc[ai][bj][m][n] * rs + bg[bj][n];
; #pragma unroll
;                             for (int j = 0; j < 4; ++j) { const float az = fabsf(z[j]); r2[n][j] = (fminf(z[j], 0.f) - __logf(1.0f + fast_exp(-az))) * (1.0f / 16.0f); }
;                         }
;                         pk[bj] = pack8(r2[0], r2[1]);
;                     }
;                     v4u a, b; tt.bf(pk[0], pk[1], a, b);
;                     bf16* d = (bf16*)(ws + WS_LOGA) + (size_t)rowa * 256 + 64 * wc + 8 * tt.p; *(v4u*)d = a; *(v4u*)(d + 8 * 256) = b;
	v_ldexp_f32 v157, v157, v160
	v_log_f32_e32 v157, v157
	s_nop 0
	v_mul_f32_e32 v160, 0x3f317217, v157
	v_fma_f32 v160, v157, s90, -v160
	v_fmac_f32_e32 v160, 0x3377d1cf, v157
	v_fmac_f32_e32 v160, 0x3f317217, v157
	v_cmp_lt_f32_e64 s[6:7], |v157|, s91
	s_nop 1
	v_cndmask_b32_e64 v157, v157, v160, s[6:7]
	v_cndmask_b32_e32 v160, 0, v222, vcc
	v_sub_f32_e32 v160, v157, v160
	v_min_f32_e32 v157, 0, v161
	v_mul_f32_e64 v161, |v161|, s88
	v_exp_f32_e32 v161, v161
	s_nop 0
	v_add_f32_e32 v161, 1.0, v161
	v_cmp_gt_f32_e32 vcc, s89, v161
	s_nop 1
	v_cndmask_b32_e64 v163, 0, 32, vcc
	v_ldexp_f32 v161, v161, v163
	v_log_f32_e32 v161, v161
	s_nop 0
	v_mul_f32_e32 v163, 0x3f317217, v161
	v_fma_f32 v163, v161, s90, -v163
	v_fmac_f32_e32 v163, 0x3377d1cf, v161
	v_fmac_f32_e32 v163, 0x3f317217, v161
	v_cmp_lt_f32_e64 s[6:7], |v161|, s91
	s_nop 1
	v_cndmask_b32_e64 v161, v161, v163, s[6:7]
	v_cndmask_b32_e32 v163, 0, v222, vcc
	v_sub_f32_e32 v161, v161, v163
	v_pk_add_f32 v[156:157], v[156:157], v[160:161] neg_lo:[0,1] neg_hi:[0,1]
	v_fma_f32 v161, v116, v162, v132
	v_min_f32_e32 v160, 0, v161
	v_mul_f32_e64 v161, |v161|, s88
	v_exp_f32_e32 v161, v161
	v_pk_mul_f32 v[156:157], v[156:157], s[28:29] op_sel_hi:[1,0]
	v_add_f32_e32 v161, 1.0, v161
	v_cmp_gt_f32_e32 vcc, s89, v161
	v_cvt_pk_bf16_f32 v154, v156, v157
	v_lshlrev_b64 v[156:157], 9, v[150:151]
	v_cndmask_b32_e64 v163, 0, 32, vcc
	v_ldexp_f32 v161, v161, v163
	v_log_f32_e32 v161, v161
	v_lshl_add_u64 v[156:157], s[24:25], 0, v[156:157]
	v_lshl_add_u64 v[156:157], v[156:157], 0, v[184:185]
	v_mul_f32_e32 v163, 0x3f317217, v161
	v_fma_f32 v163, v161, s90, -v163
	v_fmac_f32_e32 v163, 0x3377d1cf, v161
	v_fmac_f32_e32 v163, 0x3f317217, v161
	v_cmp_lt_f32_e64 s[6:7], |v161|, s91
	s_nop 1
	v_cndmask_b32_e64 v161, v161, v163, s[6:7]
	v_cndmask_b32_e32 v163, 0, v222, vcc
	v_sub_f32_e32 v164, v161, v163
	v_fma_f32 v163, v117, v162, v133
	v_min_f32_e32 v161, 0, v163
	v_mul_f32_e64 v163, |v163|, s88
	v_exp_f32_e32 v163, v163
	s_nop 0
	v_add_f32_e32 v163, 1.0, v163
	v_cmp_gt_f32_e32 vcc, s89, v163
	s_nop 1
	v_cndmask_b32_e64 v165, 0, 32, vcc
	v_ldexp_f32 v163, v163, v165
	v_log_f32_e32 v163, v163
	s_nop 0
	v_mul_f32_e32 v165, 0x3f317217, v163
	v_fma_f32 v165, v163, s90, -v165
	v_fmac_f32_e32 v165, 0x3377d1cf, v163
	v_fmac_f32_e32 v165, 0x3f317217, v163
	v_cmp_lt_f32_e64 s[6:7], |v163|, s91
	s_nop 1
	v_cndmask_b32_e64 v163, v163, v165, s[6:7]
	v_cndmask_b32_e32 v165, 0, v222, vcc
	v_sub_f32_e32 v165, v163, v165
	v_pk_add_f32 v[160:161], v[160:161], v[164:165] neg_lo:[0,1] neg_hi:[0,1]
	v_add_u32_e32 v163, s77, v230
	v_pk_mul_f32 v[160:161], v[160:161], s[28:29] op_sel_hi:[1,0]
	v_fma_f32 v165, v99, v210, v131
	v_cvt_pk_bf16_f32 v155, v160, v161
	v_add_u32_e32 v160, s77, v229
	v_add_u32_e32 v161, s77, v228
	ds_write_b128 v160, v[146:149]
	ds_write_b128 v161, v[152:155]
	ds_read_b128 v[146:149], v163
	ds_read_b128 v[152:155], v163 offset:1024
	s_waitcnt lgkmcnt(1)
	global_store_dwordx4 v[156:157], v[146:149], off
	s_nop 1
	v_add_co_u32_e32 v146, vcc, s92, v156
	v_fma_f32 v149, v111, v210, v143
	s_nop 0
	v_addc_co_u32_e32 v147, vcc, 0, v157, vcc
	s_waitcnt lgkmcnt(0)
	global_store_dwordx4 v[146:147], v[152:155], off
	v_fma_f32 v147, v110, v210, v142
	v_min_f32_e32 v146, 0, v147
	v_mul_f32_e64 v147, |v147|, s88
	v_exp_f32_e32 v147, v147
	v_fma_f32 v153, v113, v210, v145
	v_fma_f32 v155, v107, v210, v139
	v_fma_f32 v157, v109, v210, v141
	v_add_f32_e32 v147, 1.0, v147
	v_cmp_gt_f32_e32 vcc, s89, v147
	s_nop 1
	v_cndmask_b32_e64 v148, 0, 32, vcc
	v_ldexp_f32 v147, v147, v148
	v_log_f32_e32 v147, v147
	s_nop 0
	v_mul_f32_e32 v148, 0x3f317217, v147
	v_fma_f32 v148, v147, s90, -v148
	v_fmac_f32_e32 v148, 0x3377d1cf, v147
	v_fmac_f32_e32 v148, 0x3f317217, v147
	v_cmp_lt_f32_e64 s[6:7], |v147|, s91
	s_nop 1
	v_cndmask_b32_e64 v147, v147, v148, s[6:7]
	v_cndmask_b32_e32 v148, 0, v222, vcc
	v_sub_f32_e32 v148, v147, v148
	v_min_f32_e32 v147, 0, v149
	v_mul_f32_e64 v149, |v149|, s88
	v_exp_f32_e32 v149, v149
	s_nop 0
	v_add_f32_e32 v149, 1.0, v149
	v_cmp_gt_f32_e32 vcc, s89, v149
	s_nop 1
	v_cndmask_b32_e64 v152, 0, 32, vcc
	v_ldexp_f32 v149, v149, v152
	v_log_f32_e32 v149, v149
	s_nop 0
	v_mul_f32_e32 v152, 0x3f317217, v149
	v_fma_f32 v152, v149, s90, -v152
	v_fmac_f32_e32 v152, 0x3377d1cf, v149
	v_fmac_f32_e32 v152, 0x3f317217, v149
	v_cmp_lt_f32_e64 s[6:7], |v149|, s91
	s_nop 1
	v_cndmask_b32_e64 v149, v149, v152, s[6:7]
	v_cndmask_b32_e32 v152, 0, v222, vcc
	v_sub_f32_e32 v149, v149, v152
	v_pk_add_f32 v[146:147], v[146:147], v[148:149] neg_lo:[0,1] neg_hi:[0,1]
	v_fma_f32 v149, v112, v210, v144
	v_min_f32_e32 v148, 0, v149
	v_mul_f32_e64 v149, |v149|, s88
	v_exp_f32_e32 v149, v149
	v_pk_mul_f32 v[146:147], v[146:147], s[28:29] op_sel_hi:[1,0]
	v_add_f32_e32 v149, 1.0, v149
	v_cmp_gt_f32_e32 vcc, s89, v149
	v_cvt_pk_bf16_f32 v146, v146, v147
	s_nop 0
	v_cndmask_b32_e64 v152, 0, 32, vcc
	v_ldexp_f32 v149, v149, v152
	v_log_f32_e32 v149, v149
	s_nop 0
	v_mul_f32_e32 v152, 0x3f317217, v149
	v_fma_f32 v152, v149, s90, -v152
	v_fmac_f32_e32 v152, 0x3377d1cf, v149
	v_fmac_f32_e32 v152, 0x3f317217, v149
	v_cmp_lt_f32_e64 s[6:7], |v149|, s91
	s_nop 1
	v_cndmask_b32_e64 v149, v149, v152, s[6:7]
	v_cndmask_b32_e32 v152, 0, v222, vcc
	v_sub_f32_e32 v152, v149, v152
	v_min_f32_e32 v149, 0, v153
	v_mul_f32_e64 v153, |v153|, s88
	v_exp_f32_e32 v153, v153
	s_nop 0
	v_add_f32_e32 v153, 1.0, v153
	v_cmp_gt_f32_e32 vcc, s89, v153
	s_nop 1
	v_cndmask_b32_e64 v154, 0, 32, vcc
	v_ldexp_f32 v153, v153, v154
	v_log_f32_e32 v153, v153
	s_nop 0
	v_mul_f32_e32 v154, 0x3f317217, v153
	v_fma_f32 v154, v153, s90, -v154
	v_fmac_f32_e32 v154, 0x3377d1cf, v153
; __device__ __forceinline__ v4u pack8(const f32x4 a, const f32x4 b) { v4u w; w.x = pk2(a[0], a[1]); w.y = pk2(a[2], a[3]); w.z = pk2(b[0], b[1]); w.w = pk2(b[2], b[3]); return w; }
; __device__ __forceinline__ float fast_exp(float x) { return __builtin_amdgcn_exp2f(x * LOG2E); }
;     __device__ __forceinline__ void operator()(const f32x4 (&acc)[2][2][4][2], const pg8::Unit& u, int wr, int wc, int fr, int fq) const {
;     ...
;             for (int ai = 0; ai < 2; ++ai)
; #pragma unroll
;                 for (int m = 0; m < 4; ++m) {
;                     const int rowa = 256 * pm + 128 * ai + 64 * wr + 16 * m + tt.rr;
;                     const float rs = rs8[ai][m];
;                     v4u pk[2];
; #pragma unroll
;                     for (int bj = 0; bj < 2; ++bj) {
;                         f32x4 r2[2];
; #pragma unroll
;                         for (int n = 0; n < 2; ++n) {
;                             const f32x4 z = acc[ai][bj][m][n] * rs + bg[bj][n];
; #pragma unroll
;                             for (int j = 0; j < 4; ++j) { const float az = fabsf(z[j]); r2[n][j] = (fminf(z[j], 0.f) - __logf(1.0f + fast_exp(-az))) * (1.0f / 16.0f); }
;                         }
;                         pk[bj] = pack8(r2[0], r2[1]);
;                     }
;                     v4u a, b; tt.bf(pk[0], pk[1], a, b);
;                     bf16* d = (bf16*)(ws + WS_LOGA) + (size_t)rowa * 256 + 64 * wc + 8 * tt.p; *(v4u*)d = a; *(v4u*)(d + 8 * 256) = b;
	v_fmac_f32_e32 v154, 0x3f317217, v153
	v_cmp_lt_f32_e64 s[6:7], |v153|, s91
	s_nop 1
	v_cndmask_b32_e64 v153, v153, v154, s[6:7]
	v_cndmask_b32_e32 v154, 0, v222, vcc
	v_sub_f32_e32 v153, v153, v154
	v_pk_add_f32 v[148:149], v[148:149], v[152:153] neg_lo:[0,1] neg_hi:[0,1]
	v_fma_f32 v153, v106, v210, v138
	v_min_f32_e32 v152, 0, v153
	v_mul_f32_e64 v153, |v153|, s88
	v_exp_f32_e32 v153, v153
	v_pk_mul_f32 v[148:149], v[148:149], s[28:29] op_sel_hi:[1,0]
	v_add_f32_e32 v153, 1.0, v153
	v_cmp_gt_f32_e32 vcc, s89, v153
	v_cvt_pk_bf16_f32 v147, v148, v149
	s_nop 0
	v_cndmask_b32_e64 v154, 0, 32, vcc
	v_ldexp_f32 v153, v153, v154
	v_log_f32_e32 v153, v153
	s_nop 0
	v_mul_f32_e32 v154, 0x3f317217, v153
	v_fma_f32 v154, v153, s90, -v154
	v_fmac_f32_e32 v154, 0x3377d1cf, v153
	v_fmac_f32_e32 v154, 0x3f317217, v153
	v_cmp_lt_f32_e64 s[6:7], |v153|, s91
	s_nop 1
	v_cndmask_b32_e64 v153, v153, v154, s[6:7]
	v_cndmask_b32_e32 v154, 0, v222, vcc
	v_sub_f32_e32 v154, v153, v154
	v_min_f32_e32 v153, 0, v155
	v_mul_f32_e64 v155, |v155|, s88
	v_exp_f32_e32 v155, v155
	s_nop 0
	v_add_f32_e32 v155, 1.0, v155
	v_cmp_gt_f32_e32 vcc, s89, v155
	s_nop 1
	v_cndmask_b32_e64 v156, 0, 32, vcc
	v_ldexp_f32 v155, v155, v156
	v_log_f32_e32 v155, v155
	s_nop 0
	v_mul_f32_e32 v156, 0x3f317217, v155
	v_fma_f32 v156, v155, s90, -v156
	v_fmac_f32_e32 v156, 0x3377d1cf, v155
	v_fmac_f32_e32 v156, 0x3f317217, v155
	v_cmp_lt_f32_e64 s[6:7], |v155|, s91
	s_nop 1
	v_cndmask_b32_e64 v155, v155, v156, s[6:7]
	v_cndmask_b32_e32 v156, 0, v222, vcc
	v_sub_f32_e32 v155, v155, v156
	v_pk_add_f32 v[152:153], v[152:153], v[154:155] neg_lo:[0,1] neg_hi:[0,1]
	v_fma_f32 v155, v108, v210, v140
	v_min_f32_e32 v154, 0, v155
	v_mul_f32_e64 v155, |v155|, s88
	v_exp_f32_e32 v155, v155
	v_pk_mul_f32 v[152:153], v[152:153], s[28:29] op_sel_hi:[1,0]
	v_add_f32_e32 v155, 1.0, v155
	v_cmp_gt_f32_e32 vcc, s89, v155
	v_cvt_pk_bf16_f32 v148, v152, v153
	v_fma_f32 v153, v102, v210, v134
	v_cndmask_b32_e64 v156, 0, 32, vcc
	v_ldexp_f32 v155, v155, v156
	v_log_f32_e32 v155, v155
	v_min_f32_e32 v152, 0, v153
	v_mul_f32_e64 v153, |v153|, s88
	v_exp_f32_e32 v153, v153
	v_mul_f32_e32 v156, 0x3f317217, v155
	v_fma_f32 v156, v155, s90, -v156
	v_fmac_f32_e32 v156, 0x3377d1cf, v155
	v_fmac_f32_e32 v156, 0x3f317217, v155
	v_cmp_lt_f32_e64 s[6:7], |v155|, s91
	v_add_f32_e32 v153, 1.0, v153
	s_nop 0
	v_cndmask_b32_e64 v155, v155, v156, s[6:7]
	v_cndmask_b32_e32 v156, 0, v222, vcc
	v_sub_f32_e32 v156, v155, v156
	v_min_f32_e32 v155, 0, v157
	v_mul_f32_e64 v157, |v157|, s88
	v_exp_f32_e32 v157, v157
	s_nop 0
	v_add_f32_e32 v157, 1.0, v157
	v_cmp_gt_f32_e32 vcc, s89, v157
	s_nop 1
	v_cndmask_b32_e64 v164, 0, 32, vcc
	v_ldexp_f32 v157, v157, v164
	v_log_f32_e32 v157, v157
	s_nop 0
	v_mul_f32_e32 v164, 0x3f317217, v157
	v_fma_f32 v164, v157, s90, -v164
	v_fmac_f32_e32 v164, 0x3377d1cf, v157
	v_fmac_f32_e32 v164, 0x3f317217, v157
	v_cmp_lt_f32_e64 s[6:7], |v157|, s91
	s_nop 1
	v_cndmask_b32_e64 v157, v157, v164, s[6:7]
	v_cndmask_b32_e32 v164, 0, v222, vcc
	v_sub_f32_e32 v157, v157, v164
	v_pk_add_f32 v[154:155], v[154:155], v[156:157] neg_lo:[0,1] neg_hi:[0,1]
	v_cmp_gt_f32_e32 vcc, s89, v153
	v_pk_mul_f32 v[154:155], v[154:155], s[28:29] op_sel_hi:[1,0]
	v_fma_f32 v157, v105, v210, v137
	v_cvt_pk_bf16_f32 v149, v154, v155
	v_cndmask_b32_e64 v154, 0, 32, vcc
	v_ldexp_f32 v153, v153, v154
	v_log_f32_e32 v153, v153
	v_fma_f32 v155, v103, v210, v135
	v_mul_f32_e32 v154, 0x3f317217, v153
	v_fma_f32 v154, v153, s90, -v154
	v_fmac_f32_e32 v154, 0x3377d1cf, v153
	v_fmac_f32_e32 v154, 0x3f317217, v153
	v_cmp_lt_f32_e64 s[6:7], |v153|, s91
	s_nop 1
	v_cndmask_b32_e64 v153, v153, v154, s[6:7]
	v_cndmask_b32_e32 v154, 0, v222, vcc
	v_sub_f32_e32 v154, v153, v154
	v_min_f32_e32 v153, 0, v155
	v_mul_f32_e64 v155, |v155|, s88
	v_exp_f32_e32 v155, v155
	s_nop 0
	v_add_f32_e32 v155, 1.0, v155
	v_cmp_gt_f32_e32 vcc, s89, v155
	s_nop 1
	v_cndmask_b32_e64 v156, 0, 32, vcc
	v_ldexp_f32 v155, v155, v156
	v_log_f32_e32 v155, v155
	s_nop 0
	v_mul_f32_e32 v156, 0x3f317217, v155
	v_fma_f32 v156, v155, s90, -v156
	v_fmac_f32_e32 v156, 0x3377d1cf, v155
	v_fmac_f32_e32 v156, 0x3f317217, v155
	v_cmp_lt_f32_e64 s[6:7], |v155|, s91
	s_nop 1
	v_cndmask_b32_e64 v155, v155, v156, s[6:7]
	v_cndmask_b32_e32 v156, 0, v222, vcc
	v_sub_f32_e32 v155, v155, v156
	v_pk_add_f32 v[152:153], v[152:153], v[154:155] neg_lo:[0,1] neg_hi:[0,1]
	v_fma_f32 v155, v104, v210, v136
	v_min_f32_e32 v154, 0, v155
	v_mul_f32_e64 v155, |v155|, s88
	v_exp_f32_e32 v155, v155
	v_pk_mul_f32 v[152:153], v[152:153], s[28:29] op_sel_hi:[1,0]
	v_add_f32_e32 v155, 1.0, v155
	v_cmp_gt_f32_e32 vcc, s89, v155
	v_cvt_pk_bf16_f32 v152, v152, v153
	s_nop 0
	v_cndmask_b32_e64 v156, 0, 32, vcc
	v_ldexp_f32 v155, v155, v156
	v_log_f32_e32 v155, v155
	s_nop 0
	v_mul_f32_e32 v156, 0x3f317217, v155
	v_fma_f32 v156, v155, s90, -v156
	v_fmac_f32_e32 v156, 0x3377d1cf, v155
	v_fmac_f32_e32 v156, 0x3f317217, v155
	v_cmp_lt_f32_e64 s[6:7], |v155|, s91
	s_nop 1
	v_cndmask_b32_e64 v155, v155, v156, s[6:7]
	v_cndmask_b32_e32 v156, 0, v222, vcc
	v_sub_f32_e32 v156, v155, v156
	v_min_f32_e32 v155, 0, v157
	v_mul_f32_e64 v157, |v157|, s88
	v_exp_f32_e32 v157, v157
	s_nop 0
	v_add_f32_e32 v157, 1.0, v157
	v_cmp_gt_f32_e32 vcc, s89, v157
	s_nop 1
	v_cndmask_b32_e64 v164, 0, 32, vcc
	v_ldexp_f32 v157, v157, v164
	v_log_f32_e32 v157, v157
	s_nop 0
	v_mul_f32_e32 v164, 0x3f317217, v157
	v_fma_f32 v164, v157, s90, -v164
	v_fmac_f32_e32 v164, 0x3377d1cf, v157
	v_fmac_f32_e32 v164, 0x3f317217, v157
	v_cmp_lt_f32_e64 s[6:7], |v157|, s91
	s_nop 1
	v_cndmask_b32_e64 v157, v157, v164, s[6:7]
	v_cndmask_b32_e32 v164, 0, v222, vcc
; __device__ __forceinline__ v4u pack8(const f32x4 a, const f32x4 b) { v4u w; w.x = pk2(a[0], a[1]); w.y = pk2(a[2], a[3]); w.z = pk2(b[0], b[1]); w.w = pk2(b[2], b[3]); return w; }
; __device__ __forceinline__ float fast_exp(float x) { return __builtin_amdgcn_exp2f(x * LOG2E); }
;     __device__ __forceinline__ void operator()(const f32x4 (&acc)[2][2][4][2], const pg8::Unit& u, int wr, int wc, int fr, int fq) const {
;     ...
;             for (int ai = 0; ai < 2; ++ai)
; #pragma unroll
;                 for (int m = 0; m < 4; ++m) {
;                     const int rowa = 256 * pm + 128 * ai + 64 * wr + 16 * m + tt.rr;
;                     const float rs = rs8[ai][m];
;                     v4u pk[2];
; #pragma unroll
;                     for (int bj = 0; bj < 2; ++bj) {
;                         f32x4 r2[2];
; #pragma unroll
;                         for (int n = 0; n < 2; ++n) {
;                             const f32x4 z = acc[ai][bj][m][n] * rs + bg[bj][n];
; #pragma unroll
;                             for (int j = 0; j < 4; ++j) { const float az = fabsf(z[j]); r2[n][j] = (fminf(z[j], 0.f) - __logf(1.0f + fast_exp(-az))) * (1.0f / 16.0f); }
;                         }
;                         pk[bj] = pack8(r2[0], r2[1]);
;                     }
;                     v4u a, b; tt.bf(pk[0], pk[1], a, b);
;                     bf16* d = (bf16*)(ws + WS_LOGA) + (size_t)rowa * 256 + 64 * wc + 8 * tt.p; *(v4u*)d = a; *(v4u*)(d + 8 * 256) = b;
	v_sub_f32_e32 v157, v157, v164
	v_pk_add_f32 v[154:155], v[154:155], v[156:157] neg_lo:[0,1] neg_hi:[0,1]
	v_fma_f32 v157, v98, v210, v130
	v_min_f32_e32 v156, 0, v157
	v_mul_f32_e64 v157, |v157|, s88
	v_exp_f32_e32 v157, v157
	v_pk_mul_f32 v[154:155], v[154:155], s[28:29] op_sel_hi:[1,0]
	v_add_f32_e32 v157, 1.0, v157
	v_cmp_gt_f32_e32 vcc, s89, v157
	v_cvt_pk_bf16_f32 v153, v154, v155
	s_nop 0
	v_cndmask_b32_e64 v164, 0, 32, vcc
	v_ldexp_f32 v157, v157, v164
	v_log_f32_e32 v157, v157
	s_nop 0
	v_mul_f32_e32 v164, 0x3f317217, v157
	v_fma_f32 v164, v157, s90, -v164
	v_fmac_f32_e32 v164, 0x3377d1cf, v157
	v_fmac_f32_e32 v164, 0x3f317217, v157
	v_cmp_lt_f32_e64 s[6:7], |v157|, s91
	s_nop 1
	v_cndmask_b32_e64 v157, v157, v164, s[6:7]
	v_cndmask_b32_e32 v164, 0, v222, vcc
	v_sub_f32_e32 v164, v157, v164
	v_min_f32_e32 v157, 0, v165
	v_mul_f32_e64 v165, |v165|, s88
	v_exp_f32_e32 v165, v165
	s_nop 0
	v_add_f32_e32 v165, 1.0, v165
	v_cmp_gt_f32_e32 vcc, s89, v165
	s_nop 1
	v_cndmask_b32_e64 v166, 0, 32, vcc
	v_ldexp_f32 v165, v165, v166
	v_log_f32_e32 v165, v165
	s_nop 0
	v_mul_f32_e32 v166, 0x3f317217, v165
	v_fma_f32 v166, v165, s90, -v166
	v_fmac_f32_e32 v166, 0x3377d1cf, v165
	v_fmac_f32_e32 v166, 0x3f317217, v165
	v_cmp_lt_f32_e64 s[6:7], |v165|, s91
	s_nop 1
	v_cndmask_b32_e64 v165, v165, v166, s[6:7]
	v_cndmask_b32_e32 v166, 0, v222, vcc
	v_sub_f32_e32 v165, v165, v166
	v_pk_add_f32 v[156:157], v[156:157], v[164:165] neg_lo:[0,1] neg_hi:[0,1]
	v_fma_f32 v165, v100, v210, v132
	v_min_f32_e32 v164, 0, v165
	v_mul_f32_e64 v165, |v165|, s88
	v_exp_f32_e32 v165, v165
	v_pk_mul_f32 v[156:157], v[156:157], s[28:29] op_sel_hi:[1,0]
	v_add_f32_e32 v165, 1.0, v165
	v_cmp_gt_f32_e32 vcc, s89, v165
	v_cvt_pk_bf16_f32 v154, v156, v157
	v_add_u32_e32 v156, 16, v150
	v_cndmask_b32_e64 v166, 0, 32, vcc
	v_ldexp_f32 v165, v165, v166
	v_log_f32_e32 v165, v165
	v_ashrrev_i32_e32 v157, 31, v156
	v_lshlrev_b64 v[156:157], 9, v[156:157]
	v_lshl_add_u64 v[156:157], s[24:25], 0, v[156:157]
	v_mul_f32_e32 v166, 0x3f317217, v165
	v_fma_f32 v166, v165, s90, -v166
	v_fmac_f32_e32 v166, 0x3377d1cf, v165
	v_fmac_f32_e32 v166, 0x3f317217, v165
	v_cmp_lt_f32_e64 s[6:7], |v165|, s91
	v_lshl_add_u64 v[156:157], v[156:157], 0, v[184:185]
	s_nop 0
	v_cndmask_b32_e64 v165, v165, v166, s[6:7]
	v_cndmask_b32_e32 v166, 0, v222, vcc
	v_sub_f32_e32 v166, v165, v166
	v_min_f32_e32 v165, 0, v167
	v_mul_f32_e64 v167, |v167|, s88
	v_exp_f32_e32 v167, v167
	s_nop 0
	v_add_f32_e32 v167, 1.0, v167
	v_cmp_gt_f32_e32 vcc, s89, v167
	s_nop 1
	v_cndmask_b32_e64 v168, 0, 32, vcc
	v_ldexp_f32 v167, v167, v168
	v_log_f32_e32 v167, v167
	s_nop 0
	v_mul_f32_e32 v168, 0x3f317217, v167
	v_fma_f32 v168, v167, s90, -v168
	v_fmac_f32_e32 v168, 0x3377d1cf, v167
	v_fmac_f32_e32 v168, 0x3f317217, v167
	v_cmp_lt_f32_e64 s[6:7], |v167|, s91
	s_nop 1
	v_cndmask_b32_e64 v167, v167, v168, s[6:7]
	v_cndmask_b32_e32 v168, 0, v222, vcc
	v_sub_f32_e32 v167, v167, v168
	v_pk_add_f32 v[164:165], v[164:165], v[166:167] neg_lo:[0,1] neg_hi:[0,1]
	v_fma_f32 v167, v85, v208, v133
	v_pk_mul_f32 v[164:165], v[164:165], s[28:29] op_sel_hi:[1,0]
	s_nop 0
	v_cvt_pk_bf16_f32 v155, v164, v165
	ds_write_b128 v160, v[146:149]
	ds_write_b128 v161, v[152:155]
	ds_read_b128 v[146:149], v163
	ds_read_b128 v[152:155], v163 offset:1024
	v_fma_f32 v165, v83, v208, v131
	s_waitcnt lgkmcnt(1)
	global_store_dwordx4 v[156:157], v[146:149], off
	s_nop 1
	v_add_co_u32_e32 v146, vcc, s92, v156
	v_fma_f32 v149, v95, v208, v143
	s_nop 0
	v_addc_co_u32_e32 v147, vcc, 0, v157, vcc
	s_waitcnt lgkmcnt(0)
	global_store_dwordx4 v[146:147], v[152:155], off
	v_fma_f32 v147, v94, v208, v142
	v_min_f32_e32 v146, 0, v147
	v_mul_f32_e64 v147, |v147|, s88
	v_exp_f32_e32 v147, v147
	v_fma_f32 v153, v97, v208, v145
	v_fma_f32 v155, v91, v208, v139
	v_fma_f32 v157, v93, v208, v141
	v_add_f32_e32 v147, 1.0, v147
	v_cmp_gt_f32_e32 vcc, s89, v147
	s_nop 1
	v_cndmask_b32_e64 v148, 0, 32, vcc
	v_ldexp_f32 v147, v147, v148
	v_log_f32_e32 v147, v147
	s_nop 0
	v_mul_f32_e32 v148, 0x3f317217, v147
	v_fma_f32 v148, v147, s90, -v148
	v_fmac_f32_e32 v148, 0x3377d1cf, v147
	v_fmac_f32_e32 v148, 0x3f317217, v147
	v_cmp_lt_f32_e64 s[6:7], |v147|, s91
	s_nop 1
	v_cndmask_b32_e64 v147, v147, v148, s[6:7]
	v_cndmask_b32_e32 v148, 0, v222, vcc
	v_sub_f32_e32 v148, v147, v148
	v_min_f32_e32 v147, 0, v149
	v_mul_f32_e64 v149, |v149|, s88
	v_exp_f32_e32 v149, v149
	s_nop 0
	v_add_f32_e32 v149, 1.0, v149
	v_cmp_gt_f32_e32 vcc, s89, v149
	s_nop 1
	v_cndmask_b32_e64 v152, 0, 32, vcc
	v_ldexp_f32 v149, v149, v152
	v_log_f32_e32 v149, v149
	s_nop 0
	v_mul_f32_e32 v152, 0x3f317217, v149
	v_fma_f32 v152, v149, s90, -v152
	v_fmac_f32_e32 v152, 0x3377d1cf, v149
	v_fmac_f32_e32 v152, 0x3f317217, v149
	v_cmp_lt_f32_e64 s[6:7], |v149|, s91
	s_nop 1
	v_cndmask_b32_e64 v149, v149, v152, s[6:7]
	v_cndmask_b32_e32 v152, 0, v222, vcc
	v_sub_f32_e32 v149, v149, v152
	v_pk_add_f32 v[146:147], v[146:147], v[148:149] neg_lo:[0,1] neg_hi:[0,1]
	v_fma_f32 v149, v96, v208, v144
	v_min_f32_e32 v148, 0, v149
	v_mul_f32_e64 v149, |v149|, s88
	v_exp_f32_e32 v149, v149
	v_pk_mul_f32 v[146:147], v[146:147], s[28:29] op_sel_hi:[1,0]
	v_add_f32_e32 v149, 1.0, v149
	v_cmp_gt_f32_e32 vcc, s89, v149
	v_cvt_pk_bf16_f32 v146, v146, v147
	s_nop 0
	v_cndmask_b32_e64 v152, 0, 32, vcc
	v_ldexp_f32 v149, v149, v152
	v_log_f32_e32 v149, v149
	s_nop 0
	v_mul_f32_e32 v152, 0x3f317217, v149
	v_fma_f32 v152, v149, s90, -v152
	v_fmac_f32_e32 v152, 0x3377d1cf, v149
	v_fmac_f32_e32 v152, 0x3f317217, v149
	v_cmp_lt_f32_e64 s[6:7], |v149|, s91
	s_nop 1
	v_cndmask_b32_e64 v149, v149, v152, s[6:7]
	v_cndmask_b32_e32 v152, 0, v222, vcc
; __device__ __forceinline__ v4u pack8(const f32x4 a, const f32x4 b) { v4u w; w.x = pk2(a[0], a[1]); w.y = pk2(a[2], a[3]); w.z = pk2(b[0], b[1]); w.w = pk2(b[2], b[3]); return w; }
; __device__ __forceinline__ float fast_exp(float x) { return __builtin_amdgcn_exp2f(x * LOG2E); }
;     __device__ __forceinline__ void operator()(const f32x4 (&acc)[2][2][4][2], const pg8::Unit& u, int wr, int wc, int fr, int fq) const {
;     ...
;             for (int ai = 0; ai < 2; ++ai)
; #pragma unroll
;                 for (int m = 0; m < 4; ++m) {
;                     const int rowa = 256 * pm + 128 * ai + 64 * wr + 16 * m + tt.rr;
;                     const float rs = rs8[ai][m];
;                     v4u pk[2];
; #pragma unroll
;                     for (int bj = 0; bj < 2; ++bj) {
;                         f32x4 r2[2];
; #pragma unroll
;                         for (int n = 0; n < 2; ++n) {
;                             const f32x4 z = acc[ai][bj][m][n] * rs + bg[bj][n];
; #pragma unroll
;                             for (int j = 0; j < 4; ++j) { const float az = fabsf(z[j]); r2[n][j] = (fminf(z[j], 0.f) - __logf(1.0f + fast_exp(-az))) * (1.0f / 16.0f); }
;                         }
;                         pk[bj] = pack8(r2[0], r2[1]);
;                     }
;                     v4u a, b; tt.bf(pk[0], pk[1], a, b);
;                     bf16* d = (bf16*)(ws + WS_LOGA) + (size_t)rowa * 256 + 64 * wc + 8 * tt.p; *(v4u*)d = a; *(v4u*)(d + 8 * 256) = b;
	v_sub_f32_e32 v152, v149, v152
	v_min_f32_e32 v149, 0, v153
	v_mul_f32_e64 v153, |v153|, s88
	v_exp_f32_e32 v153, v153
	s_nop 0
	v_add_f32_e32 v153, 1.0, v153
	v_cmp_gt_f32_e32 vcc, s89, v153
	s_nop 1
	v_cndmask_b32_e64 v154, 0, 32, vcc
	v_ldexp_f32 v153, v153, v154
	v_log_f32_e32 v153, v153
	s_nop 0
	v_mul_f32_e32 v154, 0x3f317217, v153
	v_fma_f32 v154, v153, s90, -v154
	v_fmac_f32_e32 v154, 0x3377d1cf, v153
	v_fmac_f32_e32 v154, 0x3f317217, v153
	v_cmp_lt_f32_e64 s[6:7], |v153|, s91
	s_nop 1
	v_cndmask_b32_e64 v153, v153, v154, s[6:7]
	v_cndmask_b32_e32 v154, 0, v222, vcc
	v_sub_f32_e32 v153, v153, v154
	v_pk_add_f32 v[148:149], v[148:149], v[152:153] neg_lo:[0,1] neg_hi:[0,1]
	v_fma_f32 v153, v90, v208, v138
	v_min_f32_e32 v152, 0, v153
	v_mul_f32_e64 v153, |v153|, s88
	v_exp_f32_e32 v153, v153
	v_pk_mul_f32 v[148:149], v[148:149], s[28:29] op_sel_hi:[1,0]
	v_add_f32_e32 v153, 1.0, v153
	v_cmp_gt_f32_e32 vcc, s89, v153
	v_cvt_pk_bf16_f32 v147, v148, v149
	s_nop 0
	v_cndmask_b32_e64 v154, 0, 32, vcc
	v_ldexp_f32 v153, v153, v154
	v_log_f32_e32 v153, v153
	s_nop 0
	v_mul_f32_e32 v154, 0x3f317217, v153
	v_fma_f32 v154, v153, s90, -v154
	v_fmac_f32_e32 v154, 0x3377d1cf, v153
	v_fmac_f32_e32 v154, 0x3f317217, v153
	v_cmp_lt_f32_e64 s[6:7], |v153|, s91
	s_nop 1
	v_cndmask_b32_e64 v153, v153, v154, s[6:7]
	v_cndmask_b32_e32 v154, 0, v222, vcc
	v_sub_f32_e32 v154, v153, v154
	v_min_f32_e32 v153, 0, v155
	v_mul_f32_e64 v155, |v155|, s88
	v_exp_f32_e32 v155, v155
	s_nop 0
	v_add_f32_e32 v155, 1.0, v155
	v_cmp_gt_f32_e32 vcc, s89, v155
	s_nop 1
	v_cndmask_b32_e64 v156, 0, 32, vcc
	v_ldexp_f32 v155, v155, v156
	v_log_f32_e32 v155, v155
	s_nop 0
	v_mul_f32_e32 v156, 0x3f317217, v155
	v_fma_f32 v156, v155, s90, -v156
	v_fmac_f32_e32 v156, 0x3377d1cf, v155
	v_fmac_f32_e32 v156, 0x3f317217, v155
	v_cmp_lt_f32_e64 s[6:7], |v155|, s91
	s_nop 1
	v_cndmask_b32_e64 v155, v155, v156, s[6:7]
	v_cndmask_b32_e32 v156, 0, v222, vcc
	v_sub_f32_e32 v155, v155, v156
	v_pk_add_f32 v[152:153], v[152:153], v[154:155] neg_lo:[0,1] neg_hi:[0,1]
	v_fma_f32 v155, v92, v208, v140
	v_min_f32_e32 v154, 0, v155
	v_mul_f32_e64 v155, |v155|, s88
	v_exp_f32_e32 v155, v155
	v_pk_mul_f32 v[152:153], v[152:153], s[28:29] op_sel_hi:[1,0]
	v_add_f32_e32 v155, 1.0, v155
	v_cmp_gt_f32_e32 vcc, s89, v155
	v_cvt_pk_bf16_f32 v148, v152, v153
	v_fma_f32 v153, v86, v208, v134
	v_cndmask_b32_e64 v156, 0, 32, vcc
	v_ldexp_f32 v155, v155, v156
	v_log_f32_e32 v155, v155
	v_min_f32_e32 v152, 0, v153
	v_mul_f32_e64 v153, |v153|, s88
	v_exp_f32_e32 v153, v153
	v_mul_f32_e32 v156, 0x3f317217, v155
	v_fma_f32 v156, v155, s90, -v156
	v_fmac_f32_e32 v156, 0x3377d1cf, v155
	v_fmac_f32_e32 v156, 0x3f317217, v155
	v_cmp_lt_f32_e64 s[6:7], |v155|, s91
	v_add_f32_e32 v153, 1.0, v153
	s_nop 0
	v_cndmask_b32_e64 v155, v155, v156, s[6:7]
	v_cndmask_b32_e32 v156, 0, v222, vcc
	v_sub_f32_e32 v156, v155, v156
	v_min_f32_e32 v155, 0, v157
	v_mul_f32_e64 v157, |v157|, s88
	v_exp_f32_e32 v157, v157
	s_nop 0
	v_add_f32_e32 v157, 1.0, v157
	v_cmp_gt_f32_e32 vcc, s89, v157
	s_nop 1
	v_cndmask_b32_e64 v164, 0, 32, vcc
	v_ldexp_f32 v157, v157, v164
	v_log_f32_e32 v157, v157
	s_nop 0
	v_mul_f32_e32 v164, 0x3f317217, v157
	v_fma_f32 v164, v157, s90, -v164
	v_fmac_f32_e32 v164, 0x3377d1cf, v157
	v_fmac_f32_e32 v164, 0x3f317217, v157
	v_cmp_lt_f32_e64 s[6:7], |v157|, s91
	s_nop 1
	v_cndmask_b32_e64 v157, v157, v164, s[6:7]
	v_cndmask_b32_e32 v164, 0, v222, vcc
	v_sub_f32_e32 v157, v157, v164
	v_pk_add_f32 v[154:155], v[154:155], v[156:157] neg_lo:[0,1] neg_hi:[0,1]
	v_cmp_gt_f32_e32 vcc, s89, v153
	v_pk_mul_f32 v[154:155], v[154:155], s[28:29] op_sel_hi:[1,0]
	v_fma_f32 v157, v89, v208, v137
	v_cvt_pk_bf16_f32 v149, v154, v155
	v_cndmask_b32_e64 v154, 0, 32, vcc
	v_ldexp_f32 v153, v153, v154
	v_log_f32_e32 v153, v153
	v_fma_f32 v155, v87, v208, v135
	v_mul_f32_e32 v154, 0x3f317217, v153
	v_fma_f32 v154, v153, s90, -v154
	v_fmac_f32_e32 v154, 0x3377d1cf, v153
	v_fmac_f32_e32 v154, 0x3f317217, v153
	v_cmp_lt_f32_e64 s[6:7], |v153|, s91
	s_nop 1
	v_cndmask_b32_e64 v153, v153, v154, s[6:7]
	v_cndmask_b32_e32 v154, 0, v222, vcc
	v_sub_f32_e32 v154, v153, v154
	v_min_f32_e32 v153, 0, v155
	v_mul_f32_e64 v155, |v155|, s88
	v_exp_f32_e32 v155, v155
	s_nop 0
	v_add_f32_e32 v155, 1.0, v155
	v_cmp_gt_f32_e32 vcc, s89, v155
	s_nop 1
	v_cndmask_b32_e64 v156, 0, 32, vcc
	v_ldexp_f32 v155, v155, v156
	v_log_f32_e32 v155, v155
	s_nop 0
	v_mul_f32_e32 v156, 0x3f317217, v155
	v_fma_f32 v156, v155, s90, -v156
	v_fmac_f32_e32 v156, 0x3377d1cf, v155
	v_fmac_f32_e32 v156, 0x3f317217, v155
	v_cmp_lt_f32_e64 s[6:7], |v155|, s91
	s_nop 1
	v_cndmask_b32_e64 v155, v155, v156, s[6:7]
	v_cndmask_b32_e32 v156, 0, v222, vcc
	v_sub_f32_e32 v155, v155, v156
	v_pk_add_f32 v[152:153], v[152:153], v[154:155] neg_lo:[0,1] neg_hi:[0,1]
	v_fma_f32 v155, v88, v208, v136
	v_min_f32_e32 v154, 0, v155
	v_mul_f32_e64 v155, |v155|, s88
	v_exp_f32_e32 v155, v155
	v_pk_mul_f32 v[152:153], v[152:153], s[28:29] op_sel_hi:[1,0]
	v_add_f32_e32 v155, 1.0, v155
	v_cmp_gt_f32_e32 vcc, s89, v155
	v_cvt_pk_bf16_f32 v152, v152, v153
	s_nop 0
	v_cndmask_b32_e64 v156, 0, 32, vcc
	v_ldexp_f32 v155, v155, v156
	v_log_f32_e32 v155, v155
	s_nop 0
	v_mul_f32_e32 v156, 0x3f317217, v155
	v_fma_f32 v156, v155, s90, -v156
	v_fmac_f32_e32 v156, 0x3377d1cf, v155
	v_fmac_f32_e32 v156, 0x3f317217, v155
	v_cmp_lt_f32_e64 s[6:7], |v155|, s91
	s_nop 1
	v_cndmask_b32_e64 v155, v155, v156, s[6:7]
	v_cndmask_b32_e32 v156, 0, v222, vcc
	v_sub_f32_e32 v156, v155, v156
	v_min_f32_e32 v155, 0, v157
	v_mul_f32_e64 v157, |v157|, s88
	v_exp_f32_e32 v157, v157
	s_nop 0
	v_add_f32_e32 v157, 1.0, v157
; __device__ __forceinline__ v4u pack8(const f32x4 a, const f32x4 b) { v4u w; w.x = pk2(a[0], a[1]); w.y = pk2(a[2], a[3]); w.z = pk2(b[0], b[1]); w.w = pk2(b[2], b[3]); return w; }
; __device__ __forceinline__ float fast_exp(float x) { return __builtin_amdgcn_exp2f(x * LOG2E); }
;     __device__ __forceinline__ void operator()(const f32x4 (&acc)[2][2][4][2], const pg8::Unit& u, int wr, int wc, int fr, int fq) const {
;     ...
;             for (int ai = 0; ai < 2; ++ai)
; #pragma unroll
;                 for (int m = 0; m < 4; ++m) {
;                     const int rowa = 256 * pm + 128 * ai + 64 * wr + 16 * m + tt.rr;
;                     const float rs = rs8[ai][m];
;                     v4u pk[2];
; #pragma unroll
;                     for (int bj = 0; bj < 2; ++bj) {
;                         f32x4 r2[2];
; #pragma unroll
;                         for (int n = 0; n < 2; ++n) {
;                             const f32x4 z = acc[ai][bj][m][n] * rs + bg[bj][n];
; #pragma unroll
;                             for (int j = 0; j < 4; ++j) { const float az = fabsf(z[j]); r2[n][j] = (fminf(z[j], 0.f) - __logf(1.0f + fast_exp(-az))) * (1.0f / 16.0f); }
;                         }
;                         pk[bj] = pack8(r2[0], r2[1]);
;                     }
;                     v4u a, b; tt.bf(pk[0], pk[1], a, b);
;                     bf16* d = (bf16*)(ws + WS_LOGA) + (size_t)rowa * 256 + 64 * wc + 8 * tt.p; *(v4u*)d = a; *(v4u*)(d + 8 * 256) = b;
	v_cmp_gt_f32_e32 vcc, s89, v157
	s_nop 1
	v_cndmask_b32_e64 v164, 0, 32, vcc
	v_ldexp_f32 v157, v157, v164
	v_log_f32_e32 v157, v157
	s_nop 0
	v_mul_f32_e32 v164, 0x3f317217, v157
	v_fma_f32 v164, v157, s90, -v164
	v_fmac_f32_e32 v164, 0x3377d1cf, v157
	v_fmac_f32_e32 v164, 0x3f317217, v157
	v_cmp_lt_f32_e64 s[6:7], |v157|, s91
	s_nop 1
	v_cndmask_b32_e64 v157, v157, v164, s[6:7]
	v_cndmask_b32_e32 v164, 0, v222, vcc
	v_sub_f32_e32 v157, v157, v164
	v_pk_add_f32 v[154:155], v[154:155], v[156:157] neg_lo:[0,1] neg_hi:[0,1]
	v_fma_f32 v157, v82, v208, v130
	v_min_f32_e32 v156, 0, v157
	v_mul_f32_e64 v157, |v157|, s88
	v_exp_f32_e32 v157, v157
	v_pk_mul_f32 v[154:155], v[154:155], s[28:29] op_sel_hi:[1,0]
	v_add_f32_e32 v157, 1.0, v157
	v_cmp_gt_f32_e32 vcc, s89, v157
	v_cvt_pk_bf16_f32 v153, v154, v155
	s_nop 0
	v_cndmask_b32_e64 v164, 0, 32, vcc
	v_ldexp_f32 v157, v157, v164
	v_log_f32_e32 v157, v157
	s_nop 0
	v_mul_f32_e32 v164, 0x3f317217, v157
	v_fma_f32 v164, v157, s90, -v164
	v_fmac_f32_e32 v164, 0x3377d1cf, v157
	v_fmac_f32_e32 v164, 0x3f317217, v157
	v_cmp_lt_f32_e64 s[6:7], |v157|, s91
	s_nop 1
	v_cndmask_b32_e64 v157, v157, v164, s[6:7]
	v_cndmask_b32_e32 v164, 0, v222, vcc
	v_sub_f32_e32 v164, v157, v164
	v_min_f32_e32 v157, 0, v165
	v_mul_f32_e64 v165, |v165|, s88
	v_exp_f32_e32 v165, v165
	s_nop 0
	v_add_f32_e32 v165, 1.0, v165
	v_cmp_gt_f32_e32 vcc, s89, v165
	s_nop 1
	v_cndmask_b32_e64 v166, 0, 32, vcc
	v_ldexp_f32 v165, v165, v166
	v_log_f32_e32 v165, v165
	s_nop 0
	v_mul_f32_e32 v166, 0x3f317217, v165
	v_fma_f32 v166, v165, s90, -v166
	v_fmac_f32_e32 v166, 0x3377d1cf, v165
	v_fmac_f32_e32 v166, 0x3f317217, v165
	v_cmp_lt_f32_e64 s[6:7], |v165|, s91
	s_nop 1
	v_cndmask_b32_e64 v165, v165, v166, s[6:7]
	v_cndmask_b32_e32 v166, 0, v222, vcc
	v_sub_f32_e32 v165, v165, v166
	v_pk_add_f32 v[156:157], v[156:157], v[164:165] neg_lo:[0,1] neg_hi:[0,1]
	v_fma_f32 v165, v84, v208, v132
	v_min_f32_e32 v164, 0, v165
	v_mul_f32_e64 v165, |v165|, s88
	v_exp_f32_e32 v165, v165
	v_pk_mul_f32 v[156:157], v[156:157], s[28:29] op_sel_hi:[1,0]
	v_add_f32_e32 v165, 1.0, v165
	v_cmp_gt_f32_e32 vcc, s89, v165
	v_cvt_pk_bf16_f32 v154, v156, v157
	v_add_u32_e32 v156, 32, v150
	v_cndmask_b32_e64 v166, 0, 32, vcc
	v_ldexp_f32 v165, v165, v166
	v_log_f32_e32 v165, v165
	v_ashrrev_i32_e32 v157, 31, v156
	v_lshlrev_b64 v[156:157], 9, v[156:157]
	v_lshl_add_u64 v[156:157], s[24:25], 0, v[156:157]
	v_mul_f32_e32 v166, 0x3f317217, v165
	v_fma_f32 v166, v165, s90, -v166
	v_fmac_f32_e32 v166, 0x3377d1cf, v165
	v_fmac_f32_e32 v166, 0x3f317217, v165
	v_cmp_lt_f32_e64 s[6:7], |v165|, s91
	v_lshl_add_u64 v[156:157], v[156:157], 0, v[184:185]
	s_nop 0
	v_cndmask_b32_e64 v165, v165, v166, s[6:7]
	v_cndmask_b32_e32 v166, 0, v222, vcc
	v_sub_f32_e32 v166, v165, v166
	v_min_f32_e32 v165, 0, v167
	v_mul_f32_e64 v167, |v167|, s88
	v_exp_f32_e32 v167, v167
	s_nop 0
	v_add_f32_e32 v167, 1.0, v167
	v_cmp_gt_f32_e32 vcc, s89, v167
	s_nop 1
	v_cndmask_b32_e64 v168, 0, 32, vcc
	v_ldexp_f32 v167, v167, v168
	v_log_f32_e32 v167, v167
	s_nop 0
	v_mul_f32_e32 v168, 0x3f317217, v167
	v_fma_f32 v168, v167, s90, -v168
	v_fmac_f32_e32 v168, 0x3377d1cf, v167
	v_fmac_f32_e32 v168, 0x3f317217, v167
	v_cmp_lt_f32_e64 s[6:7], |v167|, s91
	s_nop 1
	v_cndmask_b32_e64 v167, v167, v168, s[6:7]
	v_cndmask_b32_e32 v168, 0, v222, vcc
	v_sub_f32_e32 v167, v167, v168
	v_pk_add_f32 v[164:165], v[164:165], v[166:167] neg_lo:[0,1] neg_hi:[0,1]
	v_fma_f32 v167, v69, v206, v133
	v_pk_mul_f32 v[164:165], v[164:165], s[28:29] op_sel_hi:[1,0]
	s_nop 0
	v_cvt_pk_bf16_f32 v155, v164, v165
	ds_write_b128 v160, v[146:149]
	ds_write_b128 v161, v[152:155]
	ds_read_b128 v[146:149], v163
	ds_read_b128 v[152:155], v163 offset:1024
	v_fma_f32 v165, v67, v206, v131
	s_waitcnt lgkmcnt(1)
	global_store_dwordx4 v[156:157], v[146:149], off
	s_nop 1
	v_add_co_u32_e32 v146, vcc, s92, v156
	v_fma_f32 v149, v79, v206, v143
	s_nop 0
	v_addc_co_u32_e32 v147, vcc, 0, v157, vcc
	s_waitcnt lgkmcnt(0)
	global_store_dwordx4 v[146:147], v[152:155], off
	v_fma_f32 v147, v78, v206, v142
	v_min_f32_e32 v146, 0, v147
	v_mul_f32_e64 v147, |v147|, s88
	v_exp_f32_e32 v147, v147
	v_fma_f32 v153, v81, v206, v145
	v_fma_f32 v155, v75, v206, v139
	v_fma_f32 v157, v77, v206, v141
	v_add_f32_e32 v147, 1.0, v147
	v_cmp_gt_f32_e32 vcc, s89, v147
	s_nop 1
	v_cndmask_b32_e64 v148, 0, 32, vcc
	v_ldexp_f32 v147, v147, v148
	v_log_f32_e32 v147, v147
	s_nop 0
	v_mul_f32_e32 v148, 0x3f317217, v147
	v_fma_f32 v148, v147, s90, -v148
	v_fmac_f32_e32 v148, 0x3377d1cf, v147
	v_fmac_f32_e32 v148, 0x3f317217, v147
	v_cmp_lt_f32_e64 s[6:7], |v147|, s91
	s_nop 1
	v_cndmask_b32_e64 v147, v147, v148, s[6:7]
	v_cndmask_b32_e32 v148, 0, v222, vcc
	v_sub_f32_e32 v148, v147, v148
	v_min_f32_e32 v147, 0, v149
	v_mul_f32_e64 v149, |v149|, s88
	v_exp_f32_e32 v149, v149
	s_nop 0
	v_add_f32_e32 v149, 1.0, v149
	v_cmp_gt_f32_e32 vcc, s89, v149
	s_nop 1
	v_cndmask_b32_e64 v152, 0, 32, vcc
	v_ldexp_f32 v149, v149, v152
	v_log_f32_e32 v149, v149
	s_nop 0
	v_mul_f32_e32 v152, 0x3f317217, v149
	v_fma_f32 v152, v149, s90, -v152
	v_fmac_f32_e32 v152, 0x3377d1cf, v149
	v_fmac_f32_e32 v152, 0x3f317217, v149
	v_cmp_lt_f32_e64 s[6:7], |v149|, s91
	s_nop 1
	v_cndmask_b32_e64 v149, v149, v152, s[6:7]
	v_cndmask_b32_e32 v152, 0, v222, vcc
	v_sub_f32_e32 v149, v149, v152
	v_pk_add_f32 v[146:147], v[146:147], v[148:149] neg_lo:[0,1] neg_hi:[0,1]
	v_fma_f32 v149, v80, v206, v144
	v_min_f32_e32 v148, 0, v149
	v_mul_f32_e64 v149, |v149|, s88
	v_exp_f32_e32 v149, v149
	v_pk_mul_f32 v[146:147], v[146:147], s[28:29] op_sel_hi:[1,0]
	v_add_f32_e32 v149, 1.0, v149
	v_cmp_gt_f32_e32 vcc, s89, v149
; __device__ __forceinline__ v4u pack8(const f32x4 a, const f32x4 b) { v4u w; w.x = pk2(a[0], a[1]); w.y = pk2(a[2], a[3]); w.z = pk2(b[0], b[1]); w.w = pk2(b[2], b[3]); return w; }
; __device__ __forceinline__ float fast_exp(float x) { return __builtin_amdgcn_exp2f(x * LOG2E); }
;     __device__ __forceinline__ void operator()(const f32x4 (&acc)[2][2][4][2], const pg8::Unit& u, int wr, int wc, int fr, int fq) const {
;     ...
;             for (int ai = 0; ai < 2; ++ai)
; #pragma unroll
;                 for (int m = 0; m < 4; ++m) {
;                     const int rowa = 256 * pm + 128 * ai + 64 * wr + 16 * m + tt.rr;
;                     const float rs = rs8[ai][m];
;                     v4u pk[2];
; #pragma unroll
;                     for (int bj = 0; bj < 2; ++bj) {
;                         f32x4 r2[2];
; #pragma unroll
;                         for (int n = 0; n < 2; ++n) {
;                             const f32x4 z = acc[ai][bj][m][n] * rs + bg[bj][n];
; #pragma unroll
;                             for (int j = 0; j < 4; ++j) { const float az = fabsf(z[j]); r2[n][j] = (fminf(z[j], 0.f) - __logf(1.0f + fast_exp(-az))) * (1.0f / 16.0f); }
;                         }
;                         pk[bj] = pack8(r2[0], r2[1]);
;                     }
;                     v4u a, b; tt.bf(pk[0], pk[1], a, b);
;                     bf16* d = (bf16*)(ws + WS_LOGA) + (size_t)rowa * 256 + 64 * wc + 8 * tt.p; *(v4u*)d = a; *(v4u*)(d + 8 * 256) = b;
	v_cvt_pk_bf16_f32 v146, v146, v147
	s_nop 0
	v_cndmask_b32_e64 v152, 0, 32, vcc
	v_ldexp_f32 v149, v149, v152
	v_log_f32_e32 v149, v149
	s_nop 0
	v_mul_f32_e32 v152, 0x3f317217, v149
	v_fma_f32 v152, v149, s90, -v152
	v_fmac_f32_e32 v152, 0x3377d1cf, v149
	v_fmac_f32_e32 v152, 0x3f317217, v149
	v_cmp_lt_f32_e64 s[6:7], |v149|, s91
	s_nop 1
	v_cndmask_b32_e64 v149, v149, v152, s[6:7]
	v_cndmask_b32_e32 v152, 0, v222, vcc
	v_sub_f32_e32 v152, v149, v152
	v_min_f32_e32 v149, 0, v153
	v_mul_f32_e64 v153, |v153|, s88
	v_exp_f32_e32 v153, v153
	s_nop 0
	v_add_f32_e32 v153, 1.0, v153
	v_cmp_gt_f32_e32 vcc, s89, v153
	s_nop 1
	v_cndmask_b32_e64 v154, 0, 32, vcc
	v_ldexp_f32 v153, v153, v154
	v_log_f32_e32 v153, v153
	s_nop 0
	v_mul_f32_e32 v154, 0x3f317217, v153
	v_fma_f32 v154, v153, s90, -v154
	v_fmac_f32_e32 v154, 0x3377d1cf, v153
	v_fmac_f32_e32 v154, 0x3f317217, v153
	v_cmp_lt_f32_e64 s[6:7], |v153|, s91
	s_nop 1
	v_cndmask_b32_e64 v153, v153, v154, s[6:7]
	v_cndmask_b32_e32 v154, 0, v222, vcc
	v_sub_f32_e32 v153, v153, v154
	v_pk_add_f32 v[148:149], v[148:149], v[152:153] neg_lo:[0,1] neg_hi:[0,1]
	v_fma_f32 v153, v74, v206, v138
	v_min_f32_e32 v152, 0, v153
	v_mul_f32_e64 v153, |v153|, s88
	v_exp_f32_e32 v153, v153
	v_pk_mul_f32 v[148:149], v[148:149], s[28:29] op_sel_hi:[1,0]
	v_add_f32_e32 v153, 1.0, v153
	v_cmp_gt_f32_e32 vcc, s89, v153
	v_cvt_pk_bf16_f32 v147, v148, v149
	s_nop 0
	v_cndmask_b32_e64 v154, 0, 32, vcc
	v_ldexp_f32 v153, v153, v154
	v_log_f32_e32 v153, v153
	s_nop 0
	v_mul_f32_e32 v154, 0x3f317217, v153
	v_fma_f32 v154, v153, s90, -v154
	v_fmac_f32_e32 v154, 0x3377d1cf, v153
	v_fmac_f32_e32 v154, 0x3f317217, v153
	v_cmp_lt_f32_e64 s[6:7], |v153|, s91
	s_nop 1
	v_cndmask_b32_e64 v153, v153, v154, s[6:7]
	v_cndmask_b32_e32 v154, 0, v222, vcc
	v_sub_f32_e32 v154, v153, v154
	v_min_f32_e32 v153, 0, v155
	v_mul_f32_e64 v155, |v155|, s88
	v_exp_f32_e32 v155, v155
	s_nop 0
	v_add_f32_e32 v155, 1.0, v155
	v_cmp_gt_f32_e32 vcc, s89, v155
	s_nop 1
	v_cndmask_b32_e64 v156, 0, 32, vcc
	v_ldexp_f32 v155, v155, v156
	v_log_f32_e32 v155, v155
	s_nop 0
	v_mul_f32_e32 v156, 0x3f317217, v155
	v_fma_f32 v156, v155, s90, -v156
	v_fmac_f32_e32 v156, 0x3377d1cf, v155
	v_fmac_f32_e32 v156, 0x3f317217, v155
	v_cmp_lt_f32_e64 s[6:7], |v155|, s91
	s_nop 1
	v_cndmask_b32_e64 v155, v155, v156, s[6:7]
	v_cndmask_b32_e32 v156, 0, v222, vcc
	v_sub_f32_e32 v155, v155, v156
	v_pk_add_f32 v[152:153], v[152:153], v[154:155] neg_lo:[0,1] neg_hi:[0,1]
	v_fma_f32 v155, v76, v206, v140
	v_min_f32_e32 v154, 0, v155
	v_mul_f32_e64 v155, |v155|, s88
	v_exp_f32_e32 v155, v155
	v_pk_mul_f32 v[152:153], v[152:153], s[28:29] op_sel_hi:[1,0]
	v_add_f32_e32 v155, 1.0, v155
	v_cmp_gt_f32_e32 vcc, s89, v155
	v_cvt_pk_bf16_f32 v148, v152, v153
	v_fma_f32 v153, v70, v206, v134
	v_cndmask_b32_e64 v156, 0, 32, vcc
	v_ldexp_f32 v155, v155, v156
	v_log_f32_e32 v155, v155
	v_min_f32_e32 v152, 0, v153
	v_mul_f32_e64 v153, |v153|, s88
	v_exp_f32_e32 v153, v153
	v_mul_f32_e32 v156, 0x3f317217, v155
	v_fma_f32 v156, v155, s90, -v156
	v_fmac_f32_e32 v156, 0x3377d1cf, v155
	v_fmac_f32_e32 v156, 0x3f317217, v155
	v_cmp_lt_f32_e64 s[6:7], |v155|, s91
	v_add_f32_e32 v153, 1.0, v153
	s_nop 0
	v_cndmask_b32_e64 v155, v155, v156, s[6:7]
	v_cndmask_b32_e32 v156, 0, v222, vcc
	v_sub_f32_e32 v156, v155, v156
	v_min_f32_e32 v155, 0, v157
	v_mul_f32_e64 v157, |v157|, s88
	v_exp_f32_e32 v157, v157
	s_nop 0
	v_add_f32_e32 v157, 1.0, v157
	v_cmp_gt_f32_e32 vcc, s89, v157
	s_nop 1
	v_cndmask_b32_e64 v164, 0, 32, vcc
	v_ldexp_f32 v157, v157, v164
	v_log_f32_e32 v157, v157
	s_nop 0
	v_mul_f32_e32 v164, 0x3f317217, v157
	v_fma_f32 v164, v157, s90, -v164
	v_fmac_f32_e32 v164, 0x3377d1cf, v157
	v_fmac_f32_e32 v164, 0x3f317217, v157
	v_cmp_lt_f32_e64 s[6:7], |v157|, s91
	s_nop 1
	v_cndmask_b32_e64 v157, v157, v164, s[6:7]
	v_cndmask_b32_e32 v164, 0, v222, vcc
	v_sub_f32_e32 v157, v157, v164
	v_pk_add_f32 v[154:155], v[154:155], v[156:157] neg_lo:[0,1] neg_hi:[0,1]
	v_cmp_gt_f32_e32 vcc, s89, v153
	v_pk_mul_f32 v[154:155], v[154:155], s[28:29] op_sel_hi:[1,0]
	v_fma_f32 v157, v73, v206, v137
	v_cvt_pk_bf16_f32 v149, v154, v155
	v_cndmask_b32_e64 v154, 0, 32, vcc
	v_ldexp_f32 v153, v153, v154
	v_log_f32_e32 v153, v153
	v_fma_f32 v155, v71, v206, v135
	v_mul_f32_e32 v154, 0x3f317217, v153
	v_fma_f32 v154, v153, s90, -v154
	v_fmac_f32_e32 v154, 0x3377d1cf, v153
	v_fmac_f32_e32 v154, 0x3f317217, v153
	v_cmp_lt_f32_e64 s[6:7], |v153|, s91
	s_nop 1
	v_cndmask_b32_e64 v153, v153, v154, s[6:7]
	v_cndmask_b32_e32 v154, 0, v222, vcc
	v_sub_f32_e32 v154, v153, v154
	v_min_f32_e32 v153, 0, v155
	v_mul_f32_e64 v155, |v155|, s88
	v_exp_f32_e32 v155, v155
	s_nop 0
	v_add_f32_e32 v155, 1.0, v155
	v_cmp_gt_f32_e32 vcc, s89, v155
	s_nop 1
	v_cndmask_b32_e64 v156, 0, 32, vcc
	v_ldexp_f32 v155, v155, v156
	v_log_f32_e32 v155, v155
	s_nop 0
	v_mul_f32_e32 v156, 0x3f317217, v155
	v_fma_f32 v156, v155, s90, -v156
	v_fmac_f32_e32 v156, 0x3377d1cf, v155
	v_fmac_f32_e32 v156, 0x3f317217, v155
	v_cmp_lt_f32_e64 s[6:7], |v155|, s91
	s_nop 1
	v_cndmask_b32_e64 v155, v155, v156, s[6:7]
	v_cndmask_b32_e32 v156, 0, v222, vcc
	v_sub_f32_e32 v155, v155, v156
	v_pk_add_f32 v[152:153], v[152:153], v[154:155] neg_lo:[0,1] neg_hi:[0,1]
	v_fma_f32 v155, v72, v206, v136
	v_min_f32_e32 v154, 0, v155
	v_mul_f32_e64 v155, |v155|, s88
	v_exp_f32_e32 v155, v155
	v_pk_mul_f32 v[152:153], v[152:153], s[28:29] op_sel_hi:[1,0]
	v_add_f32_e32 v155, 1.0, v155
	v_cmp_gt_f32_e32 vcc, s89, v155
	v_cvt_pk_bf16_f32 v152, v152, v153
	s_nop 0
	v_cndmask_b32_e64 v156, 0, 32, vcc
	v_ldexp_f32 v155, v155, v156
	v_log_f32_e32 v155, v155
	s_nop 0
; __device__ __forceinline__ v4u pack8(const f32x4 a, const f32x4 b) { v4u w; w.x = pk2(a[0], a[1]); w.y = pk2(a[2], a[3]); w.z = pk2(b[0], b[1]); w.w = pk2(b[2], b[3]); return w; }
; __device__ __forceinline__ float fast_exp(float x) { return __builtin_amdgcn_exp2f(x * LOG2E); }
;     __device__ __forceinline__ void operator()(const f32x4 (&acc)[2][2][4][2], const pg8::Unit& u, int wr, int wc, int fr, int fq) const {
;     ...
;             for (int ai = 0; ai < 2; ++ai)
; #pragma unroll
;                 for (int m = 0; m < 4; ++m) {
;                     const int rowa = 256 * pm + 128 * ai + 64 * wr + 16 * m + tt.rr;
;                     const float rs = rs8[ai][m];
;                     v4u pk[2];
; #pragma unroll
;                     for (int bj = 0; bj < 2; ++bj) {
;                         f32x4 r2[2];
; #pragma unroll
;                         for (int n = 0; n < 2; ++n) {
;                             const f32x4 z = acc[ai][bj][m][n] * rs + bg[bj][n];
; #pragma unroll
;                             for (int j = 0; j < 4; ++j) { const float az = fabsf(z[j]); r2[n][j] = (fminf(z[j], 0.f) - __logf(1.0f + fast_exp(-az))) * (1.0f / 16.0f); }
;                         }
;                         pk[bj] = pack8(r2[0], r2[1]);
;                     }
;                     v4u a, b; tt.bf(pk[0], pk[1], a, b);
;                     bf16* d = (bf16*)(ws + WS_LOGA) + (size_t)rowa * 256 + 64 * wc + 8 * tt.p; *(v4u*)d = a; *(v4u*)(d + 8 * 256) = b;
	v_mul_f32_e32 v156, 0x3f317217, v155
	v_fma_f32 v156, v155, s90, -v156
	v_fmac_f32_e32 v156, 0x3377d1cf, v155
	v_fmac_f32_e32 v156, 0x3f317217, v155
	v_cmp_lt_f32_e64 s[6:7], |v155|, s91
	s_nop 1
	v_cndmask_b32_e64 v155, v155, v156, s[6:7]
	v_cndmask_b32_e32 v156, 0, v222, vcc
	v_sub_f32_e32 v156, v155, v156
	v_min_f32_e32 v155, 0, v157
	v_mul_f32_e64 v157, |v157|, s88
	v_exp_f32_e32 v157, v157
	s_nop 0
	v_add_f32_e32 v157, 1.0, v157
	v_cmp_gt_f32_e32 vcc, s89, v157
	s_nop 1
	v_cndmask_b32_e64 v164, 0, 32, vcc
	v_ldexp_f32 v157, v157, v164
	v_log_f32_e32 v157, v157
	s_nop 0
	v_mul_f32_e32 v164, 0x3f317217, v157
	v_fma_f32 v164, v157, s90, -v164
	v_fmac_f32_e32 v164, 0x3377d1cf, v157
	v_fmac_f32_e32 v164, 0x3f317217, v157
	v_cmp_lt_f32_e64 s[6:7], |v157|, s91
	s_nop 1
	v_cndmask_b32_e64 v157, v157, v164, s[6:7]
	v_cndmask_b32_e32 v164, 0, v222, vcc
	v_sub_f32_e32 v157, v157, v164
	v_pk_add_f32 v[154:155], v[154:155], v[156:157] neg_lo:[0,1] neg_hi:[0,1]
	v_fma_f32 v157, v66, v206, v130
	v_min_f32_e32 v156, 0, v157
	v_mul_f32_e64 v157, |v157|, s88
	v_exp_f32_e32 v157, v157
	v_pk_mul_f32 v[154:155], v[154:155], s[28:29] op_sel_hi:[1,0]
	v_add_f32_e32 v157, 1.0, v157
	v_cmp_gt_f32_e32 vcc, s89, v157
	v_cvt_pk_bf16_f32 v153, v154, v155
	s_nop 0
	v_cndmask_b32_e64 v164, 0, 32, vcc
	v_ldexp_f32 v157, v157, v164
	v_log_f32_e32 v157, v157
	s_nop 0
	v_mul_f32_e32 v164, 0x3f317217, v157
	v_fma_f32 v164, v157, s90, -v164
	v_fmac_f32_e32 v164, 0x3377d1cf, v157
	v_fmac_f32_e32 v164, 0x3f317217, v157
	v_cmp_lt_f32_e64 s[6:7], |v157|, s91
	s_nop 1
	v_cndmask_b32_e64 v157, v157, v164, s[6:7]
	v_cndmask_b32_e32 v164, 0, v222, vcc
	v_sub_f32_e32 v164, v157, v164
	v_min_f32_e32 v157, 0, v165
	v_mul_f32_e64 v165, |v165|, s88
	v_exp_f32_e32 v165, v165
	s_nop 0
	v_add_f32_e32 v165, 1.0, v165
	v_cmp_gt_f32_e32 vcc, s89, v165
	s_nop 1
	v_cndmask_b32_e64 v166, 0, 32, vcc
	v_ldexp_f32 v165, v165, v166
	v_log_f32_e32 v165, v165
	s_nop 0
	v_mul_f32_e32 v166, 0x3f317217, v165
	v_fma_f32 v166, v165, s90, -v166
	v_fmac_f32_e32 v166, 0x3377d1cf, v165
	v_fmac_f32_e32 v166, 0x3f317217, v165
	v_cmp_lt_f32_e64 s[6:7], |v165|, s91
	s_nop 1
	v_cndmask_b32_e64 v165, v165, v166, s[6:7]
	v_cndmask_b32_e32 v166, 0, v222, vcc
	v_sub_f32_e32 v165, v165, v166
	v_pk_add_f32 v[156:157], v[156:157], v[164:165] neg_lo:[0,1] neg_hi:[0,1]
	v_fma_f32 v165, v68, v206, v132
	v_min_f32_e32 v164, 0, v165
	v_mul_f32_e64 v165, |v165|, s88
	v_exp_f32_e32 v165, v165
	v_pk_mul_f32 v[156:157], v[156:157], s[28:29] op_sel_hi:[1,0]
	v_add_f32_e32 v165, 1.0, v165
	v_cmp_gt_f32_e32 vcc, s89, v165
	v_cvt_pk_bf16_f32 v154, v156, v157
	v_add_u32_e32 v156, 48, v150
	v_cndmask_b32_e64 v166, 0, 32, vcc
	v_ldexp_f32 v165, v165, v166
	v_log_f32_e32 v165, v165
	v_ashrrev_i32_e32 v157, 31, v156
	v_lshlrev_b64 v[156:157], 9, v[156:157]
	v_lshl_add_u64 v[156:157], s[24:25], 0, v[156:157]
	v_mul_f32_e32 v166, 0x3f317217, v165
	v_fma_f32 v166, v165, s90, -v166
	v_fmac_f32_e32 v166, 0x3377d1cf, v165
	v_fmac_f32_e32 v166, 0x3f317217, v165
	v_cmp_lt_f32_e64 s[6:7], |v165|, s91
	v_lshl_add_u64 v[156:157], v[156:157], 0, v[184:185]
	s_nop 0
	v_cndmask_b32_e64 v165, v165, v166, s[6:7]
	v_cndmask_b32_e32 v166, 0, v222, vcc
	v_sub_f32_e32 v166, v165, v166
	v_min_f32_e32 v165, 0, v167
	v_mul_f32_e64 v167, |v167|, s88
	v_exp_f32_e32 v167, v167
	s_nop 0
	v_add_f32_e32 v167, 1.0, v167
	v_cmp_gt_f32_e32 vcc, s89, v167
	s_nop 1
	v_cndmask_b32_e64 v168, 0, 32, vcc
	v_ldexp_f32 v167, v167, v168
	v_log_f32_e32 v167, v167
	s_nop 0
	v_mul_f32_e32 v168, 0x3f317217, v167
	v_fma_f32 v168, v167, s90, -v168
	v_fmac_f32_e32 v168, 0x3377d1cf, v167
	v_fmac_f32_e32 v168, 0x3f317217, v167
	v_cmp_lt_f32_e64 s[6:7], |v167|, s91
	s_nop 1
	v_cndmask_b32_e64 v167, v167, v168, s[6:7]
	v_cndmask_b32_e32 v168, 0, v222, vcc
	v_sub_f32_e32 v167, v167, v168
	v_pk_add_f32 v[164:165], v[164:165], v[166:167] neg_lo:[0,1] neg_hi:[0,1]
	s_nop 0
	v_pk_mul_f32 v[164:165], v[164:165], s[28:29] op_sel_hi:[1,0]
	s_nop 0
	v_cvt_pk_bf16_f32 v155, v164, v165
	ds_write_b128 v160, v[146:149]
	ds_write_b128 v161, v[152:155]
	ds_read_b128 v[146:149], v163
	ds_read_b128 v[152:155], v163 offset:1024
	s_waitcnt lgkmcnt(1)
	global_store_dwordx4 v[156:157], v[146:149], off
	s_nop 1
	v_add_co_u32_e32 v146, vcc, s92, v156
	v_fma_f32 v149, v63, v204, v143
	s_nop 0
	v_addc_co_u32_e32 v147, vcc, 0, v157, vcc
	s_waitcnt lgkmcnt(0)
; __device__ __forceinline__ v4u pack8(const f32x4 a, const f32x4 b) { v4u w; w.x = pk2(a[0], a[1]); w.y = pk2(a[2], a[3]); w.z = pk2(b[0], b[1]); w.w = pk2(b[2], b[3]); return w; }
; __device__ __forceinline__ float fast_exp(float x) { return __builtin_amdgcn_exp2f(x * LOG2E); }
;     __device__ __forceinline__ void operator()(const f32x4 (&acc)[2][2][4][2], const pg8::Unit& u, int wr, int wc, int fr, int fq) const {
;     ...
;             for (int ai = 0; ai < 2; ++ai)
; #pragma unroll
;                 for (int m = 0; m < 4; ++m) {
;                     const int rowa = 256 * pm + 128 * ai + 64 * wr + 16 * m + tt.rr;
;                     const float rs = rs8[ai][m];
;                     v4u pk[2];
; #pragma unroll
;                     for (int bj = 0; bj < 2; ++bj) {
;                         f32x4 r2[2];
; #pragma unroll
;                         for (int n = 0; n < 2; ++n) {
;                             const f32x4 z = acc[ai][bj][m][n] * rs + bg[bj][n];
; #pragma unroll
;                             for (int j = 0; j < 4; ++j) { const float az = fabsf(z[j]); r2[n][j] = (fminf(z[j], 0.f) - __logf(1.0f + fast_exp(-az))) * (1.0f / 16.0f); }
;                         }
;                         pk[bj] = pack8(r2[0], r2[1]);
;                     }
;                     v4u a, b; tt.bf(pk[0], pk[1], a, b);
;                     bf16* d = (bf16*)(ws + WS_LOGA) + (size_t)rowa * 256 + 64 * wc + 8 * tt.p; *(v4u*)d = a; *(v4u*)(d + 8 * 256) = b;
	global_store_dwordx4 v[146:147], v[152:155], off
	v_fma_f32 v147, v62, v204, v142
	v_min_f32_e32 v146, 0, v147
	v_mul_f32_e64 v147, |v147|, s88
	v_exp_f32_e32 v147, v147
	v_add_u32_e32 v152, 0x80, v150
	v_add_f32_e32 v147, 1.0, v147
	v_cmp_gt_f32_e32 vcc, s89, v147
	s_nop 1
	v_cndmask_b32_e64 v148, 0, 32, vcc
	v_ldexp_f32 v147, v147, v148
	v_log_f32_e32 v147, v147
	s_nop 0
	v_mul_f32_e32 v148, 0x3f317217, v147
	v_fma_f32 v148, v147, s90, -v148
	v_fmac_f32_e32 v148, 0x3377d1cf, v147
	v_fmac_f32_e32 v148, 0x3f317217, v147
	v_cmp_lt_f32_e64 s[6:7], |v147|, s91
	s_nop 1
	v_cndmask_b32_e64 v147, v147, v148, s[6:7]
	v_cndmask_b32_e32 v148, 0, v222, vcc
	v_sub_f32_e32 v148, v147, v148
	v_min_f32_e32 v147, 0, v149
	v_mul_f32_e64 v149, |v149|, s88
	v_exp_f32_e32 v149, v149
	s_nop 0
	v_add_f32_e32 v149, 1.0, v149
	v_cmp_gt_f32_e32 vcc, s89, v149
	s_nop 1
	v_cndmask_b32_e64 v153, 0, 32, vcc
	v_ldexp_f32 v149, v149, v153
	v_log_f32_e32 v149, v149
	s_nop 0
	v_mul_f32_e32 v153, 0x3f317217, v149
	v_fma_f32 v153, v149, s90, -v153
	v_fmac_f32_e32 v153, 0x3377d1cf, v149
	v_fmac_f32_e32 v153, 0x3f317217, v149
	v_cmp_lt_f32_e64 s[6:7], |v149|, s91
	s_nop 1
	v_cndmask_b32_e64 v149, v149, v153, s[6:7]
	v_cndmask_b32_e32 v153, 0, v222, vcc
	v_sub_f32_e32 v149, v149, v153
	v_pk_add_f32 v[146:147], v[146:147], v[148:149] neg_lo:[0,1] neg_hi:[0,1]
	v_fma_f32 v149, v64, v204, v144
	v_min_f32_e32 v148, 0, v149
	v_mul_f32_e64 v149, |v149|, s88
	v_exp_f32_e32 v149, v149
	v_pk_mul_f32 v[146:147], v[146:147], s[28:29] op_sel_hi:[1,0]
	v_add_f32_e32 v149, 1.0, v149
	v_cmp_gt_f32_e32 vcc, s89, v149
	v_cvt_pk_bf16_f32 v146, v146, v147
	s_nop 0
	v_cndmask_b32_e64 v153, 0, 32, vcc
	v_ldexp_f32 v149, v149, v153
	v_log_f32_e32 v149, v149
	s_nop 0
	v_mul_f32_e32 v153, 0x3f317217, v149
	v_fma_f32 v153, v149, s90, -v153
	v_fmac_f32_e32 v153, 0x3377d1cf, v149
	v_fmac_f32_e32 v153, 0x3f317217, v149
	v_cmp_lt_f32_e64 s[6:7], |v149|, s91
	s_nop 1
	v_cndmask_b32_e64 v149, v149, v153, s[6:7]
	v_cndmask_b32_e32 v153, 0, v222, vcc
	v_sub_f32_e32 v154, v149, v153
	v_fma_f32 v153, v65, v204, v145
	v_min_f32_e32 v149, 0, v153
	v_mul_f32_e64 v153, |v153|, s88
	v_exp_f32_e32 v153, v153
	s_nop 0
	v_add_f32_e32 v153, 1.0, v153
	v_cmp_gt_f32_e32 vcc, s89, v153
	s_nop 1
	v_cndmask_b32_e64 v155, 0, 32, vcc
	v_ldexp_f32 v153, v153, v155
	v_log_f32_e32 v153, v153
	s_nop 0
	v_mul_f32_e32 v155, 0x3f317217, v153
	v_fma_f32 v155, v153, s90, -v155
	v_fmac_f32_e32 v155, 0x3377d1cf, v153
	v_fmac_f32_e32 v155, 0x3f317217, v153
	v_cmp_lt_f32_e64 s[6:7], |v153|, s91
	s_nop 1
	v_cndmask_b32_e64 v153, v153, v155, s[6:7]
	v_cndmask_b32_e32 v155, 0, v222, vcc
	v_sub_f32_e32 v155, v153, v155
	v_fma_f32 v153, v58, v204, v138
	v_pk_add_f32 v[148:149], v[148:149], v[154:155] neg_lo:[0,1] neg_hi:[0,1]
	v_min_f32_e32 v154, 0, v153
	v_mul_f32_e64 v153, |v153|, s88
	v_exp_f32_e32 v153, v153
	v_pk_mul_f32 v[148:149], v[148:149], s[28:29] op_sel_hi:[1,0]
	v_add_f32_e32 v153, 1.0, v153
	v_cmp_gt_f32_e32 vcc, s89, v153
	v_cvt_pk_bf16_f32 v147, v148, v149
	s_nop 0
	v_cndmask_b32_e64 v155, 0, 32, vcc
	v_ldexp_f32 v153, v153, v155
	v_log_f32_e32 v153, v153
	s_nop 0
	v_mul_f32_e32 v155, 0x3f317217, v153
	v_fma_f32 v155, v153, s90, -v155
	v_fmac_f32_e32 v155, 0x3377d1cf, v153
	v_fmac_f32_e32 v155, 0x3f317217, v153
	v_cmp_lt_f32_e64 s[6:7], |v153|, s91
	s_nop 1
	v_cndmask_b32_e64 v153, v153, v155, s[6:7]
	v_cndmask_b32_e32 v155, 0, v222, vcc
	v_sub_f32_e32 v156, v153, v155
	v_fma_f32 v153, v59, v204, v139
	v_min_f32_e32 v155, 0, v153
	v_mul_f32_e64 v153, |v153|, s88
	v_exp_f32_e32 v153, v153
	s_nop 0
	v_add_f32_e32 v153, 1.0, v153
	v_cmp_gt_f32_e32 vcc, s89, v153
	s_nop 1
	v_cndmask_b32_e64 v157, 0, 32, vcc
	v_ldexp_f32 v153, v153, v157
	v_log_f32_e32 v153, v153
	s_nop 0
	v_mul_f32_e32 v157, 0x3f317217, v153
	v_fma_f32 v157, v153, s90, -v157
	v_fmac_f32_e32 v157, 0x3377d1cf, v153
	v_fmac_f32_e32 v157, 0x3f317217, v153
	v_cmp_lt_f32_e64 s[6:7], |v153|, s91
	s_nop 1
	v_cndmask_b32_e64 v153, v153, v157, s[6:7]
	v_cndmask_b32_e32 v157, 0, v222, vcc
	v_sub_f32_e32 v157, v153, v157
	v_fma_f32 v153, v60, v204, v140
	v_pk_add_f32 v[154:155], v[154:155], v[156:157] neg_lo:[0,1] neg_hi:[0,1]
	v_min_f32_e32 v156, 0, v153
	v_mul_f32_e64 v153, |v153|, s88
	v_exp_f32_e32 v153, v153
	v_pk_mul_f32 v[154:155], v[154:155], s[28:29] op_sel_hi:[1,0]
	v_add_f32_e32 v153, 1.0, v153
	v_cmp_gt_f32_e32 vcc, s89, v153
	v_cvt_pk_bf16_f32 v148, v154, v155
	s_nop 0
	v_cndmask_b32_e64 v157, 0, 32, vcc
	v_ldexp_f32 v153, v153, v157
	v_log_f32_e32 v153, v153
	s_nop 0
	v_mul_f32_e32 v157, 0x3f317217, v153
	v_fma_f32 v157, v153, s90, -v157
	v_fmac_f32_e32 v157, 0x3377d1cf, v153
	v_fmac_f32_e32 v157, 0x3f317217, v153
	v_cmp_lt_f32_e64 s[6:7], |v153|, s91
	s_nop 1
	v_cndmask_b32_e64 v153, v153, v157, s[6:7]
	v_cndmask_b32_e32 v157, 0, v222, vcc
	v_sub_f32_e32 v164, v153, v157
	v_fma_f32 v153, v61, v204, v141
	v_min_f32_e32 v157, 0, v153
	v_mul_f32_e64 v153, |v153|, s88
	v_exp_f32_e32 v153, v153
	s_nop 0
	v_add_f32_e32 v153, 1.0, v153
	v_cmp_gt_f32_e32 vcc, s89, v153
	s_nop 1
	v_cndmask_b32_e64 v165, 0, 32, vcc
	v_ldexp_f32 v153, v153, v165
	v_log_f32_e32 v153, v153
	s_nop 0
	v_mul_f32_e32 v165, 0x3f317217, v153
	v_fma_f32 v165, v153, s90, -v165
	v_fmac_f32_e32 v165, 0x3377d1cf, v153
	v_fmac_f32_e32 v165, 0x3f317217, v153
	v_cmp_lt_f32_e64 s[6:7], |v153|, s91
	s_nop 1
	v_cndmask_b32_e64 v153, v153, v165, s[6:7]
	v_cndmask_b32_e32 v165, 0, v222, vcc
	v_sub_f32_e32 v165, v153, v165
	v_fma_f32 v153, v54, v204, v134
	v_min_f32_e32 v154, 0, v153
	v_mul_f32_e64 v153, |v153|, s88
	v_exp_f32_e32 v153, v153
	v_pk_add_f32 v[156:157], v[156:157], v[164:165] neg_lo:[0,1] neg_hi:[0,1]
; __device__ __forceinline__ v4u pack8(const f32x4 a, const f32x4 b) { v4u w; w.x = pk2(a[0], a[1]); w.y = pk2(a[2], a[3]); w.z = pk2(b[0], b[1]); w.w = pk2(b[2], b[3]); return w; }
; __device__ __forceinline__ float fast_exp(float x) { return __builtin_amdgcn_exp2f(x * LOG2E); }
;     __device__ __forceinline__ void operator()(const f32x4 (&acc)[2][2][4][2], const pg8::Unit& u, int wr, int wc, int fr, int fq) const {
;     ...
; #pragma unroll
;             for (int ai = 0; ai < 2; ++ai)
; #pragma unroll
;                 for (int m = 0; m < 4; ++m) {
;                     const int rowa = 256 * pm + 128 * ai + 64 * wr + 16 * m + tt.rr;
;                     const float rs = rs8[ai][m];
;                     v4u pk[2];
; #pragma unroll
;                     for (int bj = 0; bj < 2; ++bj) {
;                         f32x4 r2[2];
; #pragma unroll
;                         for (int n = 0; n < 2; ++n) {
;                             const f32x4 z = acc[ai][bj][m][n] * rs + bg[bj][n];
; #pragma unroll
;                             for (int j = 0; j < 4; ++j) { const float az = fabsf(z[j]); r2[n][j] = (fminf(z[j], 0.f) - __logf(1.0f + fast_exp(-az))) * (1.0f / 16.0f); }
;                         }
;                         pk[bj] = pack8(r2[0], r2[1]);
;                     }
;                     v4u a, b; tt.bf(pk[0], pk[1], a, b);
;                     bf16* d = (bf16*)(ws + WS_LOGA) + (size_t)rowa * 256 + 64 * wc + 8 * tt.p; *(v4u*)d = a; *(v4u*)(d + 8 * 256) = b;
	v_add_f32_e32 v153, 1.0, v153
	v_cmp_gt_f32_e32 vcc, s89, v153
	v_pk_mul_f32 v[156:157], v[156:157], s[28:29] op_sel_hi:[1,0]
	s_nop 0
	v_cndmask_b32_e64 v155, 0, 32, vcc
	v_ldexp_f32 v153, v153, v155
	v_log_f32_e32 v153, v153
	v_cvt_pk_bf16_f32 v149, v156, v157
	v_mul_f32_e32 v155, 0x3f317217, v153
	v_fma_f32 v155, v153, s90, -v155
	v_fmac_f32_e32 v155, 0x3377d1cf, v153
	v_fmac_f32_e32 v155, 0x3f317217, v153
	v_cmp_lt_f32_e64 s[6:7], |v153|, s91
	s_nop 1
	v_cndmask_b32_e64 v153, v153, v155, s[6:7]
	v_cndmask_b32_e32 v155, 0, v222, vcc
	v_sub_f32_e32 v156, v153, v155
	v_fma_f32 v153, v55, v204, v135
	v_min_f32_e32 v155, 0, v153
	v_mul_f32_e64 v153, |v153|, s88
	v_exp_f32_e32 v153, v153
	s_nop 0
	v_add_f32_e32 v153, 1.0, v153
	v_cmp_gt_f32_e32 vcc, s89, v153
	s_nop 1
	v_cndmask_b32_e64 v157, 0, 32, vcc
	v_ldexp_f32 v153, v153, v157
	v_log_f32_e32 v153, v153
	s_nop 0
	v_mul_f32_e32 v157, 0x3f317217, v153
	v_fma_f32 v157, v153, s90, -v157
	v_fmac_f32_e32 v157, 0x3377d1cf, v153
	v_fmac_f32_e32 v157, 0x3f317217, v153
	v_cmp_lt_f32_e64 s[6:7], |v153|, s91
	s_nop 1
	v_cndmask_b32_e64 v153, v153, v157, s[6:7]
	v_cndmask_b32_e32 v157, 0, v222, vcc
	v_sub_f32_e32 v157, v153, v157
	v_fma_f32 v153, v56, v204, v136
	v_pk_add_f32 v[154:155], v[154:155], v[156:157] neg_lo:[0,1] neg_hi:[0,1]
	v_min_f32_e32 v156, 0, v153
	v_mul_f32_e64 v153, |v153|, s88
	v_exp_f32_e32 v153, v153
	v_pk_mul_f32 v[154:155], v[154:155], s[28:29] op_sel_hi:[1,0]
	v_add_f32_e32 v153, 1.0, v153
	v_cmp_gt_f32_e32 vcc, s89, v153
	v_cvt_pk_bf16_f32 v154, v154, v155
	s_nop 0
	v_cndmask_b32_e64 v157, 0, 32, vcc
	v_ldexp_f32 v153, v153, v157
	v_log_f32_e32 v153, v153
	s_nop 0
	v_mul_f32_e32 v157, 0x3f317217, v153
	v_fma_f32 v157, v153, s90, -v157
	v_fmac_f32_e32 v157, 0x3377d1cf, v153
	v_fmac_f32_e32 v157, 0x3f317217, v153
	v_cmp_lt_f32_e64 s[6:7], |v153|, s91
	s_nop 1
	v_cndmask_b32_e64 v153, v153, v157, s[6:7]
	v_cndmask_b32_e32 v157, 0, v222, vcc
	v_sub_f32_e32 v164, v153, v157
	v_fma_f32 v153, v57, v204, v137
	v_min_f32_e32 v157, 0, v153
	v_mul_f32_e64 v153, |v153|, s88
	v_exp_f32_e32 v153, v153
	s_nop 0
	v_add_f32_e32 v153, 1.0, v153
	v_cmp_gt_f32_e32 vcc, s89, v153
	s_nop 1
	v_cndmask_b32_e64 v165, 0, 32, vcc
	v_ldexp_f32 v153, v153, v165
	v_log_f32_e32 v153, v153
	s_nop 0
	v_mul_f32_e32 v165, 0x3f317217, v153
	v_fma_f32 v165, v153, s90, -v165
	v_fmac_f32_e32 v165, 0x3377d1cf, v153
	v_fmac_f32_e32 v165, 0x3f317217, v153
	v_cmp_lt_f32_e64 s[6:7], |v153|, s91
	s_nop 1
	v_cndmask_b32_e64 v153, v153, v165, s[6:7]
	v_cndmask_b32_e32 v165, 0, v222, vcc
	v_sub_f32_e32 v165, v153, v165
	v_fma_f32 v153, v50, v204, v130
	v_pk_add_f32 v[156:157], v[156:157], v[164:165] neg_lo:[0,1] neg_hi:[0,1]
	v_min_f32_e32 v164, 0, v153
	v_mul_f32_e64 v153, |v153|, s88
	v_exp_f32_e32 v153, v153
	v_pk_mul_f32 v[156:157], v[156:157], s[28:29] op_sel_hi:[1,0]
	v_add_f32_e32 v153, 1.0, v153
	v_cmp_gt_f32_e32 vcc, s89, v153
	v_cvt_pk_bf16_f32 v155, v156, v157
	s_nop 0
	v_cndmask_b32_e64 v165, 0, 32, vcc
	v_ldexp_f32 v153, v153, v165
	v_log_f32_e32 v153, v153
	s_nop 0
	v_mul_f32_e32 v165, 0x3f317217, v153
	v_fma_f32 v165, v153, s90, -v165
	v_fmac_f32_e32 v165, 0x3377d1cf, v153
	v_fmac_f32_e32 v165, 0x3f317217, v153
	v_cmp_lt_f32_e64 s[6:7], |v153|, s91
	s_nop 1
	v_cndmask_b32_e64 v153, v153, v165, s[6:7]
	v_cndmask_b32_e32 v165, 0, v222, vcc
	v_sub_f32_e32 v166, v153, v165
	v_fma_f32 v153, v51, v204, v131
	v_min_f32_e32 v165, 0, v153
	v_mul_f32_e64 v153, |v153|, s88
	v_exp_f32_e32 v153, v153
	s_nop 0
	v_add_f32_e32 v153, 1.0, v153
	v_cmp_gt_f32_e32 vcc, s89, v153
	s_nop 1
	v_cndmask_b32_e64 v167, 0, 32, vcc
	v_ldexp_f32 v153, v153, v167
	v_log_f32_e32 v153, v153
	s_nop 0
	v_mul_f32_e32 v167, 0x3f317217, v153
	v_fma_f32 v167, v153, s90, -v167
	v_fmac_f32_e32 v167, 0x3377d1cf, v153
	v_fmac_f32_e32 v167, 0x3f317217, v153
	v_cmp_lt_f32_e64 s[6:7], |v153|, s91
	s_nop 1
	v_cndmask_b32_e64 v153, v153, v167, s[6:7]
	v_cndmask_b32_e32 v167, 0, v222, vcc
	v_sub_f32_e32 v167, v153, v167
	v_fma_f32 v153, v52, v204, v132
	v_pk_add_f32 v[164:165], v[164:165], v[166:167] neg_lo:[0,1] neg_hi:[0,1]
	v_min_f32_e32 v166, 0, v153
	v_mul_f32_e64 v153, |v153|, s88
	v_exp_f32_e32 v153, v153
	v_pk_mul_f32 v[164:165], v[164:165], s[28:29] op_sel_hi:[1,0]
	v_add_f32_e32 v153, 1.0, v153
	v_cmp_gt_f32_e32 vcc, s89, v153
	v_cvt_pk_bf16_f32 v156, v164, v165
	v_fma_f32 v165, v35, v202, v131
	v_cndmask_b32_e64 v167, 0, 32, vcc
	v_ldexp_f32 v153, v153, v167
	v_log_f32_e32 v153, v153
	s_nop 0
	v_mul_f32_e32 v167, 0x3f317217, v153
	v_fma_f32 v167, v153, s90, -v167
	v_fmac_f32_e32 v167, 0x3377d1cf, v153
	v_fmac_f32_e32 v167, 0x3f317217, v153
	v_cmp_lt_f32_e64 s[6:7], |v153|, s91
	s_nop 1
	v_cndmask_b32_e64 v153, v153, v167, s[6:7]
	v_cndmask_b32_e32 v167, 0, v222, vcc
	v_sub_f32_e32 v168, v153, v167
	v_fma_f32 v153, v53, v204, v133
	v_min_f32_e32 v167, 0, v153
	v_mul_f32_e64 v153, |v153|, s88
	v_exp_f32_e32 v153, v153
	s_nop 0
	v_add_f32_e32 v153, 1.0, v153
	v_cmp_gt_f32_e32 vcc, s89, v153
	s_nop 1
	v_cndmask_b32_e64 v169, 0, 32, vcc
	v_ldexp_f32 v153, v153, v169
	v_log_f32_e32 v153, v153
	s_nop 0
	v_mul_f32_e32 v169, 0x3f317217, v153
	v_fma_f32 v169, v153, s90, -v169
	v_fmac_f32_e32 v169, 0x3377d1cf, v153
	v_fmac_f32_e32 v169, 0x3f317217, v153
	v_cmp_lt_f32_e64 s[6:7], |v153|, s91
	s_nop 1
	v_cndmask_b32_e64 v153, v153, v169, s[6:7]
	v_cndmask_b32_e32 v169, 0, v222, vcc
	v_sub_f32_e32 v169, v153, v169
	v_pk_add_f32 v[166:167], v[166:167], v[168:169] neg_lo:[0,1] neg_hi:[0,1]
	v_ashrrev_i32_e32 v153, 31, v152
	v_pk_mul_f32 v[166:167], v[166:167], s[28:29] op_sel_hi:[1,0]
	v_lshlrev_b64 v[152:153], 9, v[152:153]
	v_cvt_pk_bf16_f32 v157, v166, v167
	ds_write_b128 v160, v[146:149]
	ds_write_b128 v161, v[154:157]
	ds_read_b128 v[146:149], v163
	ds_read_b128 v[154:157], v163 offset:1024
	v_lshl_add_u64 v[152:153], s[24:25], 0, v[152:153]
	v_lshl_add_u64 v[152:153], v[152:153], 0, v[184:185]
	v_fma_f32 v167, v37, v202, v133
	s_waitcnt lgkmcnt(1)
; __device__ __forceinline__ v4u pack8(const f32x4 a, const f32x4 b) { v4u w; w.x = pk2(a[0], a[1]); w.y = pk2(a[2], a[3]); w.z = pk2(b[0], b[1]); w.w = pk2(b[2], b[3]); return w; }
; __device__ __forceinline__ float fast_exp(float x) { return __builtin_amdgcn_exp2f(x * LOG2E); }
;     __device__ __forceinline__ void operator()(const f32x4 (&acc)[2][2][4][2], const pg8::Unit& u, int wr, int wc, int fr, int fq) const {
;     ...
; #pragma unroll
;             for (int ai = 0; ai < 2; ++ai)
; #pragma unroll
;                 for (int m = 0; m < 4; ++m) {
;                     const int rowa = 256 * pm + 128 * ai + 64 * wr + 16 * m + tt.rr;
;                     const float rs = rs8[ai][m];
;                     v4u pk[2];
; #pragma unroll
;                     for (int bj = 0; bj < 2; ++bj) {
;                         f32x4 r2[2];
; #pragma unroll
;                         for (int n = 0; n < 2; ++n) {
;                             const f32x4 z = acc[ai][bj][m][n] * rs + bg[bj][n];
; #pragma unroll
;                             for (int j = 0; j < 4; ++j) { const float az = fabsf(z[j]); r2[n][j] = (fminf(z[j], 0.f) - __logf(1.0f + fast_exp(-az))) * (1.0f / 16.0f); }
;                         }
;                         pk[bj] = pack8(r2[0], r2[1]);
;                     }
;                     v4u a, b; tt.bf(pk[0], pk[1], a, b);
;                     bf16* d = (bf16*)(ws + WS_LOGA) + (size_t)rowa * 256 + 64 * wc + 8 * tt.p; *(v4u*)d = a; *(v4u*)(d + 8 * 256) = b;
	global_store_dwordx4 v[152:153], v[146:149], off
	s_nop 1
	v_add_co_u32_e32 v146, vcc, s92, v152
	v_fma_f32 v149, v47, v202, v143
	s_nop 0
	v_addc_co_u32_e32 v147, vcc, 0, v153, vcc
	s_waitcnt lgkmcnt(0)
	global_store_dwordx4 v[146:147], v[154:157], off
	v_fma_f32 v147, v46, v202, v142
	v_min_f32_e32 v146, 0, v147
	v_mul_f32_e64 v147, |v147|, s88
	v_exp_f32_e32 v147, v147
	v_fma_f32 v153, v49, v202, v145
	v_fma_f32 v155, v43, v202, v139
	v_fma_f32 v157, v45, v202, v141
	v_add_f32_e32 v147, 1.0, v147
	v_cmp_gt_f32_e32 vcc, s89, v147
	s_nop 1
	v_cndmask_b32_e64 v148, 0, 32, vcc
	v_ldexp_f32 v147, v147, v148
	v_log_f32_e32 v147, v147
	s_nop 0
	v_mul_f32_e32 v148, 0x3f317217, v147
	v_fma_f32 v148, v147, s90, -v148
	v_fmac_f32_e32 v148, 0x3377d1cf, v147
	v_fmac_f32_e32 v148, 0x3f317217, v147
	v_cmp_lt_f32_e64 s[6:7], |v147|, s91
	s_nop 1
	v_cndmask_b32_e64 v147, v147, v148, s[6:7]
	v_cndmask_b32_e32 v148, 0, v222, vcc
	v_sub_f32_e32 v148, v147, v148
	v_min_f32_e32 v147, 0, v149
	v_mul_f32_e64 v149, |v149|, s88
	v_exp_f32_e32 v149, v149
	s_nop 0
	v_add_f32_e32 v149, 1.0, v149
	v_cmp_gt_f32_e32 vcc, s89, v149
	s_nop 1
	v_cndmask_b32_e64 v152, 0, 32, vcc
	v_ldexp_f32 v149, v149, v152
	v_log_f32_e32 v149, v149
	s_nop 0
	v_mul_f32_e32 v152, 0x3f317217, v149
	v_fma_f32 v152, v149, s90, -v152
	v_fmac_f32_e32 v152, 0x3377d1cf, v149
	v_fmac_f32_e32 v152, 0x3f317217, v149
	v_cmp_lt_f32_e64 s[6:7], |v149|, s91
	s_nop 1
	v_cndmask_b32_e64 v149, v149, v152, s[6:7]
	v_cndmask_b32_e32 v152, 0, v222, vcc
	v_sub_f32_e32 v149, v149, v152
	v_pk_add_f32 v[146:147], v[146:147], v[148:149] neg_lo:[0,1] neg_hi:[0,1]
	v_fma_f32 v149, v48, v202, v144
	v_min_f32_e32 v148, 0, v149
	v_mul_f32_e64 v149, |v149|, s88
	v_exp_f32_e32 v149, v149
	v_pk_mul_f32 v[146:147], v[146:147], s[28:29] op_sel_hi:[1,0]
	v_add_f32_e32 v149, 1.0, v149
	v_cmp_gt_f32_e32 vcc, s89, v149
	v_cvt_pk_bf16_f32 v146, v146, v147
	s_nop 0
	v_cndmask_b32_e64 v152, 0, 32, vcc
	v_ldexp_f32 v149, v149, v152
	v_log_f32_e32 v149, v149
	s_nop 0
	v_mul_f32_e32 v152, 0x3f317217, v149
	v_fma_f32 v152, v149, s90, -v152
	v_fmac_f32_e32 v152, 0x3377d1cf, v149
	v_fmac_f32_e32 v152, 0x3f317217, v149
	v_cmp_lt_f32_e64 s[6:7], |v149|, s91
	s_nop 1
	v_cndmask_b32_e64 v149, v149, v152, s[6:7]
	v_cndmask_b32_e32 v152, 0, v222, vcc
	v_sub_f32_e32 v152, v149, v152
	v_min_f32_e32 v149, 0, v153
	v_mul_f32_e64 v153, |v153|, s88
	v_exp_f32_e32 v153, v153
	s_nop 0
	v_add_f32_e32 v153, 1.0, v153
	v_cmp_gt_f32_e32 vcc, s89, v153
	s_nop 1
	v_cndmask_b32_e64 v154, 0, 32, vcc
	v_ldexp_f32 v153, v153, v154
	v_log_f32_e32 v153, v153
	s_nop 0
	v_mul_f32_e32 v154, 0x3f317217, v153
	v_fma_f32 v154, v153, s90, -v154
	v_fmac_f32_e32 v154, 0x3377d1cf, v153
	v_fmac_f32_e32 v154, 0x3f317217, v153
	v_cmp_lt_f32_e64 s[6:7], |v153|, s91
	s_nop 1
	v_cndmask_b32_e64 v153, v153, v154, s[6:7]
	v_cndmask_b32_e32 v154, 0, v222, vcc
	v_sub_f32_e32 v153, v153, v154
	v_pk_add_f32 v[148:149], v[148:149], v[152:153] neg_lo:[0,1] neg_hi:[0,1]
	v_fma_f32 v153, v42, v202, v138
	v_min_f32_e32 v152, 0, v153
	v_mul_f32_e64 v153, |v153|, s88
	v_exp_f32_e32 v153, v153
	v_pk_mul_f32 v[148:149], v[148:149], s[28:29] op_sel_hi:[1,0]
	v_add_f32_e32 v153, 1.0, v153
	v_cmp_gt_f32_e32 vcc, s89, v153
	v_cvt_pk_bf16_f32 v147, v148, v149
	s_nop 0
	v_cndmask_b32_e64 v154, 0, 32, vcc
	v_ldexp_f32 v153, v153, v154
	v_log_f32_e32 v153, v153
	s_nop 0
	v_mul_f32_e32 v154, 0x3f317217, v153
	v_fma_f32 v154, v153, s90, -v154
	v_fmac_f32_e32 v154, 0x3377d1cf, v153
	v_fmac_f32_e32 v154, 0x3f317217, v153
	v_cmp_lt_f32_e64 s[6:7], |v153|, s91
	s_nop 1
	v_cndmask_b32_e64 v153, v153, v154, s[6:7]
	v_cndmask_b32_e32 v154, 0, v222, vcc
	v_sub_f32_e32 v154, v153, v154
	v_min_f32_e32 v153, 0, v155
	v_mul_f32_e64 v155, |v155|, s88
	v_exp_f32_e32 v155, v155
	s_nop 0
	v_add_f32_e32 v155, 1.0, v155
	v_cmp_gt_f32_e32 vcc, s89, v155
	s_nop 1
	v_cndmask_b32_e64 v156, 0, 32, vcc
	v_ldexp_f32 v155, v155, v156
	v_log_f32_e32 v155, v155
	s_nop 0
	v_mul_f32_e32 v156, 0x3f317217, v155
	v_fma_f32 v156, v155, s90, -v156
	v_fmac_f32_e32 v156, 0x3377d1cf, v155
	v_fmac_f32_e32 v156, 0x3f317217, v155
	v_cmp_lt_f32_e64 s[6:7], |v155|, s91
	s_nop 1
	v_cndmask_b32_e64 v155, v155, v156, s[6:7]
	v_cndmask_b32_e32 v156, 0, v222, vcc
	v_sub_f32_e32 v155, v155, v156
	v_pk_add_f32 v[152:153], v[152:153], v[154:155] neg_lo:[0,1] neg_hi:[0,1]
	v_fma_f32 v155, v44, v202, v140
	v_min_f32_e32 v154, 0, v155
	v_mul_f32_e64 v155, |v155|, s88
	v_exp_f32_e32 v155, v155
	v_pk_mul_f32 v[152:153], v[152:153], s[28:29] op_sel_hi:[1,0]
	v_add_f32_e32 v155, 1.0, v155
	v_cmp_gt_f32_e32 vcc, s89, v155
	v_cvt_pk_bf16_f32 v148, v152, v153
	v_fma_f32 v153, v38, v202, v134
	v_cndmask_b32_e64 v156, 0, 32, vcc
	v_ldexp_f32 v155, v155, v156
	v_log_f32_e32 v155, v155
	v_min_f32_e32 v152, 0, v153
	v_mul_f32_e64 v153, |v153|, s88
	v_exp_f32_e32 v153, v153
	v_mul_f32_e32 v156, 0x3f317217, v155
	v_fma_f32 v156, v155, s90, -v156
	v_fmac_f32_e32 v156, 0x3377d1cf, v155
	v_fmac_f32_e32 v156, 0x3f317217, v155
	v_cmp_lt_f32_e64 s[6:7], |v155|, s91
	v_add_f32_e32 v153, 1.0, v153
	s_nop 0
	v_cndmask_b32_e64 v155, v155, v156, s[6:7]
	v_cndmask_b32_e32 v156, 0, v222, vcc
	v_sub_f32_e32 v156, v155, v156
	v_min_f32_e32 v155, 0, v157
	v_mul_f32_e64 v157, |v157|, s88
	v_exp_f32_e32 v157, v157
	s_nop 0
	v_add_f32_e32 v157, 1.0, v157
	v_cmp_gt_f32_e32 vcc, s89, v157
	s_nop 1
	v_cndmask_b32_e64 v164, 0, 32, vcc
	v_ldexp_f32 v157, v157, v164
	v_log_f32_e32 v157, v157
	s_nop 0
	v_mul_f32_e32 v164, 0x3f317217, v157
	v_fma_f32 v164, v157, s90, -v164
	v_fmac_f32_e32 v164, 0x3377d1cf, v157
	v_fmac_f32_e32 v164, 0x3f317217, v157
	v_cmp_lt_f32_e64 s[6:7], |v157|, s91
; __device__ __forceinline__ v4u pack8(const f32x4 a, const f32x4 b) { v4u w; w.x = pk2(a[0], a[1]); w.y = pk2(a[2], a[3]); w.z = pk2(b[0], b[1]); w.w = pk2(b[2], b[3]); return w; }
; __device__ __forceinline__ float fast_exp(float x) { return __builtin_amdgcn_exp2f(x * LOG2E); }
;     __device__ __forceinline__ void operator()(const f32x4 (&acc)[2][2][4][2], const pg8::Unit& u, int wr, int wc, int fr, int fq) const {
;     ...
; #pragma unroll
;             for (int ai = 0; ai < 2; ++ai)
; #pragma unroll
;                 for (int m = 0; m < 4; ++m) {
;                     const int rowa = 256 * pm + 128 * ai + 64 * wr + 16 * m + tt.rr;
;                     const float rs = rs8[ai][m];
;                     v4u pk[2];
; #pragma unroll
;                     for (int bj = 0; bj < 2; ++bj) {
;                         f32x4 r2[2];
; #pragma unroll
;                         for (int n = 0; n < 2; ++n) {
;                             const f32x4 z = acc[ai][bj][m][n] * rs + bg[bj][n];
; #pragma unroll
;                             for (int j = 0; j < 4; ++j) { const float az = fabsf(z[j]); r2[n][j] = (fminf(z[j], 0.f) - __logf(1.0f + fast_exp(-az))) * (1.0f / 16.0f); }
;                         }
;                         pk[bj] = pack8(r2[0], r2[1]);
;                     }
;                     v4u a, b; tt.bf(pk[0], pk[1], a, b);
;                     bf16* d = (bf16*)(ws + WS_LOGA) + (size_t)rowa * 256 + 64 * wc + 8 * tt.p; *(v4u*)d = a; *(v4u*)(d + 8 * 256) = b;
	s_nop 1
	v_cndmask_b32_e64 v157, v157, v164, s[6:7]
	v_cndmask_b32_e32 v164, 0, v222, vcc
	v_sub_f32_e32 v157, v157, v164
	v_pk_add_f32 v[154:155], v[154:155], v[156:157] neg_lo:[0,1] neg_hi:[0,1]
	v_cmp_gt_f32_e32 vcc, s89, v153
	v_pk_mul_f32 v[154:155], v[154:155], s[28:29] op_sel_hi:[1,0]
	v_fma_f32 v157, v41, v202, v137
	v_cvt_pk_bf16_f32 v149, v154, v155
	v_cndmask_b32_e64 v154, 0, 32, vcc
	v_ldexp_f32 v153, v153, v154
	v_log_f32_e32 v153, v153
	v_fma_f32 v155, v39, v202, v135
	v_mul_f32_e32 v154, 0x3f317217, v153
	v_fma_f32 v154, v153, s90, -v154
	v_fmac_f32_e32 v154, 0x3377d1cf, v153
	v_fmac_f32_e32 v154, 0x3f317217, v153
	v_cmp_lt_f32_e64 s[6:7], |v153|, s91
	s_nop 1
	v_cndmask_b32_e64 v153, v153, v154, s[6:7]
	v_cndmask_b32_e32 v154, 0, v222, vcc
	v_sub_f32_e32 v154, v153, v154
	v_min_f32_e32 v153, 0, v155
	v_mul_f32_e64 v155, |v155|, s88
	v_exp_f32_e32 v155, v155
	s_nop 0
	v_add_f32_e32 v155, 1.0, v155
	v_cmp_gt_f32_e32 vcc, s89, v155
	s_nop 1
	v_cndmask_b32_e64 v156, 0, 32, vcc
	v_ldexp_f32 v155, v155, v156
	v_log_f32_e32 v155, v155
	s_nop 0
	v_mul_f32_e32 v156, 0x3f317217, v155
	v_fma_f32 v156, v155, s90, -v156
	v_fmac_f32_e32 v156, 0x3377d1cf, v155
	v_fmac_f32_e32 v156, 0x3f317217, v155
	v_cmp_lt_f32_e64 s[6:7], |v155|, s91
	s_nop 1
	v_cndmask_b32_e64 v155, v155, v156, s[6:7]
	v_cndmask_b32_e32 v156, 0, v222, vcc
	v_sub_f32_e32 v155, v155, v156
	v_pk_add_f32 v[152:153], v[152:153], v[154:155] neg_lo:[0,1] neg_hi:[0,1]
	v_fma_f32 v155, v40, v202, v136
	v_min_f32_e32 v154, 0, v155
	v_mul_f32_e64 v155, |v155|, s88
	v_exp_f32_e32 v155, v155
	v_pk_mul_f32 v[152:153], v[152:153], s[28:29] op_sel_hi:[1,0]
	v_add_f32_e32 v155, 1.0, v155
	v_cmp_gt_f32_e32 vcc, s89, v155
	v_cvt_pk_bf16_f32 v152, v152, v153
	s_nop 0
	v_cndmask_b32_e64 v156, 0, 32, vcc
	v_ldexp_f32 v155, v155, v156
	v_log_f32_e32 v155, v155
	s_nop 0
	v_mul_f32_e32 v156, 0x3f317217, v155
	v_fma_f32 v156, v155, s90, -v156
	v_fmac_f32_e32 v156, 0x3377d1cf, v155
	v_fmac_f32_e32 v156, 0x3f317217, v155
	v_cmp_lt_f32_e64 s[6:7], |v155|, s91
	s_nop 1
	v_cndmask_b32_e64 v155, v155, v156, s[6:7]
	v_cndmask_b32_e32 v156, 0, v222, vcc
	v_sub_f32_e32 v156, v155, v156
	v_min_f32_e32 v155, 0, v157
	v_mul_f32_e64 v157, |v157|, s88
	v_exp_f32_e32 v157, v157
	s_nop 0
	v_add_f32_e32 v157, 1.0, v157
	v_cmp_gt_f32_e32 vcc, s89, v157
	s_nop 1
	v_cndmask_b32_e64 v164, 0, 32, vcc
	v_ldexp_f32 v157, v157, v164
	v_log_f32_e32 v157, v157
	s_nop 0
	v_mul_f32_e32 v164, 0x3f317217, v157
	v_fma_f32 v164, v157, s90, -v164
	v_fmac_f32_e32 v164, 0x3377d1cf, v157
	v_fmac_f32_e32 v164, 0x3f317217, v157
	v_cmp_lt_f32_e64 s[6:7], |v157|, s91
	s_nop 1
	v_cndmask_b32_e64 v157, v157, v164, s[6:7]
	v_cndmask_b32_e32 v164, 0, v222, vcc
	v_sub_f32_e32 v157, v157, v164
	v_pk_add_f32 v[154:155], v[154:155], v[156:157] neg_lo:[0,1] neg_hi:[0,1]
	v_fma_f32 v157, v34, v202, v130
	v_min_f32_e32 v156, 0, v157
	v_mul_f32_e64 v157, |v157|, s88
	v_exp_f32_e32 v157, v157
	v_pk_mul_f32 v[154:155], v[154:155], s[28:29] op_sel_hi:[1,0]
	v_add_f32_e32 v157, 1.0, v157
	v_cmp_gt_f32_e32 vcc, s89, v157
	v_cvt_pk_bf16_f32 v153, v154, v155
	s_nop 0
	v_cndmask_b32_e64 v164, 0, 32, vcc
	v_ldexp_f32 v157, v157, v164
	v_log_f32_e32 v157, v157
	s_nop 0
	v_mul_f32_e32 v164, 0x3f317217, v157
	v_fma_f32 v164, v157, s90, -v164
	v_fmac_f32_e32 v164, 0x3377d1cf, v157
	v_fmac_f32_e32 v164, 0x3f317217, v157
	v_cmp_lt_f32_e64 s[6:7], |v157|, s91
	s_nop 1
	v_cndmask_b32_e64 v157, v157, v164, s[6:7]
	v_cndmask_b32_e32 v164, 0, v222, vcc
	v_sub_f32_e32 v164, v157, v164
	v_min_f32_e32 v157, 0, v165
	v_mul_f32_e64 v165, |v165|, s88
	v_exp_f32_e32 v165, v165
	s_nop 0
	v_add_f32_e32 v165, 1.0, v165
	v_cmp_gt_f32_e32 vcc, s89, v165
	s_nop 1
	v_cndmask_b32_e64 v166, 0, 32, vcc
	v_ldexp_f32 v165, v165, v166
	v_log_f32_e32 v165, v165
	s_nop 0
	v_mul_f32_e32 v166, 0x3f317217, v165
	v_fma_f32 v166, v165, s90, -v166
	v_fmac_f32_e32 v166, 0x3377d1cf, v165
	v_fmac_f32_e32 v166, 0x3f317217, v165
	v_cmp_lt_f32_e64 s[6:7], |v165|, s91
	s_nop 1
	v_cndmask_b32_e64 v165, v165, v166, s[6:7]
	v_cndmask_b32_e32 v166, 0, v222, vcc
	v_sub_f32_e32 v165, v165, v166
	v_pk_add_f32 v[156:157], v[156:157], v[164:165] neg_lo:[0,1] neg_hi:[0,1]
	v_fma_f32 v165, v36, v202, v132
	v_min_f32_e32 v164, 0, v165
	v_mul_f32_e64 v165, |v165|, s88
	v_exp_f32_e32 v165, v165
	v_pk_mul_f32 v[156:157], v[156:157], s[28:29] op_sel_hi:[1,0]
	v_add_f32_e32 v165, 1.0, v165
	v_cmp_gt_f32_e32 vcc, s89, v165
	v_cvt_pk_bf16_f32 v154, v156, v157
	v_add_u32_e32 v156, 0x90, v150
	v_cndmask_b32_e64 v166, 0, 32, vcc
	v_ldexp_f32 v165, v165, v166
	v_log_f32_e32 v165, v165
	v_ashrrev_i32_e32 v157, 31, v156
	v_lshlrev_b64 v[156:157], 9, v[156:157]
	v_lshl_add_u64 v[156:157], s[24:25], 0, v[156:157]
	v_mul_f32_e32 v166, 0x3f317217, v165
	v_fma_f32 v166, v165, s90, -v166
	v_fmac_f32_e32 v166, 0x3377d1cf, v165
	v_fmac_f32_e32 v166, 0x3f317217, v165
	v_cmp_lt_f32_e64 s[6:7], |v165|, s91
	v_lshl_add_u64 v[156:157], v[156:157], 0, v[184:185]
	s_nop 0
	v_cndmask_b32_e64 v165, v165, v166, s[6:7]
	v_cndmask_b32_e32 v166, 0, v222, vcc
	v_sub_f32_e32 v166, v165, v166
	v_min_f32_e32 v165, 0, v167
	v_mul_f32_e64 v167, |v167|, s88
	v_exp_f32_e32 v167, v167
	s_nop 0
	v_add_f32_e32 v167, 1.0, v167
	v_cmp_gt_f32_e32 vcc, s89, v167
	s_nop 1
	v_cndmask_b32_e64 v168, 0, 32, vcc
	v_ldexp_f32 v167, v167, v168
	v_log_f32_e32 v167, v167
	s_nop 0
	v_mul_f32_e32 v168, 0x3f317217, v167
	v_fma_f32 v168, v167, s90, -v168
	v_fmac_f32_e32 v168, 0x3377d1cf, v167
	v_fmac_f32_e32 v168, 0x3f317217, v167
	v_cmp_lt_f32_e64 s[6:7], |v167|, s91
	s_nop 1
	v_cndmask_b32_e64 v167, v167, v168, s[6:7]
	v_cndmask_b32_e32 v168, 0, v222, vcc
	v_sub_f32_e32 v167, v167, v168
	v_pk_add_f32 v[164:165], v[164:165], v[166:167] neg_lo:[0,1] neg_hi:[0,1]
	v_fma_f32 v167, v21, v198, v133
	v_pk_mul_f32 v[164:165], v[164:165], s[28:29] op_sel_hi:[1,0]
	v_fmac_f32_e32 v133, v5, v196
	v_cvt_pk_bf16_f32 v155, v164, v165
	ds_write_b128 v160, v[146:149]
	ds_write_b128 v161, v[152:155]
	ds_read_b128 v[146:149], v163
	ds_read_b128 v[152:155], v163 offset:1024
	v_fma_f32 v165, v19, v198, v131
	s_waitcnt lgkmcnt(1)
; __device__ __forceinline__ v4u pack8(const f32x4 a, const f32x4 b) { v4u w; w.x = pk2(a[0], a[1]); w.y = pk2(a[2], a[3]); w.z = pk2(b[0], b[1]); w.w = pk2(b[2], b[3]); return w; }
; __device__ __forceinline__ float fast_exp(float x) { return __builtin_amdgcn_exp2f(x * LOG2E); }
;     __device__ __forceinline__ void operator()(const f32x4 (&acc)[2][2][4][2], const pg8::Unit& u, int wr, int wc, int fr, int fq) const {
;     ...
; #pragma unroll
;             for (int ai = 0; ai < 2; ++ai)
; #pragma unroll
;                 for (int m = 0; m < 4; ++m) {
;                     const int rowa = 256 * pm + 128 * ai + 64 * wr + 16 * m + tt.rr;
;                     const float rs = rs8[ai][m];
;                     v4u pk[2];
; #pragma unroll
;                     for (int bj = 0; bj < 2; ++bj) {
;                         f32x4 r2[2];
; #pragma unroll
;                         for (int n = 0; n < 2; ++n) {
;                             const f32x4 z = acc[ai][bj][m][n] * rs + bg[bj][n];
; #pragma unroll
;                             for (int j = 0; j < 4; ++j) { const float az = fabsf(z[j]); r2[n][j] = (fminf(z[j], 0.f) - __logf(1.0f + fast_exp(-az))) * (1.0f / 16.0f); }
;                         }
;                         pk[bj] = pack8(r2[0], r2[1]);
;                     }
;                     v4u a, b; tt.bf(pk[0], pk[1], a, b);
;                     bf16* d = (bf16*)(ws + WS_LOGA) + (size_t)rowa * 256 + 64 * wc + 8 * tt.p; *(v4u*)d = a; *(v4u*)(d + 8 * 256) = b;
	global_store_dwordx4 v[156:157], v[146:149], off
	s_nop 1
	v_add_co_u32_e32 v146, vcc, s92, v156
	v_fma_f32 v149, v31, v198, v143
	s_nop 0
	v_addc_co_u32_e32 v147, vcc, 0, v157, vcc
	s_waitcnt lgkmcnt(0)
	global_store_dwordx4 v[146:147], v[152:155], off
	v_fma_f32 v147, v30, v198, v142
	v_min_f32_e32 v146, 0, v147
	v_mul_f32_e64 v147, |v147|, s88
	v_exp_f32_e32 v147, v147
	v_fma_f32 v153, v33, v198, v145
	v_fma_f32 v155, v27, v198, v139
	v_fma_f32 v157, v29, v198, v141
	v_add_f32_e32 v147, 1.0, v147
	v_cmp_gt_f32_e32 vcc, s89, v147
	v_fmac_f32_e32 v145, v17, v196
	v_fmac_f32_e32 v141, v13, v196
	v_cndmask_b32_e64 v148, 0, 32, vcc
	v_ldexp_f32 v147, v147, v148
	v_log_f32_e32 v147, v147
	s_nop 0
	v_mul_f32_e32 v148, 0x3f317217, v147
	v_fma_f32 v148, v147, s90, -v148
	v_fmac_f32_e32 v148, 0x3377d1cf, v147
	v_fmac_f32_e32 v148, 0x3f317217, v147
	v_cmp_lt_f32_e64 s[6:7], |v147|, s91
	s_nop 1
	v_cndmask_b32_e64 v147, v147, v148, s[6:7]
	v_cndmask_b32_e32 v148, 0, v222, vcc
	v_sub_f32_e32 v148, v147, v148
	v_min_f32_e32 v147, 0, v149
	v_mul_f32_e64 v149, |v149|, s88
	v_exp_f32_e32 v149, v149
	s_nop 0
	v_add_f32_e32 v149, 1.0, v149
	v_cmp_gt_f32_e32 vcc, s89, v149
	s_nop 1
	v_cndmask_b32_e64 v152, 0, 32, vcc
	v_ldexp_f32 v149, v149, v152
	v_log_f32_e32 v149, v149
	s_nop 0
	v_mul_f32_e32 v152, 0x3f317217, v149
	v_fma_f32 v152, v149, s90, -v152
	v_fmac_f32_e32 v152, 0x3377d1cf, v149
	v_fmac_f32_e32 v152, 0x3f317217, v149
	v_cmp_lt_f32_e64 s[6:7], |v149|, s91
	s_nop 1
	v_cndmask_b32_e64 v149, v149, v152, s[6:7]
	v_cndmask_b32_e32 v152, 0, v222, vcc
	v_sub_f32_e32 v149, v149, v152
	v_pk_add_f32 v[146:147], v[146:147], v[148:149] neg_lo:[0,1] neg_hi:[0,1]
	v_fma_f32 v149, v32, v198, v144
	v_min_f32_e32 v148, 0, v149
	v_mul_f32_e64 v149, |v149|, s88
	v_exp_f32_e32 v149, v149
	v_pk_mul_f32 v[146:147], v[146:147], s[28:29] op_sel_hi:[1,0]
	v_fma_f32 v144, v16, v196, v144
	v_cvt_pk_bf16_f32 v146, v146, v147
	v_add_f32_e32 v149, 1.0, v149
	v_cmp_gt_f32_e32 vcc, s89, v149
	s_nop 1
	v_cndmask_b32_e64 v152, 0, 32, vcc
	v_ldexp_f32 v149, v149, v152
	v_log_f32_e32 v149, v149
	s_nop 0
	v_mul_f32_e32 v152, 0x3f317217, v149
	v_fma_f32 v152, v149, s90, -v152
	v_fmac_f32_e32 v152, 0x3377d1cf, v149
	v_fmac_f32_e32 v152, 0x3f317217, v149
	v_cmp_lt_f32_e64 s[6:7], |v149|, s91
	s_nop 1
	v_cndmask_b32_e64 v149, v149, v152, s[6:7]
	v_cndmask_b32_e32 v152, 0, v222, vcc
	v_sub_f32_e32 v152, v149, v152
	v_min_f32_e32 v149, 0, v153
	v_mul_f32_e64 v153, |v153|, s88
	v_exp_f32_e32 v153, v153
	s_nop 0
	v_add_f32_e32 v153, 1.0, v153
	v_cmp_gt_f32_e32 vcc, s89, v153
	s_nop 1
	v_cndmask_b32_e64 v154, 0, 32, vcc
	v_ldexp_f32 v153, v153, v154
	v_log_f32_e32 v153, v153
	s_nop 0
	v_mul_f32_e32 v154, 0x3f317217, v153
	v_fma_f32 v154, v153, s90, -v154
	v_fmac_f32_e32 v154, 0x3377d1cf, v153
	v_fmac_f32_e32 v154, 0x3f317217, v153
	v_cmp_lt_f32_e64 s[6:7], |v153|, s91
	s_nop 1
	v_cndmask_b32_e64 v153, v153, v154, s[6:7]
	v_cndmask_b32_e32 v154, 0, v222, vcc
	v_sub_f32_e32 v153, v153, v154
	v_pk_add_f32 v[148:149], v[148:149], v[152:153] neg_lo:[0,1] neg_hi:[0,1]
	v_fma_f32 v153, v26, v198, v138
	v_min_f32_e32 v152, 0, v153
	v_mul_f32_e64 v153, |v153|, s88
	v_exp_f32_e32 v153, v153
	v_pk_mul_f32 v[148:149], v[148:149], s[28:29] op_sel_hi:[1,0]
	v_add_f32_e32 v153, 1.0, v153
	v_cmp_gt_f32_e32 vcc, s89, v153
	v_cvt_pk_bf16_f32 v147, v148, v149
	s_nop 0
	v_cndmask_b32_e64 v154, 0, 32, vcc
	v_ldexp_f32 v153, v153, v154
	v_log_f32_e32 v153, v153
	s_nop 0
	v_mul_f32_e32 v154, 0x3f317217, v153
	v_fma_f32 v154, v153, s90, -v154
	v_fmac_f32_e32 v154, 0x3377d1cf, v153
	v_fmac_f32_e32 v154, 0x3f317217, v153
	v_cmp_lt_f32_e64 s[6:7], |v153|, s91
	s_nop 1
	v_cndmask_b32_e64 v153, v153, v154, s[6:7]
	v_cndmask_b32_e32 v154, 0, v222, vcc
	v_sub_f32_e32 v154, v153, v154
	v_min_f32_e32 v153, 0, v155
	v_mul_f32_e64 v155, |v155|, s88
	v_exp_f32_e32 v155, v155
	s_nop 0
	v_add_f32_e32 v155, 1.0, v155
	v_cmp_gt_f32_e32 vcc, s89, v155
	s_nop 1
	v_cndmask_b32_e64 v156, 0, 32, vcc
	v_ldexp_f32 v155, v155, v156
	v_log_f32_e32 v155, v155
	s_nop 0
	v_mul_f32_e32 v156, 0x3f317217, v155
	v_fma_f32 v156, v155, s90, -v156
	v_fmac_f32_e32 v156, 0x3377d1cf, v155
	v_fmac_f32_e32 v156, 0x3f317217, v155
	v_cmp_lt_f32_e64 s[6:7], |v155|, s91
	s_nop 1
	v_cndmask_b32_e64 v155, v155, v156, s[6:7]
	v_cndmask_b32_e32 v156, 0, v222, vcc
	v_sub_f32_e32 v155, v155, v156
	v_pk_add_f32 v[152:153], v[152:153], v[154:155] neg_lo:[0,1] neg_hi:[0,1]
	v_fma_f32 v155, v28, v198, v140
	v_min_f32_e32 v154, 0, v155
	v_mul_f32_e64 v155, |v155|, s88
	v_exp_f32_e32 v155, v155
	v_pk_mul_f32 v[152:153], v[152:153], s[28:29] op_sel_hi:[1,0]
	v_add_f32_e32 v155, 1.0, v155
	v_cmp_gt_f32_e32 vcc, s89, v155
	v_cvt_pk_bf16_f32 v148, v152, v153
	v_fma_f32 v153, v22, v198, v134
	v_cndmask_b32_e64 v156, 0, 32, vcc
	v_ldexp_f32 v155, v155, v156
	v_log_f32_e32 v155, v155
	v_min_f32_e32 v152, 0, v153
	v_mul_f32_e64 v153, |v153|, s88
	v_exp_f32_e32 v153, v153
	v_mul_f32_e32 v156, 0x3f317217, v155
	v_fma_f32 v156, v155, s90, -v156
	v_fmac_f32_e32 v156, 0x3377d1cf, v155
	v_fmac_f32_e32 v156, 0x3f317217, v155
	v_cmp_lt_f32_e64 s[6:7], |v155|, s91
	v_add_f32_e32 v153, 1.0, v153
	s_nop 0
	v_cndmask_b32_e64 v155, v155, v156, s[6:7]
	v_cndmask_b32_e32 v156, 0, v222, vcc
	v_sub_f32_e32 v156, v155, v156
	v_min_f32_e32 v155, 0, v157
	v_mul_f32_e64 v157, |v157|, s88
	v_exp_f32_e32 v157, v157
	s_nop 0
	v_add_f32_e32 v157, 1.0, v157
	v_cmp_gt_f32_e32 vcc, s89, v157
	s_nop 1
	v_cndmask_b32_e64 v164, 0, 32, vcc
	v_ldexp_f32 v157, v157, v164
	v_log_f32_e32 v157, v157
	s_nop 0
	v_mul_f32_e32 v164, 0x3f317217, v157
	v_fma_f32 v164, v157, s90, -v164
	v_fmac_f32_e32 v164, 0x3377d1cf, v157
; __device__ __forceinline__ v4u pack8(const f32x4 a, const f32x4 b) { v4u w; w.x = pk2(a[0], a[1]); w.y = pk2(a[2], a[3]); w.z = pk2(b[0], b[1]); w.w = pk2(b[2], b[3]); return w; }
; __device__ __forceinline__ float fast_exp(float x) { return __builtin_amdgcn_exp2f(x * LOG2E); }
;     __device__ __forceinline__ void operator()(const f32x4 (&acc)[2][2][4][2], const pg8::Unit& u, int wr, int wc, int fr, int fq) const {
;     ...
; #pragma unroll
;             for (int ai = 0; ai < 2; ++ai)
; #pragma unroll
;                 for (int m = 0; m < 4; ++m) {
;                     const int rowa = 256 * pm + 128 * ai + 64 * wr + 16 * m + tt.rr;
;                     const float rs = rs8[ai][m];
;                     v4u pk[2];
; #pragma unroll
;                     for (int bj = 0; bj < 2; ++bj) {
;                         f32x4 r2[2];
; #pragma unroll
;                         for (int n = 0; n < 2; ++n) {
;                             const f32x4 z = acc[ai][bj][m][n] * rs + bg[bj][n];
; #pragma unroll
;                             for (int j = 0; j < 4; ++j) { const float az = fabsf(z[j]); r2[n][j] = (fminf(z[j], 0.f) - __logf(1.0f + fast_exp(-az))) * (1.0f / 16.0f); }
;                         }
;                         pk[bj] = pack8(r2[0], r2[1]);
;                     }
;                     v4u a, b; tt.bf(pk[0], pk[1], a, b);
;                     bf16* d = (bf16*)(ws + WS_LOGA) + (size_t)rowa * 256 + 64 * wc + 8 * tt.p; *(v4u*)d = a; *(v4u*)(d + 8 * 256) = b;
	v_fmac_f32_e32 v164, 0x3f317217, v157
	v_cmp_lt_f32_e64 s[6:7], |v157|, s91
	s_nop 1
	v_cndmask_b32_e64 v157, v157, v164, s[6:7]
	v_cndmask_b32_e32 v164, 0, v222, vcc
	v_sub_f32_e32 v157, v157, v164
	v_pk_add_f32 v[154:155], v[154:155], v[156:157] neg_lo:[0,1] neg_hi:[0,1]
	v_cmp_gt_f32_e32 vcc, s89, v153
	v_pk_mul_f32 v[154:155], v[154:155], s[28:29] op_sel_hi:[1,0]
	v_fma_f32 v157, v25, v198, v137
	v_cvt_pk_bf16_f32 v149, v154, v155
	v_cndmask_b32_e64 v154, 0, 32, vcc
	v_ldexp_f32 v153, v153, v154
	v_log_f32_e32 v153, v153
	v_fma_f32 v155, v23, v198, v135
	v_fmac_f32_e32 v137, v9, v196
	v_mul_f32_e32 v154, 0x3f317217, v153
	v_fma_f32 v154, v153, s90, -v154
	v_fmac_f32_e32 v154, 0x3377d1cf, v153
	v_fmac_f32_e32 v154, 0x3f317217, v153
	v_cmp_lt_f32_e64 s[6:7], |v153|, s91
	s_nop 1
	v_cndmask_b32_e64 v153, v153, v154, s[6:7]
	v_cndmask_b32_e32 v154, 0, v222, vcc
	v_sub_f32_e32 v154, v153, v154
	v_min_f32_e32 v153, 0, v155
	v_mul_f32_e64 v155, |v155|, s88
	v_exp_f32_e32 v155, v155
	s_nop 0
	v_add_f32_e32 v155, 1.0, v155
	v_cmp_gt_f32_e32 vcc, s89, v155
	s_nop 1
	v_cndmask_b32_e64 v156, 0, 32, vcc
	v_ldexp_f32 v155, v155, v156
	v_log_f32_e32 v155, v155
	s_nop 0
	v_mul_f32_e32 v156, 0x3f317217, v155
	v_fma_f32 v156, v155, s90, -v156
	v_fmac_f32_e32 v156, 0x3377d1cf, v155
	v_fmac_f32_e32 v156, 0x3f317217, v155
	v_cmp_lt_f32_e64 s[6:7], |v155|, s91
	s_nop 1
	v_cndmask_b32_e64 v155, v155, v156, s[6:7]
	v_cndmask_b32_e32 v156, 0, v222, vcc
	v_sub_f32_e32 v155, v155, v156
	v_pk_add_f32 v[152:153], v[152:153], v[154:155] neg_lo:[0,1] neg_hi:[0,1]
	v_fma_f32 v155, v24, v198, v136
	v_min_f32_e32 v154, 0, v155
	v_mul_f32_e64 v155, |v155|, s88
	v_exp_f32_e32 v155, v155
	v_pk_mul_f32 v[152:153], v[152:153], s[28:29] op_sel_hi:[1,0]
	v_fma_f32 v136, v8, v196, v136
	v_cvt_pk_bf16_f32 v152, v152, v153
	v_add_f32_e32 v155, 1.0, v155
	v_cmp_gt_f32_e32 vcc, s89, v155
	s_nop 1
	v_cndmask_b32_e64 v156, 0, 32, vcc
	v_ldexp_f32 v155, v155, v156
	v_log_f32_e32 v155, v155
	s_nop 0
	v_mul_f32_e32 v156, 0x3f317217, v155
	v_fma_f32 v156, v155, s90, -v156
	v_fmac_f32_e32 v156, 0x3377d1cf, v155
	v_fmac_f32_e32 v156, 0x3f317217, v155
	v_cmp_lt_f32_e64 s[6:7], |v155|, s91
	s_nop 1
	v_cndmask_b32_e64 v155, v155, v156, s[6:7]
	v_cndmask_b32_e32 v156, 0, v222, vcc
	v_sub_f32_e32 v156, v155, v156
	v_min_f32_e32 v155, 0, v157
	v_mul_f32_e64 v157, |v157|, s88
	v_exp_f32_e32 v157, v157
	s_nop 0
	v_add_f32_e32 v157, 1.0, v157
	v_cmp_gt_f32_e32 vcc, s89, v157
	s_nop 1
	v_cndmask_b32_e64 v164, 0, 32, vcc
	v_ldexp_f32 v157, v157, v164
	v_log_f32_e32 v157, v157
	s_nop 0
	v_mul_f32_e32 v164, 0x3f317217, v157
	v_fma_f32 v164, v157, s90, -v164
	v_fmac_f32_e32 v164, 0x3377d1cf, v157
	v_fmac_f32_e32 v164, 0x3f317217, v157
	v_cmp_lt_f32_e64 s[6:7], |v157|, s91
	s_nop 1
	v_cndmask_b32_e64 v157, v157, v164, s[6:7]
	v_cndmask_b32_e32 v164, 0, v222, vcc
	v_sub_f32_e32 v157, v157, v164
	v_pk_add_f32 v[154:155], v[154:155], v[156:157] neg_lo:[0,1] neg_hi:[0,1]
	v_fma_f32 v157, v18, v198, v130
	v_min_f32_e32 v156, 0, v157
	v_mul_f32_e64 v157, |v157|, s88
	v_exp_f32_e32 v157, v157
	v_pk_mul_f32 v[154:155], v[154:155], s[28:29] op_sel_hi:[1,0]
	v_add_f32_e32 v157, 1.0, v157
	v_cmp_gt_f32_e32 vcc, s89, v157
	v_cvt_pk_bf16_f32 v153, v154, v155
	s_nop 0
	v_cndmask_b32_e64 v164, 0, 32, vcc
	v_ldexp_f32 v157, v157, v164
	v_log_f32_e32 v157, v157
	s_nop 0
	v_mul_f32_e32 v164, 0x3f317217, v157
	v_fma_f32 v164, v157, s90, -v164
	v_fmac_f32_e32 v164, 0x3377d1cf, v157
	v_fmac_f32_e32 v164, 0x3f317217, v157
	v_cmp_lt_f32_e64 s[6:7], |v157|, s91
	s_nop 1
	v_cndmask_b32_e64 v157, v157, v164, s[6:7]
	v_cndmask_b32_e32 v164, 0, v222, vcc
	v_sub_f32_e32 v164, v157, v164
	v_min_f32_e32 v157, 0, v165
	v_mul_f32_e64 v165, |v165|, s88
	v_exp_f32_e32 v165, v165
	s_nop 0
	v_add_f32_e32 v165, 1.0, v165
	v_cmp_gt_f32_e32 vcc, s89, v165
	s_nop 1
	v_cndmask_b32_e64 v166, 0, 32, vcc
	v_ldexp_f32 v165, v165, v166
	v_log_f32_e32 v165, v165
	s_nop 0
	v_mul_f32_e32 v166, 0x3f317217, v165
	v_fma_f32 v166, v165, s90, -v166
	v_fmac_f32_e32 v166, 0x3377d1cf, v165
	v_fmac_f32_e32 v166, 0x3f317217, v165
	v_cmp_lt_f32_e64 s[6:7], |v165|, s91
	s_nop 1
	v_cndmask_b32_e64 v165, v165, v166, s[6:7]
	v_cndmask_b32_e32 v166, 0, v222, vcc
	v_sub_f32_e32 v165, v165, v166
	v_pk_add_f32 v[156:157], v[156:157], v[164:165] neg_lo:[0,1] neg_hi:[0,1]
	v_fma_f32 v165, v20, v198, v132
	v_min_f32_e32 v164, 0, v165
	v_mul_f32_e64 v165, |v165|, s88
	v_exp_f32_e32 v165, v165
	v_pk_mul_f32 v[156:157], v[156:157], s[28:29] op_sel_hi:[1,0]
	v_add_f32_e32 v165, 1.0, v165
	v_cmp_gt_f32_e32 vcc, s89, v165
	v_cvt_pk_bf16_f32 v154, v156, v157
	v_add_u32_e32 v156, 0xa0, v150
	v_cndmask_b32_e64 v166, 0, 32, vcc
	v_ldexp_f32 v165, v165, v166
	v_log_f32_e32 v165, v165
	v_ashrrev_i32_e32 v157, 31, v156
	v_lshlrev_b64 v[156:157], 9, v[156:157]
	v_lshl_add_u64 v[156:157], s[24:25], 0, v[156:157]
	v_mul_f32_e32 v166, 0x3f317217, v165
	v_fma_f32 v166, v165, s90, -v166
	v_fmac_f32_e32 v166, 0x3377d1cf, v165
	v_fmac_f32_e32 v166, 0x3f317217, v165
	v_cmp_lt_f32_e64 s[6:7], |v165|, s91
	v_lshl_add_u64 v[156:157], v[156:157], 0, v[184:185]
	s_nop 0
	v_cndmask_b32_e64 v165, v165, v166, s[6:7]
	v_cndmask_b32_e32 v166, 0, v222, vcc
	v_sub_f32_e32 v166, v165, v166
	v_min_f32_e32 v165, 0, v167
	v_mul_f32_e64 v167, |v167|, s88
	v_exp_f32_e32 v167, v167
	s_nop 0
	v_add_f32_e32 v167, 1.0, v167
	v_cmp_gt_f32_e32 vcc, s89, v167
	s_nop 1
	v_cndmask_b32_e64 v168, 0, 32, vcc
	v_ldexp_f32 v167, v167, v168
	v_log_f32_e32 v167, v167
	s_nop 0
	v_mul_f32_e32 v168, 0x3f317217, v167
	v_fma_f32 v168, v167, s90, -v168
	v_fmac_f32_e32 v168, 0x3377d1cf, v167
	v_fmac_f32_e32 v168, 0x3f317217, v167
	v_cmp_lt_f32_e64 s[6:7], |v167|, s91
	s_nop 1
	v_cndmask_b32_e64 v167, v167, v168, s[6:7]
	v_cndmask_b32_e32 v168, 0, v222, vcc
	v_sub_f32_e32 v167, v167, v168
	v_pk_add_f32 v[164:165], v[164:165], v[166:167] neg_lo:[0,1] neg_hi:[0,1]
	s_nop 0
	v_pk_mul_f32 v[164:165], v[164:165], s[28:29] op_sel_hi:[1,0]
	s_nop 0
	v_cvt_pk_bf16_f32 v155, v164, v165
	ds_write_b128 v160, v[146:149]
	ds_write_b128 v161, v[152:155]
	ds_read_b128 v[146:149], v163
	ds_read_b128 v[152:155], v163 offset:1024
	s_waitcnt lgkmcnt(1)
; __device__ __forceinline__ v4u pack8(const f32x4 a, const f32x4 b) { v4u w; w.x = pk2(a[0], a[1]); w.y = pk2(a[2], a[3]); w.z = pk2(b[0], b[1]); w.w = pk2(b[2], b[3]); return w; }
; __device__ __forceinline__ float fast_exp(float x) { return __builtin_amdgcn_exp2f(x * LOG2E); }
;     __device__ __forceinline__ void operator()(const f32x4 (&acc)[2][2][4][2], const pg8::Unit& u, int wr, int wc, int fr, int fq) const {
;     ...
; #pragma unroll
;             for (int ai = 0; ai < 2; ++ai)
; #pragma unroll
;                 for (int m = 0; m < 4; ++m) {
;                     const int rowa = 256 * pm + 128 * ai + 64 * wr + 16 * m + tt.rr;
;                     const float rs = rs8[ai][m];
;                     v4u pk[2];
; #pragma unroll
;                     for (int bj = 0; bj < 2; ++bj) {
;                         f32x4 r2[2];
; #pragma unroll
;                         for (int n = 0; n < 2; ++n) {
;                             const f32x4 z = acc[ai][bj][m][n] * rs + bg[bj][n];
; #pragma unroll
;                             for (int j = 0; j < 4; ++j) { const float az = fabsf(z[j]); r2[n][j] = (fminf(z[j], 0.f) - __logf(1.0f + fast_exp(-az))) * (1.0f / 16.0f); }
;                         }
;                         pk[bj] = pack8(r2[0], r2[1]);
;                     }
;                     v4u a, b; tt.bf(pk[0], pk[1], a, b);
;                     bf16* d = (bf16*)(ws + WS_LOGA) + (size_t)rowa * 256 + 64 * wc + 8 * tt.p; *(v4u*)d = a; *(v4u*)(d + 8 * 256) = b;
	global_store_dwordx4 v[156:157], v[146:149], off
	s_nop 1
	v_add_co_u32_e32 v146, vcc, s92, v156
	s_nop 1
	v_addc_co_u32_e32 v147, vcc, 0, v157, vcc
	s_waitcnt lgkmcnt(0)
	global_store_dwordx4 v[146:147], v[152:155], off
	v_fma_f32 v146, v14, v196, v142
	v_min_f32_e32 v142, 0, v146
	v_mul_f32_e64 v146, |v146|, s88
	v_exp_f32_e32 v146, v146
	s_nop 0
	v_add_f32_e32 v146, 1.0, v146
	v_cmp_gt_f32_e32 vcc, s89, v146
	s_nop 1
	v_cndmask_b32_e64 v147, 0, 32, vcc
	v_ldexp_f32 v146, v146, v147
	v_log_f32_e32 v146, v146
	s_nop 0
	v_mul_f32_e32 v147, 0x3f317217, v146
	v_fma_f32 v147, v146, s90, -v147
	v_fmac_f32_e32 v147, 0x3377d1cf, v146
	v_fmac_f32_e32 v147, 0x3f317217, v146
	v_cmp_lt_f32_e64 s[6:7], |v146|, s91
	s_nop 1
	v_cndmask_b32_e64 v146, v146, v147, s[6:7]
	v_cndmask_b32_e32 v147, 0, v222, vcc
	v_sub_f32_e32 v146, v146, v147
	v_fma_f32 v147, v15, v196, v143
	v_min_f32_e32 v143, 0, v147
	v_mul_f32_e64 v147, |v147|, s88
	v_exp_f32_e32 v147, v147
	s_nop 0
	v_add_f32_e32 v147, 1.0, v147
	v_cmp_gt_f32_e32 vcc, s89, v147
	s_nop 1
	v_cndmask_b32_e64 v148, 0, 32, vcc
	v_ldexp_f32 v147, v147, v148
	v_log_f32_e32 v147, v147
	s_nop 0
	v_mul_f32_e32 v148, 0x3f317217, v147
	v_fma_f32 v148, v147, s90, -v148
	v_fmac_f32_e32 v148, 0x3377d1cf, v147
	v_fmac_f32_e32 v148, 0x3f317217, v147
	v_cmp_lt_f32_e64 s[6:7], |v147|, s91
	s_nop 1
	v_cndmask_b32_e64 v147, v147, v148, s[6:7]
	v_cndmask_b32_e32 v148, 0, v222, vcc
	v_sub_f32_e32 v147, v147, v148
	v_pk_add_f32 v[142:143], v[142:143], v[146:147] neg_lo:[0,1] neg_hi:[0,1]
	v_min_f32_e32 v146, 0, v144
	v_mul_f32_e64 v144, |v144|, s88
	v_exp_f32_e32 v144, v144
	v_pk_mul_f32 v[142:143], v[142:143], s[28:29] op_sel_hi:[1,0]
	v_add_f32_e32 v144, 1.0, v144
	v_cmp_gt_f32_e32 vcc, s89, v144
	s_nop 1
	v_cndmask_b32_e64 v147, 0, 32, vcc
	v_ldexp_f32 v144, v144, v147
	v_log_f32_e32 v144, v144
	s_nop 0
	v_mul_f32_e32 v147, 0x3f317217, v144
	v_fma_f32 v147, v144, s90, -v147
	v_fmac_f32_e32 v147, 0x3377d1cf, v144
	v_fmac_f32_e32 v147, 0x3f317217, v144
	v_cmp_lt_f32_e64 s[6:7], |v144|, s91
	s_nop 1
	v_cndmask_b32_e64 v144, v144, v147, s[6:7]
	v_cndmask_b32_e32 v147, 0, v222, vcc
	v_sub_f32_e32 v144, v144, v147
	v_min_f32_e32 v147, 0, v145
	v_mul_f32_e64 v145, |v145|, s88
	v_exp_f32_e32 v145, v145
	s_nop 0
	v_add_f32_e32 v145, 1.0, v145
	v_cmp_gt_f32_e32 vcc, s89, v145
	s_nop 1
	v_cndmask_b32_e64 v148, 0, 32, vcc
	v_ldexp_f32 v145, v145, v148
	v_log_f32_e32 v145, v145
	s_nop 0
	v_mul_f32_e32 v148, 0x3f317217, v145
	v_fma_f32 v148, v145, s90, -v148
	v_fmac_f32_e32 v148, 0x3377d1cf, v145
	v_fmac_f32_e32 v148, 0x3f317217, v145
	v_cmp_lt_f32_e64 s[6:7], |v145|, s91
	s_nop 1
	v_cndmask_b32_e64 v145, v145, v148, s[6:7]
	v_cndmask_b32_e32 v148, 0, v222, vcc
	v_sub_f32_e32 v145, v145, v148
	v_pk_add_f32 v[144:145], v[146:147], v[144:145] neg_lo:[0,1] neg_hi:[0,1]
	v_fma_f32 v146, v10, v196, v138
	v_min_f32_e32 v138, 0, v146
	v_mul_f32_e64 v146, |v146|, s88
	v_exp_f32_e32 v146, v146
	v_pk_mul_f32 v[144:145], v[144:145], s[28:29] op_sel_hi:[1,0]
	v_add_f32_e32 v146, 1.0, v146
	v_cmp_gt_f32_e32 vcc, s89, v146
	s_nop 1
	v_cndmask_b32_e64 v147, 0, 32, vcc
	v_ldexp_f32 v146, v146, v147
	v_log_f32_e32 v146, v146
	s_nop 0
	v_mul_f32_e32 v147, 0x3f317217, v146
	v_fma_f32 v147, v146, s90, -v147
	v_fmac_f32_e32 v147, 0x3377d1cf, v146
	v_fmac_f32_e32 v147, 0x3f317217, v146
	v_cmp_lt_f32_e64 s[6:7], |v146|, s91
	s_nop 1
	v_cndmask_b32_e64 v146, v146, v147, s[6:7]
	v_cndmask_b32_e32 v147, 0, v222, vcc
	v_sub_f32_e32 v146, v146, v147
	v_fma_f32 v147, v11, v196, v139
	v_min_f32_e32 v139, 0, v147
	v_mul_f32_e64 v147, |v147|, s88
	v_exp_f32_e32 v147, v147
	s_nop 0
	v_add_f32_e32 v147, 1.0, v147
	v_cmp_gt_f32_e32 vcc, s89, v147
	s_nop 1
	v_cndmask_b32_e64 v148, 0, 32, vcc
	v_ldexp_f32 v147, v147, v148
	v_log_f32_e32 v147, v147
	s_nop 0
	v_mul_f32_e32 v148, 0x3f317217, v147
	v_fma_f32 v148, v147, s90, -v148
	v_fmac_f32_e32 v148, 0x3377d1cf, v147
	v_fmac_f32_e32 v148, 0x3f317217, v147
	v_cmp_lt_f32_e64 s[6:7], |v147|, s91
	s_nop 1
	v_cndmask_b32_e64 v147, v147, v148, s[6:7]
	v_cndmask_b32_e32 v148, 0, v222, vcc
	v_sub_f32_e32 v147, v147, v148
	v_pk_add_f32 v[138:139], v[138:139], v[146:147] neg_lo:[0,1] neg_hi:[0,1]
	s_nop 0
	v_pk_mul_f32 v[146:147], v[138:139], s[28:29] op_sel_hi:[1,0]
	v_fma_f32 v139, v12, v196, v140
	v_min_f32_e32 v138, 0, v139
	v_mul_f32_e64 v139, |v139|, s88
	v_exp_f32_e32 v139, v139
	s_nop 0
	v_add_f32_e32 v139, 1.0, v139
	v_cmp_gt_f32_e32 vcc, s89, v139
	s_nop 1
	v_cndmask_b32_e64 v140, 0, 32, vcc
	v_ldexp_f32 v139, v139, v140
	v_log_f32_e32 v139, v139
	s_nop 0
	v_mul_f32_e32 v140, 0x3f317217, v139
	v_fma_f32 v140, v139, s90, -v140
	v_fmac_f32_e32 v140, 0x3377d1cf, v139
	v_fmac_f32_e32 v140, 0x3f317217, v139
	v_cmp_lt_f32_e64 s[6:7], |v139|, s91
	s_nop 1
	v_cndmask_b32_e64 v139, v139, v140, s[6:7]
	v_cndmask_b32_e32 v140, 0, v222, vcc
	v_sub_f32_e32 v140, v139, v140
	v_min_f32_e32 v139, 0, v141
	v_mul_f32_e64 v141, |v141|, s88
	v_exp_f32_e32 v141, v141
	s_nop 0
	v_add_f32_e32 v141, 1.0, v141
	v_cmp_gt_f32_e32 vcc, s89, v141
	s_nop 1
	v_cndmask_b32_e64 v148, 0, 32, vcc
	v_ldexp_f32 v141, v141, v148
	v_log_f32_e32 v141, v141
	s_nop 0
	v_mul_f32_e32 v148, 0x3f317217, v141
	v_fma_f32 v148, v141, s90, -v148
	v_fmac_f32_e32 v148, 0x3377d1cf, v141
	v_fmac_f32_e32 v148, 0x3f317217, v141
	v_cmp_lt_f32_e64 s[6:7], |v141|, s91
	s_nop 1
	v_cndmask_b32_e64 v141, v141, v148, s[6:7]
	v_cndmask_b32_e32 v148, 0, v222, vcc
	v_sub_f32_e32 v141, v141, v148
	v_pk_add_f32 v[138:139], v[138:139], v[140:141] neg_lo:[0,1] neg_hi:[0,1]
	v_cvt_pk_bf16_f32 v140, v146, v147
	v_pk_mul_f32 v[148:149], v[138:139], s[28:29] op_sel_hi:[1,0]
; __device__ __forceinline__ v4u pack8(const f32x4 a, const f32x4 b) { v4u w; w.x = pk2(a[0], a[1]); w.y = pk2(a[2], a[3]); w.z = pk2(b[0], b[1]); w.w = pk2(b[2], b[3]); return w; }
; __device__ __forceinline__ float fast_exp(float x) { return __builtin_amdgcn_exp2f(x * LOG2E); }
;     __device__ __forceinline__ void operator()(const f32x4 (&acc)[2][2][4][2], const pg8::Unit& u, int wr, int wc, int fr, int fq) const {
;     ...
; #pragma unroll
;             for (int ai = 0; ai < 2; ++ai)
; #pragma unroll
;                 for (int m = 0; m < 4; ++m) {
;                     const int rowa = 256 * pm + 128 * ai + 64 * wr + 16 * m + tt.rr;
;                     const float rs = rs8[ai][m];
;                     v4u pk[2];
; #pragma unroll
;                     for (int bj = 0; bj < 2; ++bj) {
;                         f32x4 r2[2];
; #pragma unroll
;                         for (int n = 0; n < 2; ++n) {
;                             const f32x4 z = acc[ai][bj][m][n] * rs + bg[bj][n];
; #pragma unroll
;                             for (int j = 0; j < 4; ++j) { const float az = fabsf(z[j]); r2[n][j] = (fminf(z[j], 0.f) - __logf(1.0f + fast_exp(-az))) * (1.0f / 16.0f); }
;                         }
;                         pk[bj] = pack8(r2[0], r2[1]);
;                     }
;                     v4u a, b; tt.bf(pk[0], pk[1], a, b);
;                     bf16* d = (bf16*)(ws + WS_LOGA) + (size_t)rowa * 256 + 64 * wc + 8 * tt.p; *(v4u*)d = a; *(v4u*)(d + 8 * 256) = b;
	v_cvt_pk_bf16_f32 v138, v142, v143
	v_fma_f32 v142, v6, v196, v134
	v_min_f32_e32 v134, 0, v142
	v_mul_f32_e64 v142, |v142|, s88
	v_exp_f32_e32 v142, v142
	v_cvt_pk_bf16_f32 v139, v144, v145
	v_cvt_pk_bf16_f32 v141, v148, v149
	v_add_f32_e32 v142, 1.0, v142
	v_cmp_gt_f32_e32 vcc, s89, v142
	s_nop 1
	v_cndmask_b32_e64 v143, 0, 32, vcc
	v_ldexp_f32 v142, v142, v143
	v_log_f32_e32 v142, v142
	s_nop 0
	v_mul_f32_e32 v143, 0x3f317217, v142
	v_fma_f32 v143, v142, s90, -v143
	v_fmac_f32_e32 v143, 0x3377d1cf, v142
	v_fmac_f32_e32 v143, 0x3f317217, v142
	v_cmp_lt_f32_e64 s[6:7], |v142|, s91
	s_nop 1
	v_cndmask_b32_e64 v142, v142, v143, s[6:7]
	v_cndmask_b32_e32 v143, 0, v222, vcc
	v_sub_f32_e32 v142, v142, v143
	v_fma_f32 v143, v7, v196, v135
	v_min_f32_e32 v135, 0, v143
	v_mul_f32_e64 v143, |v143|, s88
	v_exp_f32_e32 v143, v143
	s_nop 0
	v_add_f32_e32 v143, 1.0, v143
	v_cmp_gt_f32_e32 vcc, s89, v143
	s_nop 1
	v_cndmask_b32_e64 v144, 0, 32, vcc
	v_ldexp_f32 v143, v143, v144
	v_log_f32_e32 v143, v143
	s_nop 0
	v_mul_f32_e32 v144, 0x3f317217, v143
	v_fma_f32 v144, v143, s90, -v144
	v_fmac_f32_e32 v144, 0x3377d1cf, v143
	v_fmac_f32_e32 v144, 0x3f317217, v143
	v_cmp_lt_f32_e64 s[6:7], |v143|, s91
	s_nop 1
	v_cndmask_b32_e64 v143, v143, v144, s[6:7]
	v_cndmask_b32_e32 v144, 0, v222, vcc
	v_sub_f32_e32 v143, v143, v144
	v_pk_add_f32 v[134:135], v[134:135], v[142:143] neg_lo:[0,1] neg_hi:[0,1]
	v_min_f32_e32 v142, 0, v136
	v_mul_f32_e64 v136, |v136|, s88
	v_exp_f32_e32 v136, v136
	v_pk_mul_f32 v[134:135], v[134:135], s[28:29] op_sel_hi:[1,0]
	v_add_f32_e32 v136, 1.0, v136
	v_cmp_gt_f32_e32 vcc, s89, v136
	s_nop 1
	v_cndmask_b32_e64 v143, 0, 32, vcc
	v_ldexp_f32 v136, v136, v143
	v_log_f32_e32 v136, v136
	s_nop 0
	v_mul_f32_e32 v143, 0x3f317217, v136
	v_fma_f32 v143, v136, s90, -v143
	v_fmac_f32_e32 v143, 0x3377d1cf, v136
	v_fmac_f32_e32 v143, 0x3f317217, v136
	v_cmp_lt_f32_e64 s[6:7], |v136|, s91
	s_nop 1
	v_cndmask_b32_e64 v136, v136, v143, s[6:7]
	v_cndmask_b32_e32 v143, 0, v222, vcc
	v_sub_f32_e32 v136, v136, v143
	v_min_f32_e32 v143, 0, v137
	v_mul_f32_e64 v137, |v137|, s88
	v_exp_f32_e32 v137, v137
	s_nop 0
	v_add_f32_e32 v137, 1.0, v137
	v_cmp_gt_f32_e32 vcc, s89, v137
	s_nop 1
	v_cndmask_b32_e64 v144, 0, 32, vcc
	v_ldexp_f32 v137, v137, v144
	v_log_f32_e32 v137, v137
	s_nop 0
	v_mul_f32_e32 v144, 0x3f317217, v137
	v_fma_f32 v144, v137, s90, -v144
	v_fmac_f32_e32 v144, 0x3377d1cf, v137
	v_fmac_f32_e32 v144, 0x3f317217, v137
	v_cmp_lt_f32_e64 s[6:7], |v137|, s91
	s_nop 1
	v_cndmask_b32_e64 v137, v137, v144, s[6:7]
	v_cndmask_b32_e32 v144, 0, v222, vcc
	v_sub_f32_e32 v137, v137, v144
	v_pk_add_f32 v[136:137], v[142:143], v[136:137] neg_lo:[0,1] neg_hi:[0,1]
	v_fma_f32 v142, v2, v196, v130
	v_min_f32_e32 v130, 0, v142
	v_mul_f32_e64 v142, |v142|, s88
	v_exp_f32_e32 v142, v142
	v_pk_mul_f32 v[136:137], v[136:137], s[28:29] op_sel_hi:[1,0]
	v_add_f32_e32 v142, 1.0, v142
	v_cmp_gt_f32_e32 vcc, s89, v142
	s_nop 1
	v_cndmask_b32_e64 v143, 0, 32, vcc
	v_ldexp_f32 v142, v142, v143
	v_log_f32_e32 v142, v142
	s_nop 0
	v_mul_f32_e32 v143, 0x3f317217, v142
	v_fma_f32 v143, v142, s90, -v143
	v_fmac_f32_e32 v143, 0x3377d1cf, v142
	v_fmac_f32_e32 v143, 0x3f317217, v142
	v_cmp_lt_f32_e64 s[6:7], |v142|, s91
	s_nop 1
	v_cndmask_b32_e64 v142, v142, v143, s[6:7]
	v_cndmask_b32_e32 v143, 0, v222, vcc
	v_sub_f32_e32 v142, v142, v143
	v_fma_f32 v143, v3, v196, v131
	v_min_f32_e32 v131, 0, v143
	v_mul_f32_e64 v143, |v143|, s88
	v_exp_f32_e32 v143, v143
	s_nop 0
	v_add_f32_e32 v143, 1.0, v143
	v_cmp_gt_f32_e32 vcc, s89, v143
	s_nop 1
	v_cndmask_b32_e64 v144, 0, 32, vcc
	v_ldexp_f32 v143, v143, v144
	v_log_f32_e32 v143, v143
	s_nop 0
	v_mul_f32_e32 v144, 0x3f317217, v143
	v_fma_f32 v144, v143, s90, -v144
	v_fmac_f32_e32 v144, 0x3377d1cf, v143
	v_fmac_f32_e32 v144, 0x3f317217, v143
	v_cmp_lt_f32_e64 s[6:7], |v143|, s91
	s_nop 1
	v_cndmask_b32_e64 v143, v143, v144, s[6:7]
	v_cndmask_b32_e32 v144, 0, v222, vcc
	v_sub_f32_e32 v143, v143, v144
	v_pk_add_f32 v[130:131], v[130:131], v[142:143] neg_lo:[0,1] neg_hi:[0,1]
	s_nop 0
	v_pk_mul_f32 v[142:143], v[130:131], s[28:29] op_sel_hi:[1,0]
	v_fma_f32 v131, v4, v196, v132
	v_min_f32_e32 v130, 0, v131
	v_mul_f32_e64 v131, |v131|, s88
	v_exp_f32_e32 v131, v131
	s_nop 0
	v_add_f32_e32 v131, 1.0, v131
	v_cmp_gt_f32_e32 vcc, s89, v131
	s_nop 1
	v_cndmask_b32_e64 v132, 0, 32, vcc
	v_ldexp_f32 v131, v131, v132
	v_log_f32_e32 v131, v131
	s_nop 0
	v_mul_f32_e32 v132, 0x3f317217, v131
	v_fma_f32 v132, v131, s90, -v132
	v_fmac_f32_e32 v132, 0x3377d1cf, v131
	v_fmac_f32_e32 v132, 0x3f317217, v131
	v_cmp_lt_f32_e64 s[6:7], |v131|, s91
	s_nop 1
	v_cndmask_b32_e64 v131, v131, v132, s[6:7]
	v_cndmask_b32_e32 v132, 0, v222, vcc
	v_sub_f32_e32 v132, v131, v132
	v_min_f32_e32 v131, 0, v133
	v_mul_f32_e64 v133, |v133|, s88
	v_exp_f32_e32 v133, v133
	s_nop 0
	v_add_f32_e32 v133, 1.0, v133
	v_cmp_gt_f32_e32 vcc, s89, v133
	s_nop 1
	v_cndmask_b32_e64 v144, 0, 32, vcc
	v_ldexp_f32 v133, v133, v144
	v_log_f32_e32 v133, v133
	s_nop 0
	v_mul_f32_e32 v144, 0x3f317217, v133
	v_fma_f32 v144, v133, s90, -v144
	v_fmac_f32_e32 v144, 0x3377d1cf, v133
	v_fmac_f32_e32 v144, 0x3f317217, v133
	v_cmp_lt_f32_e64 s[6:7], |v133|, s91
	s_nop 1
	v_cndmask_b32_e64 v133, v133, v144, s[6:7]
	v_cndmask_b32_e32 v144, 0, v222, vcc
	v_sub_f32_e32 v133, v133, v144
	v_pk_add_f32 v[130:131], v[130:131], v[132:133] neg_lo:[0,1] neg_hi:[0,1]
	v_cvt_pk_bf16_f32 v132, v142, v143
	v_pk_mul_f32 v[144:145], v[130:131], s[28:29] op_sel_hi:[1,0]
	v_cvt_pk_bf16_f32 v130, v134, v135
	v_cvt_pk_bf16_f32 v131, v136, v137
	v_cvt_pk_bf16_f32 v133, v144, v145
	v_add_u32_e32 v142, 0xb0, v150
	ds_write_b128 v160, v[138:141]
	ds_write_b128 v161, v[130:133]
	ds_read_b128 v[130:133], v163
	ds_read_b128 v[134:137], v163 offset:1024
	v_ashrrev_i32_e32 v143, 31, v142
	v_lshlrev_b64 v[138:139], 9, v[142:143]
	v_lshl_add_u64 v[138:139], s[24:25], 0, v[138:139]
	v_lshl_add_u64 v[138:139], v[138:139], 0, v[184:185]
	s_waitcnt lgkmcnt(1)
	global_store_dwordx4 v[138:139], v[130:133], off
	s_mov_b64 s[6:7], 0
	s_nop 0
	v_add_co_u32_e32 v130, vcc, 0x1000, v138
	s_nop 1
	v_addc_co_u32_e32 v131, vcc, 0, v139, vcc
	s_waitcnt lgkmcnt(0)
	global_store_dwordx4 v[130:131], v[134:137], off

; __global__ void __launch_bounds__(NWAVES * 64, 2) hymba_fwd(Args args) {
	.amdhsa_kernel _Z9hymba_fwd4Args
		.amdhsa_group_segment_fixed_size 0
		.amdhsa_private_segment_fixed_size 0
		.amdhsa_kernarg_size 392
		.amdhsa_user_sgpr_count 2
		.amdhsa_user_sgpr_dispatch_ptr 0
		.amdhsa_user_sgpr_queue_ptr 0
		.amdhsa_user_sgpr_kernarg_segment_ptr 1
		.amdhsa_user_sgpr_dispatch_id 0
		.amdhsa_user_sgpr_kernarg_preload_length 0
		.amdhsa_user_sgpr_kernarg_preload_offset 0
		.amdhsa_user_sgpr_private_segment_size 0
		.amdhsa_uses_dynamic_stack 0
		.amdhsa_enable_private_segment 0
		.amdhsa_system_sgpr_workgroup_id_x 1
		.amdhsa_system_sgpr_workgroup_id_y 0
		.amdhsa_system_sgpr_workgroup_id_z 0
		.amdhsa_system_sgpr_workgroup_info 0
		.amdhsa_system_vgpr_workitem_id 0
		.amdhsa_next_free_vgpr 256
		.amdhsa_next_free_sgpr 100
		.amdhsa_accum_offset 256
		.amdhsa_reserve_vcc 1
		.amdhsa_float_round_mode_32 0
		.amdhsa_float_round_mode_16_64 0
		.amdhsa_float_denorm_mode_32 3
		.amdhsa_float_denorm_mode_16_64 3
		.amdhsa_dx10_clamp 1
		.amdhsa_ieee_mode 1
		.amdhsa_fp16_overflow 0
		.amdhsa_tg_split 0
		.amdhsa_exception_fp_ieee_invalid_op 0
		.amdhsa_exception_fp_denorm_src 0
		.amdhsa_exception_fp_ieee_div_zero 0
		.amdhsa_exception_fp_ieee_overflow 0
		.amdhsa_exception_fp_ieee_underflow 0
		.amdhsa_exception_fp_ieee_inexact 0
		.amdhsa_exception_int_div_zero 0
	.end_amdhsa_kernel

; __global__ void __launch_bounds__(NWAVES * 64, 2) hymba_fwd(Args args) {
amdhsa.kernels:
  - .agpr_count:     0
    .args:
      - .offset:         0
        .size:           136
        .value_kind:     by_value
      - .offset:         136
        .size:           4
        .value_kind:     hidden_block_count_x
      - .offset:         140
        .size:           4
        .value_kind:     hidden_block_count_y
      - .offset:         144
        .size:           4
        .value_kind:     hidden_block_count_z
      - .offset:         148
        .size:           2
        .value_kind:     hidden_group_size_x
      - .offset:         150
        .size:           2
        .value_kind:     hidden_group_size_y
      - .offset:         152
        .size:           2
        .value_kind:     hidden_group_size_z
      - .offset:         154
        .size:           2
        .value_kind:     hidden_remainder_x
      - .offset:         156
        .size:           2
        .value_kind:     hidden_remainder_y
      - .offset:         158
        .size:           2
        .value_kind:     hidden_remainder_z
      - .offset:         176
        .size:           8
        .value_kind:     hidden_global_offset_x
      - .offset:         184
        .size:           8
        .value_kind:     hidden_global_offset_y
      - .offset:         192
        .size:           8
        .value_kind:     hidden_global_offset_z
      - .offset:         200
        .size:           2
        .value_kind:     hidden_grid_dims
      - .offset:         256
        .size:           4
        .value_kind:     hidden_dynamic_lds_size
    .group_segment_fixed_size: 0
    .kernarg_segment_align: 8
    .kernarg_segment_size: 392
    .language:       OpenCL C
    .language_version:
      - 2
      - 0
    .max_flat_workgroup_size: 512
    .name:           _Z9hymba_fwd4Args
    .private_segment_fixed_size: 0
    .sgpr_count:     106
    .sgpr_spill_count: 112
    .symbol:         _Z9hymba_fwd4Args.kd
    .uniform_work_group_size: 1
    .uses_dynamic_stack: false
    .vgpr_count:     256
    .vgpr_spill_count: 0
    .wavefront_size: 64
